# mixer-input phases 2,4,9,14: write-back only for scattered dwordx2/2-byte stores (+wbl2 at their barrier), write-through for contiguous f32 stores
# baseline (speedup 1.0000x reference)
.LBB0_272:
	v_cvt_pk_bf16_f32 v60, v2, s0
	v_add_u32_e32 v2, s11, v173
	v_mul_lo_u32 v61, v2, s94
	v_or_b32_e32 v2, v61, v174
	v_cvt_pk_bf16_f32 v15, v3, s0
	v_ashrrev_i32_e32 v3, 31, v2
	v_lshl_add_u64 v[2:3], v[2:3], 1, s[22:23]
	global_store_short v[2:3], v15, off
	v_or_b32_e32 v2, v61, v175
	v_ashrrev_i32_e32 v3, 31, v2
	v_lshl_add_u64 v[2:3], v[2:3], 1, s[22:23]
	v_or_b32_e32 v58, 0xc0, v61
	global_store_short v[2:3], v60, off
	v_add_u32_e32 v2, v58, v174
	v_ashrrev_i32_e32 v3, 31, v2
	v_lshl_add_u64 v[2:3], v[2:3], 1, s[22:23]
	global_store_short v[2:3], v15, off
	v_add_u32_e32 v2, v58, v175
	v_ashrrev_i32_e32 v3, 31, v2
	v_lshl_add_u64 v[2:3], v[2:3], 1, s[22:23]
	v_or_b32_e32 v58, 0x180, v61
	global_store_short v[2:3], v60, off
	v_add_u32_e32 v2, v58, v174
	v_ashrrev_i32_e32 v3, 31, v2
	v_lshl_add_u64 v[2:3], v[2:3], 1, s[22:23]
	global_store_short v[2:3], v15, off
	v_add_u32_e32 v2, v58, v175
	v_ashrrev_i32_e32 v3, 31, v2
	v_lshl_add_u64 v[2:3], v[2:3], 1, s[22:23]
	v_add_u32_e32 v58, 0x240, v61
	global_store_short v[2:3], v60, off
	v_or_b32_e32 v2, v58, v174
	v_ashrrev_i32_e32 v3, 31, v2
	v_lshl_add_u64 v[2:3], v[2:3], 1, s[22:23]
	global_store_short v[2:3], v15, off
	v_or_b32_e32 v2, v58, v175
	v_ashrrev_i32_e32 v3, 31, v2
	v_lshl_add_u64 v[2:3], v[2:3], 1, s[22:23]
	v_add_u32_e32 v58, 0x300, v61
	global_store_short v[2:3], v60, off
	v_or_b32_e32 v2, v58, v174
	v_ashrrev_i32_e32 v3, 31, v2
	v_lshl_add_u64 v[2:3], v[2:3], 1, s[22:23]
	global_store_short v[2:3], v15, off
	v_or_b32_e32 v2, v58, v175
	v_pk_mul_f32 v[58:59], v[74:75], v[74:75]
	v_ashrrev_i32_e32 v3, 31, v2
	v_add_f32_e32 v58, v59, v58
	ds_bpermute_b32 v59, v14, v58
	v_lshl_add_u64 v[2:3], v[2:3], 1, s[22:23]
	v_add_u32_e32 v62, 0x3c0, v61
	global_store_short v[2:3], v60, off
	v_add_u32_e32 v2, v62, v174
	s_waitcnt lgkmcnt(0)
	v_add_f32_e32 v58, v58, v59
	ds_bpermute_b32 v59, v10, v58
	v_ashrrev_i32_e32 v3, 31, v2
	v_lshl_add_u64 v[2:3], v[2:3], 1, s[22:23]
	global_store_short v[2:3], v15, off
	v_add_u32_e32 v2, v62, v175
	s_waitcnt lgkmcnt(0)
	v_add_f32_e32 v58, v58, v59
	ds_bpermute_b32 v59, v11, v58
	v_ashrrev_i32_e32 v3, 31, v2
	v_lshl_add_u64 v[2:3], v[2:3], 1, s[22:23]
	v_add_u32_e32 v62, 0x480, v61
	global_store_short v[2:3], v60, off
	s_waitcnt lgkmcnt(0)
	v_add_f32_e32 v58, v58, v59
	ds_bpermute_b32 v59, v12, v58
	v_add_u32_e32 v2, v62, v174
	v_ashrrev_i32_e32 v3, 31, v2
	v_lshl_add_u64 v[2:3], v[2:3], 1, s[22:23]
	global_store_short v[2:3], v15, off
	v_add_u32_e32 v2, v62, v175
	s_waitcnt lgkmcnt(0)
	v_add_f32_e32 v58, v58, v59
	v_ashrrev_i32_e32 v3, 31, v2
	ds_bpermute_b32 v59, v13, v58
	v_lshl_add_u64 v[2:3], v[2:3], 1, s[22:23]
	v_add_u32_e32 v61, 0x540, v61
	global_store_short v[2:3], v60, off
	v_or_b32_e32 v2, v61, v174
	v_ashrrev_i32_e32 v3, 31, v2
	v_lshl_add_u64 v[2:3], v[2:3], 1, s[22:23]
	global_store_short v[2:3], v15, off
	s_waitcnt lgkmcnt(0)
	v_add_f32_e32 v3, v58, v59
	v_fmamk_f32 v3, v3, 0x3c800000, v209
	v_rsq_f32_e32 v58, v3
	v_or_b32_e32 v2, v61, v175
	v_ashrrev_i32_e32 v3, 31, v2
	v_lshl_add_u64 v[2:3], v[2:3], 1, s[22:23]
	global_store_short v[2:3], v60, off
	v_pk_mul_f32 v[2:3], v[0:1], v[58:59] op_sel_hi:[1,0]
	s_and_b64 vcc, exec, s[4:5]
	v_pk_mul_f32 v[2:3], v[74:75], v[2:3]
	s_mov_b64 s[80:81], -1
	s_cbranch_vccnz .LBB0_274
	v_add_u32_e32 v15, s76, v176
	v_lshl_or_b32 v58, v15, 6, v156
	v_ashrrev_i32_e32 v59, 31, v58
	v_lshl_add_u64 v[58:59], v[58:59], 2, s[24:25]
	s_mov_b64 s[80:81], 0
	global_store_dword v[58:59], v3, off sc1
	global_store_dword v[58:59], v2, off offset:128 sc1

.LBB0_276:
	v_cvt_pk_bf16_f32 v60, v2, s0
	v_add_u32_e32 v2, s11, v176
	v_mul_lo_u32 v61, v2, s94
	v_or_b32_e32 v2, v61, v174
	v_cvt_pk_bf16_f32 v15, v3, s0
	v_ashrrev_i32_e32 v3, 31, v2
	v_lshl_add_u64 v[2:3], v[2:3], 1, s[22:23]
	global_store_short v[2:3], v15, off
	v_or_b32_e32 v2, v61, v175
	v_ashrrev_i32_e32 v3, 31, v2
	v_lshl_add_u64 v[2:3], v[2:3], 1, s[22:23]
	v_or_b32_e32 v58, 0xc0, v61
	global_store_short v[2:3], v60, off
	v_add_u32_e32 v2, v58, v174
	v_ashrrev_i32_e32 v3, 31, v2
	v_lshl_add_u64 v[2:3], v[2:3], 1, s[22:23]
	global_store_short v[2:3], v15, off
	v_add_u32_e32 v2, v58, v175
	v_ashrrev_i32_e32 v3, 31, v2
	v_lshl_add_u64 v[2:3], v[2:3], 1, s[22:23]
	v_or_b32_e32 v58, 0x180, v61
	global_store_short v[2:3], v60, off
	v_add_u32_e32 v2, v58, v174
	v_ashrrev_i32_e32 v3, 31, v2
	v_lshl_add_u64 v[2:3], v[2:3], 1, s[22:23]
	global_store_short v[2:3], v15, off
	v_add_u32_e32 v2, v58, v175
	v_ashrrev_i32_e32 v3, 31, v2
	v_lshl_add_u64 v[2:3], v[2:3], 1, s[22:23]
	v_add_u32_e32 v58, 0x240, v61
	global_store_short v[2:3], v60, off
	v_or_b32_e32 v2, v58, v174
	v_ashrrev_i32_e32 v3, 31, v2
	v_lshl_add_u64 v[2:3], v[2:3], 1, s[22:23]
	global_store_short v[2:3], v15, off
	v_or_b32_e32 v2, v58, v175
	v_ashrrev_i32_e32 v3, 31, v2
	v_lshl_add_u64 v[2:3], v[2:3], 1, s[22:23]
	v_add_u32_e32 v58, 0x300, v61
	global_store_short v[2:3], v60, off
	v_or_b32_e32 v2, v58, v174
	v_ashrrev_i32_e32 v3, 31, v2
	v_lshl_add_u64 v[2:3], v[2:3], 1, s[22:23]
	global_store_short v[2:3], v15, off
	v_or_b32_e32 v2, v58, v175
	v_pk_mul_f32 v[58:59], v[72:73], v[72:73]
	v_ashrrev_i32_e32 v3, 31, v2
	v_add_f32_e32 v58, v59, v58
	ds_bpermute_b32 v59, v14, v58
	v_lshl_add_u64 v[2:3], v[2:3], 1, s[22:23]
	v_add_u32_e32 v62, 0x3c0, v61
	global_store_short v[2:3], v60, off
	v_add_u32_e32 v2, v62, v174
	s_waitcnt lgkmcnt(0)
	v_add_f32_e32 v58, v58, v59
	ds_bpermute_b32 v59, v10, v58
	v_ashrrev_i32_e32 v3, 31, v2
	v_lshl_add_u64 v[2:3], v[2:3], 1, s[22:23]
	global_store_short v[2:3], v15, off
	v_add_u32_e32 v2, v62, v175
	s_waitcnt lgkmcnt(0)
	v_add_f32_e32 v58, v58, v59
	ds_bpermute_b32 v59, v11, v58
	v_ashrrev_i32_e32 v3, 31, v2
	v_lshl_add_u64 v[2:3], v[2:3], 1, s[22:23]
	v_add_u32_e32 v62, 0x480, v61
	global_store_short v[2:3], v60, off
	s_waitcnt lgkmcnt(0)
	v_add_f32_e32 v58, v58, v59
	ds_bpermute_b32 v59, v12, v58
	v_add_u32_e32 v2, v62, v174
	v_ashrrev_i32_e32 v3, 31, v2
	v_lshl_add_u64 v[2:3], v[2:3], 1, s[22:23]
	global_store_short v[2:3], v15, off
	v_add_u32_e32 v2, v62, v175
	s_waitcnt lgkmcnt(0)
	v_add_f32_e32 v58, v58, v59
	v_ashrrev_i32_e32 v3, 31, v2
	ds_bpermute_b32 v59, v13, v58
	v_lshl_add_u64 v[2:3], v[2:3], 1, s[22:23]
	v_add_u32_e32 v61, 0x540, v61
	global_store_short v[2:3], v60, off
	v_or_b32_e32 v2, v61, v174
	v_ashrrev_i32_e32 v3, 31, v2
	v_lshl_add_u64 v[2:3], v[2:3], 1, s[22:23]
	global_store_short v[2:3], v15, off
	s_waitcnt lgkmcnt(0)
	v_add_f32_e32 v3, v58, v59
	v_fmamk_f32 v3, v3, 0x3c800000, v209
	v_rsq_f32_e32 v58, v3
	v_or_b32_e32 v2, v61, v175
	v_ashrrev_i32_e32 v3, 31, v2
	v_lshl_add_u64 v[2:3], v[2:3], 1, s[22:23]
	global_store_short v[2:3], v60, off
	v_pk_mul_f32 v[2:3], v[0:1], v[58:59] op_sel_hi:[1,0]
	s_and_b64 vcc, exec, s[4:5]
	v_pk_mul_f32 v[2:3], v[72:73], v[2:3]
	s_mov_b64 s[80:81], -1
	s_cbranch_vccnz .LBB0_278
	v_add_u32_e32 v15, s76, v177
	v_lshl_or_b32 v58, v15, 6, v156
	v_ashrrev_i32_e32 v59, 31, v58
	v_lshl_add_u64 v[58:59], v[58:59], 2, s[24:25]
	s_mov_b64 s[80:81], 0
	global_store_dword v[58:59], v3, off sc1
	global_store_dword v[58:59], v2, off offset:128 sc1

.LBB0_280:
	v_cvt_pk_bf16_f32 v60, v2, s0
	v_add_u32_e32 v2, s11, v177
	v_mul_lo_u32 v61, v2, s94
	v_or_b32_e32 v2, v61, v174
	v_cvt_pk_bf16_f32 v15, v3, s0
	v_ashrrev_i32_e32 v3, 31, v2
	v_lshl_add_u64 v[2:3], v[2:3], 1, s[22:23]
	global_store_short v[2:3], v15, off
	v_or_b32_e32 v2, v61, v175
	v_ashrrev_i32_e32 v3, 31, v2
	v_lshl_add_u64 v[2:3], v[2:3], 1, s[22:23]
	v_or_b32_e32 v58, 0xc0, v61
	global_store_short v[2:3], v60, off
	v_add_u32_e32 v2, v58, v174
	v_ashrrev_i32_e32 v3, 31, v2
	v_lshl_add_u64 v[2:3], v[2:3], 1, s[22:23]
	global_store_short v[2:3], v15, off
	v_add_u32_e32 v2, v58, v175
	v_ashrrev_i32_e32 v3, 31, v2
	v_lshl_add_u64 v[2:3], v[2:3], 1, s[22:23]
	v_or_b32_e32 v58, 0x180, v61
	global_store_short v[2:3], v60, off
	v_add_u32_e32 v2, v58, v174
	v_ashrrev_i32_e32 v3, 31, v2
	v_lshl_add_u64 v[2:3], v[2:3], 1, s[22:23]
	global_store_short v[2:3], v15, off
	v_add_u32_e32 v2, v58, v175
	v_ashrrev_i32_e32 v3, 31, v2
	v_lshl_add_u64 v[2:3], v[2:3], 1, s[22:23]
	v_add_u32_e32 v58, 0x240, v61
	global_store_short v[2:3], v60, off
	v_or_b32_e32 v2, v58, v174
	v_ashrrev_i32_e32 v3, 31, v2
	v_lshl_add_u64 v[2:3], v[2:3], 1, s[22:23]
	global_store_short v[2:3], v15, off
	v_or_b32_e32 v2, v58, v175
	v_ashrrev_i32_e32 v3, 31, v2
	v_lshl_add_u64 v[2:3], v[2:3], 1, s[22:23]
	v_add_u32_e32 v58, 0x300, v61
	global_store_short v[2:3], v60, off
	v_or_b32_e32 v2, v58, v174
	v_ashrrev_i32_e32 v3, 31, v2
	v_lshl_add_u64 v[2:3], v[2:3], 1, s[22:23]
	global_store_short v[2:3], v15, off
	v_or_b32_e32 v2, v58, v175
	v_pk_mul_f32 v[58:59], v[70:71], v[70:71]
	v_ashrrev_i32_e32 v3, 31, v2
	v_add_f32_e32 v58, v59, v58
	ds_bpermute_b32 v59, v14, v58
	v_lshl_add_u64 v[2:3], v[2:3], 1, s[22:23]
	v_add_u32_e32 v62, 0x3c0, v61
	global_store_short v[2:3], v60, off
	v_add_u32_e32 v2, v62, v174
	s_waitcnt lgkmcnt(0)
	v_add_f32_e32 v58, v58, v59
	ds_bpermute_b32 v59, v10, v58
	v_ashrrev_i32_e32 v3, 31, v2
	v_lshl_add_u64 v[2:3], v[2:3], 1, s[22:23]
	global_store_short v[2:3], v15, off
	v_add_u32_e32 v2, v62, v175
	s_waitcnt lgkmcnt(0)
	v_add_f32_e32 v58, v58, v59
	ds_bpermute_b32 v59, v11, v58
	v_ashrrev_i32_e32 v3, 31, v2
	v_lshl_add_u64 v[2:3], v[2:3], 1, s[22:23]
	v_add_u32_e32 v62, 0x480, v61
	global_store_short v[2:3], v60, off
	s_waitcnt lgkmcnt(0)
	v_add_f32_e32 v58, v58, v59
	ds_bpermute_b32 v59, v12, v58
	v_add_u32_e32 v2, v62, v174
	v_ashrrev_i32_e32 v3, 31, v2
	v_lshl_add_u64 v[2:3], v[2:3], 1, s[22:23]
	global_store_short v[2:3], v15, off
	v_add_u32_e32 v2, v62, v175
	s_waitcnt lgkmcnt(0)
	v_add_f32_e32 v58, v58, v59
	v_ashrrev_i32_e32 v3, 31, v2
	ds_bpermute_b32 v59, v13, v58
	v_lshl_add_u64 v[2:3], v[2:3], 1, s[22:23]
	v_add_u32_e32 v61, 0x540, v61
	global_store_short v[2:3], v60, off
	v_or_b32_e32 v2, v61, v174
	v_ashrrev_i32_e32 v3, 31, v2
	v_lshl_add_u64 v[2:3], v[2:3], 1, s[22:23]
	global_store_short v[2:3], v15, off
	s_waitcnt lgkmcnt(0)
	v_add_f32_e32 v3, v58, v59
	v_fmamk_f32 v3, v3, 0x3c800000, v209
	v_rsq_f32_e32 v58, v3
	v_or_b32_e32 v2, v61, v175
	v_ashrrev_i32_e32 v3, 31, v2
	v_lshl_add_u64 v[2:3], v[2:3], 1, s[22:23]
	global_store_short v[2:3], v60, off
	v_pk_mul_f32 v[2:3], v[0:1], v[58:59] op_sel_hi:[1,0]
	s_and_b64 vcc, exec, s[4:5]
	v_pk_mul_f32 v[2:3], v[70:71], v[2:3]
	s_mov_b64 s[80:81], -1
	s_cbranch_vccnz .LBB0_282
	v_add_u32_e32 v15, s76, v178
	v_lshl_or_b32 v58, v15, 6, v156
	v_ashrrev_i32_e32 v59, 31, v58
	v_lshl_add_u64 v[58:59], v[58:59], 2, s[24:25]
	s_mov_b64 s[80:81], 0
	global_store_dword v[58:59], v3, off sc1
	global_store_dword v[58:59], v2, off offset:128 sc1

.LBB0_284:
	v_cvt_pk_bf16_f32 v60, v2, s0
	v_add_u32_e32 v2, s11, v178
	v_mul_lo_u32 v61, v2, s94
	v_or_b32_e32 v2, v61, v174
	v_cvt_pk_bf16_f32 v15, v3, s0
	v_ashrrev_i32_e32 v3, 31, v2
	v_lshl_add_u64 v[2:3], v[2:3], 1, s[22:23]
	global_store_short v[2:3], v15, off
	v_or_b32_e32 v2, v61, v175
	v_ashrrev_i32_e32 v3, 31, v2
	v_lshl_add_u64 v[2:3], v[2:3], 1, s[22:23]
	v_or_b32_e32 v58, 0xc0, v61
	global_store_short v[2:3], v60, off
	v_add_u32_e32 v2, v58, v174
	v_ashrrev_i32_e32 v3, 31, v2
	v_lshl_add_u64 v[2:3], v[2:3], 1, s[22:23]
	global_store_short v[2:3], v15, off
	v_add_u32_e32 v2, v58, v175
	v_ashrrev_i32_e32 v3, 31, v2
	v_lshl_add_u64 v[2:3], v[2:3], 1, s[22:23]
	v_or_b32_e32 v58, 0x180, v61
	global_store_short v[2:3], v60, off
	v_add_u32_e32 v2, v58, v174
	v_ashrrev_i32_e32 v3, 31, v2
	v_lshl_add_u64 v[2:3], v[2:3], 1, s[22:23]
	global_store_short v[2:3], v15, off
	v_add_u32_e32 v2, v58, v175
	v_ashrrev_i32_e32 v3, 31, v2
	v_lshl_add_u64 v[2:3], v[2:3], 1, s[22:23]
	v_add_u32_e32 v58, 0x240, v61
	global_store_short v[2:3], v60, off
	v_or_b32_e32 v2, v58, v174
	v_ashrrev_i32_e32 v3, 31, v2
	v_lshl_add_u64 v[2:3], v[2:3], 1, s[22:23]
	global_store_short v[2:3], v15, off
	v_or_b32_e32 v2, v58, v175
	v_ashrrev_i32_e32 v3, 31, v2
	v_lshl_add_u64 v[2:3], v[2:3], 1, s[22:23]
	v_add_u32_e32 v58, 0x300, v61
	global_store_short v[2:3], v60, off
	v_or_b32_e32 v2, v58, v174
	v_ashrrev_i32_e32 v3, 31, v2
	v_lshl_add_u64 v[2:3], v[2:3], 1, s[22:23]
	global_store_short v[2:3], v15, off
	v_or_b32_e32 v2, v58, v175
	v_pk_mul_f32 v[58:59], v[68:69], v[68:69]
	v_ashrrev_i32_e32 v3, 31, v2
	v_add_f32_e32 v58, v59, v58
	ds_bpermute_b32 v59, v14, v58
	v_lshl_add_u64 v[2:3], v[2:3], 1, s[22:23]
	v_add_u32_e32 v62, 0x3c0, v61
	global_store_short v[2:3], v60, off
	v_add_u32_e32 v2, v62, v174
	s_waitcnt lgkmcnt(0)
	v_add_f32_e32 v58, v58, v59
	ds_bpermute_b32 v59, v10, v58
	v_ashrrev_i32_e32 v3, 31, v2
	v_lshl_add_u64 v[2:3], v[2:3], 1, s[22:23]
	global_store_short v[2:3], v15, off
	v_add_u32_e32 v2, v62, v175
	s_waitcnt lgkmcnt(0)
	v_add_f32_e32 v58, v58, v59
	ds_bpermute_b32 v59, v11, v58
	v_ashrrev_i32_e32 v3, 31, v2
	v_lshl_add_u64 v[2:3], v[2:3], 1, s[22:23]
	v_add_u32_e32 v62, 0x480, v61
	global_store_short v[2:3], v60, off
	s_waitcnt lgkmcnt(0)
	v_add_f32_e32 v58, v58, v59
	ds_bpermute_b32 v59, v12, v58
	v_add_u32_e32 v2, v62, v174
	v_ashrrev_i32_e32 v3, 31, v2
	v_lshl_add_u64 v[2:3], v[2:3], 1, s[22:23]
	global_store_short v[2:3], v15, off
	v_add_u32_e32 v2, v62, v175
	s_waitcnt lgkmcnt(0)
	v_add_f32_e32 v58, v58, v59
	v_ashrrev_i32_e32 v3, 31, v2
	ds_bpermute_b32 v59, v13, v58
	v_lshl_add_u64 v[2:3], v[2:3], 1, s[22:23]
	v_add_u32_e32 v61, 0x540, v61
	global_store_short v[2:3], v60, off
	v_or_b32_e32 v2, v61, v174
	v_ashrrev_i32_e32 v3, 31, v2
	v_lshl_add_u64 v[2:3], v[2:3], 1, s[22:23]
	global_store_short v[2:3], v15, off
	s_waitcnt lgkmcnt(0)
	v_add_f32_e32 v3, v58, v59
	v_fmamk_f32 v3, v3, 0x3c800000, v209
	v_rsq_f32_e32 v58, v3
	v_or_b32_e32 v2, v61, v175
	v_ashrrev_i32_e32 v3, 31, v2
	v_lshl_add_u64 v[2:3], v[2:3], 1, s[22:23]
	global_store_short v[2:3], v60, off
	v_pk_mul_f32 v[2:3], v[0:1], v[58:59] op_sel_hi:[1,0]
	s_and_b64 vcc, exec, s[4:5]
	v_pk_mul_f32 v[2:3], v[68:69], v[2:3]
	s_mov_b64 s[80:81], -1
	s_cbranch_vccnz .LBB0_286
	v_add_u32_e32 v15, s76, v179
	v_lshl_or_b32 v58, v15, 6, v156
	v_ashrrev_i32_e32 v59, 31, v58
	v_lshl_add_u64 v[58:59], v[58:59], 2, s[24:25]
	s_mov_b64 s[80:81], 0
	global_store_dword v[58:59], v3, off sc1
	global_store_dword v[58:59], v2, off offset:128 sc1

.LBB0_288:
	v_cvt_pk_bf16_f32 v60, v2, s0
	v_add_u32_e32 v2, s11, v179
	v_mul_lo_u32 v61, v2, s94
	v_or_b32_e32 v2, v61, v174
	v_cvt_pk_bf16_f32 v15, v3, s0
	v_ashrrev_i32_e32 v3, 31, v2
	v_lshl_add_u64 v[2:3], v[2:3], 1, s[22:23]
	global_store_short v[2:3], v15, off
	v_or_b32_e32 v2, v61, v175
	v_ashrrev_i32_e32 v3, 31, v2
	v_lshl_add_u64 v[2:3], v[2:3], 1, s[22:23]
	v_or_b32_e32 v58, 0xc0, v61
	global_store_short v[2:3], v60, off
	v_add_u32_e32 v2, v58, v174
	v_ashrrev_i32_e32 v3, 31, v2
	v_lshl_add_u64 v[2:3], v[2:3], 1, s[22:23]
	global_store_short v[2:3], v15, off
	v_add_u32_e32 v2, v58, v175
	v_ashrrev_i32_e32 v3, 31, v2
	v_lshl_add_u64 v[2:3], v[2:3], 1, s[22:23]
	v_or_b32_e32 v58, 0x180, v61
	global_store_short v[2:3], v60, off
	v_add_u32_e32 v2, v58, v174
	v_ashrrev_i32_e32 v3, 31, v2
	v_lshl_add_u64 v[2:3], v[2:3], 1, s[22:23]
	global_store_short v[2:3], v15, off
	v_add_u32_e32 v2, v58, v175
	v_ashrrev_i32_e32 v3, 31, v2
	v_lshl_add_u64 v[2:3], v[2:3], 1, s[22:23]
	v_add_u32_e32 v58, 0x240, v61
	global_store_short v[2:3], v60, off
	v_or_b32_e32 v2, v58, v174
	v_ashrrev_i32_e32 v3, 31, v2
	v_lshl_add_u64 v[2:3], v[2:3], 1, s[22:23]
	global_store_short v[2:3], v15, off
	v_or_b32_e32 v2, v58, v175
	v_ashrrev_i32_e32 v3, 31, v2
	v_lshl_add_u64 v[2:3], v[2:3], 1, s[22:23]
	v_add_u32_e32 v58, 0x300, v61
	global_store_short v[2:3], v60, off
	v_or_b32_e32 v2, v58, v174
	v_ashrrev_i32_e32 v3, 31, v2
	v_lshl_add_u64 v[2:3], v[2:3], 1, s[22:23]
	global_store_short v[2:3], v15, off
	v_or_b32_e32 v2, v58, v175
	v_pk_mul_f32 v[58:59], v[66:67], v[66:67]
	v_ashrrev_i32_e32 v3, 31, v2
	v_add_f32_e32 v58, v59, v58
	ds_bpermute_b32 v59, v14, v58
	v_lshl_add_u64 v[2:3], v[2:3], 1, s[22:23]
	v_add_u32_e32 v62, 0x3c0, v61
	global_store_short v[2:3], v60, off
	v_add_u32_e32 v2, v62, v174
	s_waitcnt lgkmcnt(0)
	v_add_f32_e32 v58, v58, v59
	ds_bpermute_b32 v59, v10, v58
	v_ashrrev_i32_e32 v3, 31, v2
	v_lshl_add_u64 v[2:3], v[2:3], 1, s[22:23]
	global_store_short v[2:3], v15, off
	v_add_u32_e32 v2, v62, v175
	s_waitcnt lgkmcnt(0)
	v_add_f32_e32 v58, v58, v59
	ds_bpermute_b32 v59, v11, v58
	v_ashrrev_i32_e32 v3, 31, v2
	v_lshl_add_u64 v[2:3], v[2:3], 1, s[22:23]
	v_add_u32_e32 v62, 0x480, v61
	global_store_short v[2:3], v60, off
	s_waitcnt lgkmcnt(0)
	v_add_f32_e32 v58, v58, v59
	ds_bpermute_b32 v59, v12, v58
	v_add_u32_e32 v2, v62, v174
	v_ashrrev_i32_e32 v3, 31, v2
	v_lshl_add_u64 v[2:3], v[2:3], 1, s[22:23]
	global_store_short v[2:3], v15, off
	v_add_u32_e32 v2, v62, v175
	s_waitcnt lgkmcnt(0)
	v_add_f32_e32 v58, v58, v59
	v_ashrrev_i32_e32 v3, 31, v2
	ds_bpermute_b32 v59, v13, v58
	v_lshl_add_u64 v[2:3], v[2:3], 1, s[22:23]
	v_add_u32_e32 v61, 0x540, v61
	global_store_short v[2:3], v60, off
	v_or_b32_e32 v2, v61, v174
	v_ashrrev_i32_e32 v3, 31, v2
	v_lshl_add_u64 v[2:3], v[2:3], 1, s[22:23]
	global_store_short v[2:3], v15, off
	s_waitcnt lgkmcnt(0)
	v_add_f32_e32 v3, v58, v59
	v_fmamk_f32 v3, v3, 0x3c800000, v209
	v_rsq_f32_e32 v58, v3
	v_or_b32_e32 v2, v61, v175
	v_ashrrev_i32_e32 v3, 31, v2
	v_lshl_add_u64 v[2:3], v[2:3], 1, s[22:23]
	global_store_short v[2:3], v60, off
	v_pk_mul_f32 v[2:3], v[0:1], v[58:59] op_sel_hi:[1,0]
	s_and_b64 vcc, exec, s[4:5]
	v_pk_mul_f32 v[2:3], v[66:67], v[2:3]
	s_mov_b64 s[80:81], -1
	s_cbranch_vccnz .LBB0_290
	v_add_u32_e32 v15, s76, v180
	v_lshl_or_b32 v58, v15, 6, v156
	v_ashrrev_i32_e32 v59, 31, v58
	v_lshl_add_u64 v[58:59], v[58:59], 2, s[24:25]
	s_mov_b64 s[80:81], 0
	global_store_dword v[58:59], v3, off sc1
	global_store_dword v[58:59], v2, off offset:128 sc1

.LBB0_292:
	v_cvt_pk_bf16_f32 v60, v2, s0
	v_add_u32_e32 v2, s11, v180
	v_mul_lo_u32 v61, v2, s94
	v_or_b32_e32 v2, v61, v174
	v_cvt_pk_bf16_f32 v15, v3, s0
	v_ashrrev_i32_e32 v3, 31, v2
	v_lshl_add_u64 v[2:3], v[2:3], 1, s[22:23]
	global_store_short v[2:3], v15, off
	v_or_b32_e32 v2, v61, v175
	v_ashrrev_i32_e32 v3, 31, v2
	v_lshl_add_u64 v[2:3], v[2:3], 1, s[22:23]
	v_or_b32_e32 v58, 0xc0, v61
	global_store_short v[2:3], v60, off
	v_add_u32_e32 v2, v58, v174
	v_ashrrev_i32_e32 v3, 31, v2
	v_lshl_add_u64 v[2:3], v[2:3], 1, s[22:23]
	global_store_short v[2:3], v15, off
	v_add_u32_e32 v2, v58, v175
	v_ashrrev_i32_e32 v3, 31, v2
	v_lshl_add_u64 v[2:3], v[2:3], 1, s[22:23]
	v_or_b32_e32 v58, 0x180, v61
	global_store_short v[2:3], v60, off
	v_add_u32_e32 v2, v58, v174
	v_ashrrev_i32_e32 v3, 31, v2
	v_lshl_add_u64 v[2:3], v[2:3], 1, s[22:23]
	global_store_short v[2:3], v15, off
	v_add_u32_e32 v2, v58, v175
	v_ashrrev_i32_e32 v3, 31, v2
	v_lshl_add_u64 v[2:3], v[2:3], 1, s[22:23]
	v_add_u32_e32 v58, 0x240, v61
	global_store_short v[2:3], v60, off
	v_or_b32_e32 v2, v58, v174
	v_ashrrev_i32_e32 v3, 31, v2
	v_lshl_add_u64 v[2:3], v[2:3], 1, s[22:23]
	global_store_short v[2:3], v15, off
	v_or_b32_e32 v2, v58, v175
	v_ashrrev_i32_e32 v3, 31, v2
	v_lshl_add_u64 v[2:3], v[2:3], 1, s[22:23]
	v_add_u32_e32 v58, 0x300, v61
	global_store_short v[2:3], v60, off
	v_or_b32_e32 v2, v58, v174
	v_ashrrev_i32_e32 v3, 31, v2
	v_lshl_add_u64 v[2:3], v[2:3], 1, s[22:23]
	global_store_short v[2:3], v15, off
	v_or_b32_e32 v2, v58, v175
	v_pk_mul_f32 v[58:59], v[64:65], v[64:65]
	v_ashrrev_i32_e32 v3, 31, v2
	v_add_f32_e32 v58, v59, v58
	ds_bpermute_b32 v59, v14, v58
	v_lshl_add_u64 v[2:3], v[2:3], 1, s[22:23]
	v_add_u32_e32 v62, 0x3c0, v61
	global_store_short v[2:3], v60, off
	v_add_u32_e32 v2, v62, v174
	s_waitcnt lgkmcnt(0)
	v_add_f32_e32 v58, v58, v59
	ds_bpermute_b32 v59, v10, v58
	v_ashrrev_i32_e32 v3, 31, v2
	v_lshl_add_u64 v[2:3], v[2:3], 1, s[22:23]
	global_store_short v[2:3], v15, off
	v_add_u32_e32 v2, v62, v175
	s_waitcnt lgkmcnt(0)
	v_add_f32_e32 v58, v58, v59
	ds_bpermute_b32 v59, v11, v58
	v_ashrrev_i32_e32 v3, 31, v2
	v_lshl_add_u64 v[2:3], v[2:3], 1, s[22:23]
	v_add_u32_e32 v62, 0x480, v61
	global_store_short v[2:3], v60, off
	s_waitcnt lgkmcnt(0)
	v_add_f32_e32 v58, v58, v59
	ds_bpermute_b32 v59, v12, v58
	v_add_u32_e32 v2, v62, v174
	v_ashrrev_i32_e32 v3, 31, v2
	v_lshl_add_u64 v[2:3], v[2:3], 1, s[22:23]
	global_store_short v[2:3], v15, off
	v_add_u32_e32 v2, v62, v175
	s_waitcnt lgkmcnt(0)
	v_add_f32_e32 v58, v58, v59
	v_ashrrev_i32_e32 v3, 31, v2
	ds_bpermute_b32 v59, v13, v58
	v_lshl_add_u64 v[2:3], v[2:3], 1, s[22:23]
	v_add_u32_e32 v61, 0x540, v61
	global_store_short v[2:3], v60, off
	v_or_b32_e32 v2, v61, v174
	v_ashrrev_i32_e32 v3, 31, v2
	v_lshl_add_u64 v[2:3], v[2:3], 1, s[22:23]
	global_store_short v[2:3], v15, off
	s_waitcnt lgkmcnt(0)
	v_add_f32_e32 v3, v58, v59
	v_fmamk_f32 v3, v3, 0x3c800000, v209
	v_rsq_f32_e32 v58, v3
	v_or_b32_e32 v2, v61, v175
	v_ashrrev_i32_e32 v3, 31, v2
	v_lshl_add_u64 v[2:3], v[2:3], 1, s[22:23]
	global_store_short v[2:3], v60, off
	v_pk_mul_f32 v[2:3], v[0:1], v[58:59] op_sel_hi:[1,0]
	s_and_b64 vcc, exec, s[4:5]
	v_pk_mul_f32 v[2:3], v[64:65], v[2:3]
	s_mov_b64 s[80:81], -1
	s_cbranch_vccnz .LBB0_294
	v_add_u32_e32 v15, s76, v181
	v_lshl_or_b32 v58, v15, 6, v156
	v_ashrrev_i32_e32 v59, 31, v58
	v_lshl_add_u64 v[58:59], v[58:59], 2, s[24:25]
	s_mov_b64 s[80:81], 0
	global_store_dword v[58:59], v3, off sc1
	global_store_dword v[58:59], v2, off offset:128 sc1

.LBB0_296:
	v_cvt_pk_bf16_f32 v60, v2, s0
	v_add_u32_e32 v2, s11, v181
	v_mul_lo_u32 v61, v2, s94
	v_or_b32_e32 v2, v61, v174
	v_cvt_pk_bf16_f32 v15, v3, s0
	v_ashrrev_i32_e32 v3, 31, v2
	v_lshl_add_u64 v[2:3], v[2:3], 1, s[22:23]
	global_store_short v[2:3], v15, off
	v_or_b32_e32 v2, v61, v175
	v_ashrrev_i32_e32 v3, 31, v2
	v_lshl_add_u64 v[2:3], v[2:3], 1, s[22:23]
	v_or_b32_e32 v58, 0xc0, v61
	global_store_short v[2:3], v60, off
	v_add_u32_e32 v2, v58, v174
	v_ashrrev_i32_e32 v3, 31, v2
	v_lshl_add_u64 v[2:3], v[2:3], 1, s[22:23]
	global_store_short v[2:3], v15, off
	v_add_u32_e32 v2, v58, v175
	v_ashrrev_i32_e32 v3, 31, v2
	v_lshl_add_u64 v[2:3], v[2:3], 1, s[22:23]
	v_or_b32_e32 v58, 0x180, v61
	global_store_short v[2:3], v60, off
	v_add_u32_e32 v2, v58, v174
	v_ashrrev_i32_e32 v3, 31, v2
	v_lshl_add_u64 v[2:3], v[2:3], 1, s[22:23]
	global_store_short v[2:3], v15, off
	v_add_u32_e32 v2, v58, v175
	v_ashrrev_i32_e32 v3, 31, v2
	v_lshl_add_u64 v[2:3], v[2:3], 1, s[22:23]
	v_add_u32_e32 v58, 0x240, v61
	global_store_short v[2:3], v60, off
	v_or_b32_e32 v2, v58, v174
	v_ashrrev_i32_e32 v3, 31, v2
	v_lshl_add_u64 v[2:3], v[2:3], 1, s[22:23]
	global_store_short v[2:3], v15, off
	v_or_b32_e32 v2, v58, v175
	v_ashrrev_i32_e32 v3, 31, v2
	v_lshl_add_u64 v[2:3], v[2:3], 1, s[22:23]
	v_add_u32_e32 v58, 0x300, v61
	global_store_short v[2:3], v60, off
	v_or_b32_e32 v2, v58, v174
	v_ashrrev_i32_e32 v3, 31, v2
	v_lshl_add_u64 v[2:3], v[2:3], 1, s[22:23]
	global_store_short v[2:3], v15, off
	v_or_b32_e32 v2, v58, v175
	v_pk_mul_f32 v[58:59], v[54:55], v[54:55]
	v_ashrrev_i32_e32 v3, 31, v2
	v_add_f32_e32 v58, v59, v58
	ds_bpermute_b32 v59, v14, v58
	v_lshl_add_u64 v[2:3], v[2:3], 1, s[22:23]
	v_add_u32_e32 v62, 0x3c0, v61
	global_store_short v[2:3], v60, off
	v_add_u32_e32 v2, v62, v174
	s_waitcnt lgkmcnt(0)
	v_add_f32_e32 v58, v58, v59
	ds_bpermute_b32 v59, v10, v58
	v_ashrrev_i32_e32 v3, 31, v2
	v_lshl_add_u64 v[2:3], v[2:3], 1, s[22:23]
	global_store_short v[2:3], v15, off
	v_add_u32_e32 v2, v62, v175
	s_waitcnt lgkmcnt(0)
	v_add_f32_e32 v58, v58, v59
	ds_bpermute_b32 v59, v11, v58
	v_ashrrev_i32_e32 v3, 31, v2
	v_lshl_add_u64 v[2:3], v[2:3], 1, s[22:23]
	v_add_u32_e32 v62, 0x480, v61
	global_store_short v[2:3], v60, off
	s_waitcnt lgkmcnt(0)
	v_add_f32_e32 v58, v58, v59
	ds_bpermute_b32 v59, v12, v58
	v_add_u32_e32 v2, v62, v174
	v_ashrrev_i32_e32 v3, 31, v2
	v_lshl_add_u64 v[2:3], v[2:3], 1, s[22:23]
	global_store_short v[2:3], v15, off
	v_add_u32_e32 v2, v62, v175
	s_waitcnt lgkmcnt(0)
	v_add_f32_e32 v58, v58, v59
	v_ashrrev_i32_e32 v3, 31, v2
	ds_bpermute_b32 v59, v13, v58
	v_lshl_add_u64 v[2:3], v[2:3], 1, s[22:23]
	v_add_u32_e32 v61, 0x540, v61
	global_store_short v[2:3], v60, off
	v_or_b32_e32 v2, v61, v174
	v_ashrrev_i32_e32 v3, 31, v2
	v_lshl_add_u64 v[2:3], v[2:3], 1, s[22:23]
	global_store_short v[2:3], v15, off
	s_waitcnt lgkmcnt(0)
	v_add_f32_e32 v3, v58, v59
	v_fmamk_f32 v3, v3, 0x3c800000, v209
	v_rsq_f32_e32 v58, v3
	v_or_b32_e32 v2, v61, v175
	v_ashrrev_i32_e32 v3, 31, v2
	v_lshl_add_u64 v[2:3], v[2:3], 1, s[22:23]
	global_store_short v[2:3], v60, off
	v_pk_mul_f32 v[2:3], v[0:1], v[58:59] op_sel_hi:[1,0]
	s_and_b64 vcc, exec, s[4:5]
	v_pk_mul_f32 v[2:3], v[54:55], v[2:3]
	s_mov_b64 s[80:81], -1
	s_cbranch_vccnz .LBB0_298
	v_add_u32_e32 v15, s76, v182
	v_lshl_or_b32 v58, v15, 6, v156
	v_ashrrev_i32_e32 v59, 31, v58
	v_lshl_add_u64 v[58:59], v[58:59], 2, s[24:25]
	s_mov_b64 s[80:81], 0
	global_store_dword v[58:59], v3, off sc1
	global_store_dword v[58:59], v2, off offset:128 sc1

.LBB0_300:
	v_cvt_pk_bf16_f32 v60, v2, s0
	v_add_u32_e32 v2, s11, v182
	v_mul_lo_u32 v61, v2, s94
	v_or_b32_e32 v2, v61, v174
	v_cvt_pk_bf16_f32 v15, v3, s0
	v_ashrrev_i32_e32 v3, 31, v2
	v_lshl_add_u64 v[2:3], v[2:3], 1, s[22:23]
	global_store_short v[2:3], v15, off
	v_or_b32_e32 v2, v61, v175
	v_ashrrev_i32_e32 v3, 31, v2
	v_lshl_add_u64 v[2:3], v[2:3], 1, s[22:23]
	v_or_b32_e32 v58, 0xc0, v61
	global_store_short v[2:3], v60, off
	v_add_u32_e32 v2, v58, v174
	v_ashrrev_i32_e32 v3, 31, v2
	v_lshl_add_u64 v[2:3], v[2:3], 1, s[22:23]
	global_store_short v[2:3], v15, off
	v_add_u32_e32 v2, v58, v175
	v_ashrrev_i32_e32 v3, 31, v2
	v_lshl_add_u64 v[2:3], v[2:3], 1, s[22:23]
	v_or_b32_e32 v58, 0x180, v61
	global_store_short v[2:3], v60, off
	v_add_u32_e32 v2, v58, v174
	v_ashrrev_i32_e32 v3, 31, v2
	v_lshl_add_u64 v[2:3], v[2:3], 1, s[22:23]
	global_store_short v[2:3], v15, off
	v_add_u32_e32 v2, v58, v175
	v_ashrrev_i32_e32 v3, 31, v2
	v_lshl_add_u64 v[2:3], v[2:3], 1, s[22:23]
	v_add_u32_e32 v58, 0x240, v61
	global_store_short v[2:3], v60, off
	v_or_b32_e32 v2, v58, v174
	v_ashrrev_i32_e32 v3, 31, v2
	v_lshl_add_u64 v[2:3], v[2:3], 1, s[22:23]
	global_store_short v[2:3], v15, off
	v_or_b32_e32 v2, v58, v175
	v_ashrrev_i32_e32 v3, 31, v2
	v_lshl_add_u64 v[2:3], v[2:3], 1, s[22:23]
	v_add_u32_e32 v58, 0x300, v61
	global_store_short v[2:3], v60, off
	v_or_b32_e32 v2, v58, v174
	v_ashrrev_i32_e32 v3, 31, v2
	v_lshl_add_u64 v[2:3], v[2:3], 1, s[22:23]
	global_store_short v[2:3], v15, off
	v_or_b32_e32 v2, v58, v175
	v_pk_mul_f32 v[58:59], v[52:53], v[52:53]
	v_ashrrev_i32_e32 v3, 31, v2
	v_add_f32_e32 v58, v59, v58
	ds_bpermute_b32 v59, v14, v58
	v_lshl_add_u64 v[2:3], v[2:3], 1, s[22:23]
	v_add_u32_e32 v62, 0x3c0, v61
	global_store_short v[2:3], v60, off
	v_add_u32_e32 v2, v62, v174
	s_waitcnt lgkmcnt(0)
	v_add_f32_e32 v58, v58, v59
	ds_bpermute_b32 v59, v10, v58
	v_ashrrev_i32_e32 v3, 31, v2
	v_lshl_add_u64 v[2:3], v[2:3], 1, s[22:23]
	global_store_short v[2:3], v15, off
	v_add_u32_e32 v2, v62, v175
	s_waitcnt lgkmcnt(0)
	v_add_f32_e32 v58, v58, v59
	ds_bpermute_b32 v59, v11, v58
	v_ashrrev_i32_e32 v3, 31, v2
	v_lshl_add_u64 v[2:3], v[2:3], 1, s[22:23]
	v_add_u32_e32 v62, 0x480, v61
	global_store_short v[2:3], v60, off
	s_waitcnt lgkmcnt(0)
	v_add_f32_e32 v58, v58, v59
	ds_bpermute_b32 v59, v12, v58
	v_add_u32_e32 v2, v62, v174
	v_ashrrev_i32_e32 v3, 31, v2
	v_lshl_add_u64 v[2:3], v[2:3], 1, s[22:23]
	global_store_short v[2:3], v15, off
	v_add_u32_e32 v2, v62, v175
	s_waitcnt lgkmcnt(0)
	v_add_f32_e32 v58, v58, v59
	v_ashrrev_i32_e32 v3, 31, v2
	ds_bpermute_b32 v59, v13, v58
	v_lshl_add_u64 v[2:3], v[2:3], 1, s[22:23]
	v_add_u32_e32 v61, 0x540, v61
	global_store_short v[2:3], v60, off
	v_or_b32_e32 v2, v61, v174
	v_ashrrev_i32_e32 v3, 31, v2
	v_lshl_add_u64 v[2:3], v[2:3], 1, s[22:23]
	global_store_short v[2:3], v15, off
	s_waitcnt lgkmcnt(0)
	v_add_f32_e32 v3, v58, v59
	v_fmamk_f32 v3, v3, 0x3c800000, v209
	v_rsq_f32_e32 v58, v3
	v_or_b32_e32 v2, v61, v175
	v_ashrrev_i32_e32 v3, 31, v2
	v_lshl_add_u64 v[2:3], v[2:3], 1, s[22:23]
	global_store_short v[2:3], v60, off
	v_pk_mul_f32 v[2:3], v[0:1], v[58:59] op_sel_hi:[1,0]
	s_and_b64 vcc, exec, s[4:5]
	v_pk_mul_f32 v[2:3], v[52:53], v[2:3]
	s_mov_b64 s[80:81], -1
	s_cbranch_vccnz .LBB0_302
	v_add_u32_e32 v15, s76, v183
	v_lshl_or_b32 v58, v15, 6, v156
	v_ashrrev_i32_e32 v59, 31, v58
	v_lshl_add_u64 v[58:59], v[58:59], 2, s[24:25]
	s_mov_b64 s[80:81], 0
	global_store_dword v[58:59], v3, off sc1
	global_store_dword v[58:59], v2, off offset:128 sc1

.LBB0_304:
	v_cvt_pk_bf16_f32 v60, v2, s0
	v_add_u32_e32 v2, s11, v183
	v_mul_lo_u32 v61, v2, s94
	v_or_b32_e32 v2, v61, v174
	v_cvt_pk_bf16_f32 v15, v3, s0
	v_ashrrev_i32_e32 v3, 31, v2
	v_lshl_add_u64 v[2:3], v[2:3], 1, s[22:23]
	global_store_short v[2:3], v15, off
	v_or_b32_e32 v2, v61, v175
	v_ashrrev_i32_e32 v3, 31, v2
	v_lshl_add_u64 v[2:3], v[2:3], 1, s[22:23]
	v_or_b32_e32 v58, 0xc0, v61
	global_store_short v[2:3], v60, off
	v_add_u32_e32 v2, v58, v174
	v_ashrrev_i32_e32 v3, 31, v2
	v_lshl_add_u64 v[2:3], v[2:3], 1, s[22:23]
	global_store_short v[2:3], v15, off
	v_add_u32_e32 v2, v58, v175
	v_ashrrev_i32_e32 v3, 31, v2
	v_lshl_add_u64 v[2:3], v[2:3], 1, s[22:23]
	v_or_b32_e32 v58, 0x180, v61
	global_store_short v[2:3], v60, off
	v_add_u32_e32 v2, v58, v174
	v_ashrrev_i32_e32 v3, 31, v2
	v_lshl_add_u64 v[2:3], v[2:3], 1, s[22:23]
	global_store_short v[2:3], v15, off
	v_add_u32_e32 v2, v58, v175
	v_ashrrev_i32_e32 v3, 31, v2
	v_lshl_add_u64 v[2:3], v[2:3], 1, s[22:23]
	v_add_u32_e32 v58, 0x240, v61
	global_store_short v[2:3], v60, off
	v_or_b32_e32 v2, v58, v174
	v_ashrrev_i32_e32 v3, 31, v2
	v_lshl_add_u64 v[2:3], v[2:3], 1, s[22:23]
	global_store_short v[2:3], v15, off
	v_or_b32_e32 v2, v58, v175
	v_ashrrev_i32_e32 v3, 31, v2
	v_lshl_add_u64 v[2:3], v[2:3], 1, s[22:23]
	v_add_u32_e32 v58, 0x300, v61
	global_store_short v[2:3], v60, off
	v_or_b32_e32 v2, v58, v174
	v_ashrrev_i32_e32 v3, 31, v2
	v_lshl_add_u64 v[2:3], v[2:3], 1, s[22:23]
	global_store_short v[2:3], v15, off
	v_or_b32_e32 v2, v58, v175
	v_pk_mul_f32 v[58:59], v[50:51], v[50:51]
	v_ashrrev_i32_e32 v3, 31, v2
	v_add_f32_e32 v58, v59, v58
	ds_bpermute_b32 v59, v14, v58
	v_lshl_add_u64 v[2:3], v[2:3], 1, s[22:23]
	v_add_u32_e32 v62, 0x3c0, v61
	global_store_short v[2:3], v60, off
	v_add_u32_e32 v2, v62, v174
	s_waitcnt lgkmcnt(0)
	v_add_f32_e32 v58, v58, v59
	ds_bpermute_b32 v59, v10, v58
	v_ashrrev_i32_e32 v3, 31, v2
	v_lshl_add_u64 v[2:3], v[2:3], 1, s[22:23]
	global_store_short v[2:3], v15, off
	v_add_u32_e32 v2, v62, v175
	s_waitcnt lgkmcnt(0)
	v_add_f32_e32 v58, v58, v59
	ds_bpermute_b32 v59, v11, v58
	v_ashrrev_i32_e32 v3, 31, v2
	v_lshl_add_u64 v[2:3], v[2:3], 1, s[22:23]
	v_add_u32_e32 v62, 0x480, v61
	global_store_short v[2:3], v60, off
	s_waitcnt lgkmcnt(0)
	v_add_f32_e32 v58, v58, v59
	ds_bpermute_b32 v59, v12, v58
	v_add_u32_e32 v2, v62, v174
	v_ashrrev_i32_e32 v3, 31, v2
	v_lshl_add_u64 v[2:3], v[2:3], 1, s[22:23]
	global_store_short v[2:3], v15, off
	v_add_u32_e32 v2, v62, v175
	s_waitcnt lgkmcnt(0)
	v_add_f32_e32 v58, v58, v59
	v_ashrrev_i32_e32 v3, 31, v2
	ds_bpermute_b32 v59, v13, v58
	v_lshl_add_u64 v[2:3], v[2:3], 1, s[22:23]
	v_add_u32_e32 v61, 0x540, v61
	global_store_short v[2:3], v60, off
	v_or_b32_e32 v2, v61, v174
	v_ashrrev_i32_e32 v3, 31, v2
	v_lshl_add_u64 v[2:3], v[2:3], 1, s[22:23]
	global_store_short v[2:3], v15, off
	s_waitcnt lgkmcnt(0)
	v_add_f32_e32 v3, v58, v59
	v_fmamk_f32 v3, v3, 0x3c800000, v209
	v_rsq_f32_e32 v58, v3
	v_or_b32_e32 v2, v61, v175
	v_ashrrev_i32_e32 v3, 31, v2
	v_lshl_add_u64 v[2:3], v[2:3], 1, s[22:23]
	global_store_short v[2:3], v60, off
	v_pk_mul_f32 v[2:3], v[0:1], v[58:59] op_sel_hi:[1,0]
	s_and_b64 vcc, exec, s[4:5]
	v_pk_mul_f32 v[2:3], v[50:51], v[2:3]
	s_mov_b64 s[80:81], -1
	s_cbranch_vccnz .LBB0_306
	v_add_u32_e32 v15, s76, v184
	v_lshl_or_b32 v58, v15, 6, v156
	v_ashrrev_i32_e32 v59, 31, v58
	v_lshl_add_u64 v[58:59], v[58:59], 2, s[24:25]
	s_mov_b64 s[80:81], 0
	global_store_dword v[58:59], v3, off sc1
	global_store_dword v[58:59], v2, off offset:128 sc1

.LBB0_308:
	v_cvt_pk_bf16_f32 v60, v2, s0
	v_add_u32_e32 v2, s11, v184
	v_mul_lo_u32 v61, v2, s94
	v_or_b32_e32 v2, v61, v174
	v_cvt_pk_bf16_f32 v15, v3, s0
	v_ashrrev_i32_e32 v3, 31, v2
	v_lshl_add_u64 v[2:3], v[2:3], 1, s[22:23]
	global_store_short v[2:3], v15, off
	v_or_b32_e32 v2, v61, v175
	v_ashrrev_i32_e32 v3, 31, v2
	v_lshl_add_u64 v[2:3], v[2:3], 1, s[22:23]
	v_or_b32_e32 v58, 0xc0, v61
	global_store_short v[2:3], v60, off
	v_add_u32_e32 v2, v58, v174
	v_ashrrev_i32_e32 v3, 31, v2
	v_lshl_add_u64 v[2:3], v[2:3], 1, s[22:23]
	global_store_short v[2:3], v15, off
	v_add_u32_e32 v2, v58, v175
	v_ashrrev_i32_e32 v3, 31, v2
	v_lshl_add_u64 v[2:3], v[2:3], 1, s[22:23]
	v_or_b32_e32 v58, 0x180, v61
	global_store_short v[2:3], v60, off
	v_add_u32_e32 v2, v58, v174
	v_ashrrev_i32_e32 v3, 31, v2
	v_lshl_add_u64 v[2:3], v[2:3], 1, s[22:23]
	global_store_short v[2:3], v15, off
	v_add_u32_e32 v2, v58, v175
	v_ashrrev_i32_e32 v3, 31, v2
	v_lshl_add_u64 v[2:3], v[2:3], 1, s[22:23]
	v_add_u32_e32 v58, 0x240, v61
	global_store_short v[2:3], v60, off
	v_or_b32_e32 v2, v58, v174
	v_ashrrev_i32_e32 v3, 31, v2
	v_lshl_add_u64 v[2:3], v[2:3], 1, s[22:23]
	global_store_short v[2:3], v15, off
	v_or_b32_e32 v2, v58, v175
	v_ashrrev_i32_e32 v3, 31, v2
	v_lshl_add_u64 v[2:3], v[2:3], 1, s[22:23]
	v_add_u32_e32 v58, 0x300, v61
	global_store_short v[2:3], v60, off
	v_or_b32_e32 v2, v58, v174
	v_ashrrev_i32_e32 v3, 31, v2
	v_lshl_add_u64 v[2:3], v[2:3], 1, s[22:23]
	global_store_short v[2:3], v15, off
	v_or_b32_e32 v2, v58, v175
	v_pk_mul_f32 v[58:59], v[48:49], v[48:49]
	v_ashrrev_i32_e32 v3, 31, v2
	v_add_f32_e32 v58, v59, v58
	ds_bpermute_b32 v59, v14, v58
	v_lshl_add_u64 v[2:3], v[2:3], 1, s[22:23]
	v_add_u32_e32 v62, 0x3c0, v61
	global_store_short v[2:3], v60, off
	v_add_u32_e32 v2, v62, v174
	s_waitcnt lgkmcnt(0)
	v_add_f32_e32 v58, v58, v59
	ds_bpermute_b32 v59, v10, v58
	v_ashrrev_i32_e32 v3, 31, v2
	v_lshl_add_u64 v[2:3], v[2:3], 1, s[22:23]
	global_store_short v[2:3], v15, off
	v_add_u32_e32 v2, v62, v175
	s_waitcnt lgkmcnt(0)
	v_add_f32_e32 v58, v58, v59
	ds_bpermute_b32 v59, v11, v58
	v_ashrrev_i32_e32 v3, 31, v2
	v_lshl_add_u64 v[2:3], v[2:3], 1, s[22:23]
	v_add_u32_e32 v62, 0x480, v61
	global_store_short v[2:3], v60, off
	s_waitcnt lgkmcnt(0)
	v_add_f32_e32 v58, v58, v59
	ds_bpermute_b32 v59, v12, v58
	v_add_u32_e32 v2, v62, v174
	v_ashrrev_i32_e32 v3, 31, v2
	v_lshl_add_u64 v[2:3], v[2:3], 1, s[22:23]
	global_store_short v[2:3], v15, off
	v_add_u32_e32 v2, v62, v175
	s_waitcnt lgkmcnt(0)
	v_add_f32_e32 v58, v58, v59
	v_ashrrev_i32_e32 v3, 31, v2
	ds_bpermute_b32 v59, v13, v58
	v_lshl_add_u64 v[2:3], v[2:3], 1, s[22:23]
	v_add_u32_e32 v61, 0x540, v61
	global_store_short v[2:3], v60, off
	v_or_b32_e32 v2, v61, v174
	v_ashrrev_i32_e32 v3, 31, v2
	v_lshl_add_u64 v[2:3], v[2:3], 1, s[22:23]
	global_store_short v[2:3], v15, off
	s_waitcnt lgkmcnt(0)
	v_add_f32_e32 v3, v58, v59
	v_fmamk_f32 v3, v3, 0x3c800000, v209
	v_rsq_f32_e32 v58, v3
	v_or_b32_e32 v2, v61, v175
	v_ashrrev_i32_e32 v3, 31, v2
	v_lshl_add_u64 v[2:3], v[2:3], 1, s[22:23]
	global_store_short v[2:3], v60, off
	v_pk_mul_f32 v[2:3], v[0:1], v[58:59] op_sel_hi:[1,0]
	s_and_b64 vcc, exec, s[4:5]
	v_pk_mul_f32 v[2:3], v[48:49], v[2:3]
	s_mov_b64 s[80:81], -1
	s_cbranch_vccnz .LBB0_310
	v_add_u32_e32 v15, s76, v185
	v_lshl_or_b32 v58, v15, 6, v156
	v_ashrrev_i32_e32 v59, 31, v58
	v_lshl_add_u64 v[58:59], v[58:59], 2, s[24:25]
	s_mov_b64 s[80:81], 0
	global_store_dword v[58:59], v3, off sc1
	global_store_dword v[58:59], v2, off offset:128 sc1

.LBB0_312:
	v_cvt_pk_bf16_f32 v60, v2, s0
	v_add_u32_e32 v2, s11, v185
	v_mul_lo_u32 v61, v2, s94
	v_or_b32_e32 v2, v61, v174
	v_cvt_pk_bf16_f32 v15, v3, s0
	v_ashrrev_i32_e32 v3, 31, v2
	v_lshl_add_u64 v[2:3], v[2:3], 1, s[22:23]
	global_store_short v[2:3], v15, off
	v_or_b32_e32 v2, v61, v175
	v_ashrrev_i32_e32 v3, 31, v2
	v_lshl_add_u64 v[2:3], v[2:3], 1, s[22:23]
	v_or_b32_e32 v58, 0xc0, v61
	global_store_short v[2:3], v60, off
	v_add_u32_e32 v2, v58, v174
	v_ashrrev_i32_e32 v3, 31, v2
	v_lshl_add_u64 v[2:3], v[2:3], 1, s[22:23]
	global_store_short v[2:3], v15, off
	v_add_u32_e32 v2, v58, v175
	v_ashrrev_i32_e32 v3, 31, v2
	v_lshl_add_u64 v[2:3], v[2:3], 1, s[22:23]
	v_or_b32_e32 v58, 0x180, v61
	global_store_short v[2:3], v60, off
	v_add_u32_e32 v2, v58, v174
	v_ashrrev_i32_e32 v3, 31, v2
	v_lshl_add_u64 v[2:3], v[2:3], 1, s[22:23]
	global_store_short v[2:3], v15, off
	v_add_u32_e32 v2, v58, v175
	v_ashrrev_i32_e32 v3, 31, v2
	v_lshl_add_u64 v[2:3], v[2:3], 1, s[22:23]
	v_add_u32_e32 v58, 0x240, v61
	global_store_short v[2:3], v60, off
	v_or_b32_e32 v2, v58, v174
	v_ashrrev_i32_e32 v3, 31, v2
	v_lshl_add_u64 v[2:3], v[2:3], 1, s[22:23]
	global_store_short v[2:3], v15, off
	v_or_b32_e32 v2, v58, v175
	v_ashrrev_i32_e32 v3, 31, v2
	v_lshl_add_u64 v[2:3], v[2:3], 1, s[22:23]
	v_add_u32_e32 v58, 0x300, v61
	global_store_short v[2:3], v60, off
	v_or_b32_e32 v2, v58, v174
	v_ashrrev_i32_e32 v3, 31, v2
	v_lshl_add_u64 v[2:3], v[2:3], 1, s[22:23]
	global_store_short v[2:3], v15, off
	v_or_b32_e32 v2, v58, v175
	v_pk_mul_f32 v[58:59], v[40:41], v[40:41]
	v_ashrrev_i32_e32 v3, 31, v2
	v_add_f32_e32 v58, v59, v58
	ds_bpermute_b32 v59, v14, v58
	v_lshl_add_u64 v[2:3], v[2:3], 1, s[22:23]
	v_add_u32_e32 v62, 0x3c0, v61
	global_store_short v[2:3], v60, off
	v_add_u32_e32 v2, v62, v174
	s_waitcnt lgkmcnt(0)
	v_add_f32_e32 v58, v58, v59
	ds_bpermute_b32 v59, v10, v58
	v_ashrrev_i32_e32 v3, 31, v2
	v_lshl_add_u64 v[2:3], v[2:3], 1, s[22:23]
	global_store_short v[2:3], v15, off
	v_add_u32_e32 v2, v62, v175
	s_waitcnt lgkmcnt(0)
	v_add_f32_e32 v58, v58, v59
	ds_bpermute_b32 v59, v11, v58
	v_ashrrev_i32_e32 v3, 31, v2
	v_lshl_add_u64 v[2:3], v[2:3], 1, s[22:23]
	v_add_u32_e32 v62, 0x480, v61
	global_store_short v[2:3], v60, off
	s_waitcnt lgkmcnt(0)
	v_add_f32_e32 v58, v58, v59
	ds_bpermute_b32 v59, v12, v58
	v_add_u32_e32 v2, v62, v174
	v_ashrrev_i32_e32 v3, 31, v2
	v_lshl_add_u64 v[2:3], v[2:3], 1, s[22:23]
	global_store_short v[2:3], v15, off
	v_add_u32_e32 v2, v62, v175
	s_waitcnt lgkmcnt(0)
	v_add_f32_e32 v58, v58, v59
	v_ashrrev_i32_e32 v3, 31, v2
	ds_bpermute_b32 v59, v13, v58
	v_lshl_add_u64 v[2:3], v[2:3], 1, s[22:23]
	v_add_u32_e32 v61, 0x540, v61
	global_store_short v[2:3], v60, off
	v_or_b32_e32 v2, v61, v174
	v_ashrrev_i32_e32 v3, 31, v2
	v_lshl_add_u64 v[2:3], v[2:3], 1, s[22:23]
	global_store_short v[2:3], v15, off
	s_waitcnt lgkmcnt(0)
	v_add_f32_e32 v3, v58, v59
	v_fmamk_f32 v3, v3, 0x3c800000, v209
	v_rsq_f32_e32 v58, v3
	v_or_b32_e32 v2, v61, v175
	v_ashrrev_i32_e32 v3, 31, v2
	v_lshl_add_u64 v[2:3], v[2:3], 1, s[22:23]
	global_store_short v[2:3], v60, off
	v_pk_mul_f32 v[2:3], v[0:1], v[58:59] op_sel_hi:[1,0]
	s_and_b64 vcc, exec, s[4:5]
	v_pk_mul_f32 v[2:3], v[40:41], v[2:3]
	s_mov_b64 s[80:81], -1
	s_cbranch_vccnz .LBB0_314
	v_add_u32_e32 v15, s76, v186
	v_lshl_or_b32 v58, v15, 6, v156
	v_ashrrev_i32_e32 v59, 31, v58
	v_lshl_add_u64 v[58:59], v[58:59], 2, s[24:25]
	s_mov_b64 s[80:81], 0
	global_store_dword v[58:59], v3, off sc1
	global_store_dword v[58:59], v2, off offset:128 sc1

.LBB0_316:
	v_cvt_pk_bf16_f32 v60, v2, s0
	v_add_u32_e32 v2, s11, v186
	v_mul_lo_u32 v61, v2, s94
	v_or_b32_e32 v2, v61, v174
	v_cvt_pk_bf16_f32 v15, v3, s0
	v_ashrrev_i32_e32 v3, 31, v2
	v_lshl_add_u64 v[2:3], v[2:3], 1, s[22:23]
	global_store_short v[2:3], v15, off
	v_or_b32_e32 v2, v61, v175
	v_ashrrev_i32_e32 v3, 31, v2
	v_lshl_add_u64 v[2:3], v[2:3], 1, s[22:23]
	v_or_b32_e32 v58, 0xc0, v61
	global_store_short v[2:3], v60, off
	v_add_u32_e32 v2, v58, v174
	v_ashrrev_i32_e32 v3, 31, v2
	v_lshl_add_u64 v[2:3], v[2:3], 1, s[22:23]
	global_store_short v[2:3], v15, off
	v_add_u32_e32 v2, v58, v175
	v_ashrrev_i32_e32 v3, 31, v2
	v_lshl_add_u64 v[2:3], v[2:3], 1, s[22:23]
	v_or_b32_e32 v58, 0x180, v61
	global_store_short v[2:3], v60, off
	v_add_u32_e32 v2, v58, v174
	v_ashrrev_i32_e32 v3, 31, v2
	v_lshl_add_u64 v[2:3], v[2:3], 1, s[22:23]
	global_store_short v[2:3], v15, off
	v_add_u32_e32 v2, v58, v175
	v_ashrrev_i32_e32 v3, 31, v2
	v_lshl_add_u64 v[2:3], v[2:3], 1, s[22:23]
	v_add_u32_e32 v58, 0x240, v61
	global_store_short v[2:3], v60, off
	v_or_b32_e32 v2, v58, v174
	v_ashrrev_i32_e32 v3, 31, v2
	v_lshl_add_u64 v[2:3], v[2:3], 1, s[22:23]
	global_store_short v[2:3], v15, off
	v_or_b32_e32 v2, v58, v175
	v_ashrrev_i32_e32 v3, 31, v2
	v_lshl_add_u64 v[2:3], v[2:3], 1, s[22:23]
	v_add_u32_e32 v58, 0x300, v61
	global_store_short v[2:3], v60, off
	v_or_b32_e32 v2, v58, v174
	v_ashrrev_i32_e32 v3, 31, v2
	v_lshl_add_u64 v[2:3], v[2:3], 1, s[22:23]
	global_store_short v[2:3], v15, off
	v_or_b32_e32 v2, v58, v175
	v_pk_mul_f32 v[58:59], v[38:39], v[38:39]
	v_ashrrev_i32_e32 v3, 31, v2
	v_add_f32_e32 v58, v59, v58
	ds_bpermute_b32 v59, v14, v58
	v_lshl_add_u64 v[2:3], v[2:3], 1, s[22:23]
	v_add_u32_e32 v62, 0x3c0, v61
	global_store_short v[2:3], v60, off
	v_add_u32_e32 v2, v62, v174
	s_waitcnt lgkmcnt(0)
	v_add_f32_e32 v58, v58, v59
	ds_bpermute_b32 v59, v10, v58
	v_ashrrev_i32_e32 v3, 31, v2
	v_lshl_add_u64 v[2:3], v[2:3], 1, s[22:23]
	global_store_short v[2:3], v15, off
	v_add_u32_e32 v2, v62, v175
	s_waitcnt lgkmcnt(0)
	v_add_f32_e32 v58, v58, v59
	ds_bpermute_b32 v59, v11, v58
	v_ashrrev_i32_e32 v3, 31, v2
	v_lshl_add_u64 v[2:3], v[2:3], 1, s[22:23]
	v_add_u32_e32 v62, 0x480, v61
	global_store_short v[2:3], v60, off
	s_waitcnt lgkmcnt(0)
	v_add_f32_e32 v58, v58, v59
	ds_bpermute_b32 v59, v12, v58
	v_add_u32_e32 v2, v62, v174
	v_ashrrev_i32_e32 v3, 31, v2
	v_lshl_add_u64 v[2:3], v[2:3], 1, s[22:23]
	global_store_short v[2:3], v15, off
	v_add_u32_e32 v2, v62, v175
	s_waitcnt lgkmcnt(0)
	v_add_f32_e32 v58, v58, v59
	v_ashrrev_i32_e32 v3, 31, v2
	ds_bpermute_b32 v59, v13, v58
	v_lshl_add_u64 v[2:3], v[2:3], 1, s[22:23]
	v_add_u32_e32 v61, 0x540, v61
	global_store_short v[2:3], v60, off
	v_or_b32_e32 v2, v61, v174
	v_ashrrev_i32_e32 v3, 31, v2
	v_lshl_add_u64 v[2:3], v[2:3], 1, s[22:23]
	global_store_short v[2:3], v15, off
	s_waitcnt lgkmcnt(0)
	v_add_f32_e32 v3, v58, v59
	v_fmamk_f32 v3, v3, 0x3c800000, v209
	v_rsq_f32_e32 v58, v3
	v_or_b32_e32 v2, v61, v175
	v_ashrrev_i32_e32 v3, 31, v2
	v_lshl_add_u64 v[2:3], v[2:3], 1, s[22:23]
	global_store_short v[2:3], v60, off
	v_pk_mul_f32 v[2:3], v[0:1], v[58:59] op_sel_hi:[1,0]
	s_and_b64 vcc, exec, s[4:5]
	v_pk_mul_f32 v[2:3], v[38:39], v[2:3]
	s_mov_b64 s[80:81], -1
	s_cbranch_vccnz .LBB0_318
	v_add_u32_e32 v15, s76, v187
	v_lshl_or_b32 v58, v15, 6, v156
	v_ashrrev_i32_e32 v59, 31, v58
	v_lshl_add_u64 v[58:59], v[58:59], 2, s[24:25]
	s_mov_b64 s[80:81], 0
	global_store_dword v[58:59], v3, off sc1
	global_store_dword v[58:59], v2, off offset:128 sc1

.LBB0_320:
	v_cvt_pk_bf16_f32 v60, v2, s0
	v_add_u32_e32 v2, s11, v187
	v_mul_lo_u32 v61, v2, s94
	v_or_b32_e32 v2, v61, v174
	v_cvt_pk_bf16_f32 v15, v3, s0
	v_ashrrev_i32_e32 v3, 31, v2
	v_lshl_add_u64 v[2:3], v[2:3], 1, s[22:23]
	global_store_short v[2:3], v15, off
	v_or_b32_e32 v2, v61, v175
	v_ashrrev_i32_e32 v3, 31, v2
	v_lshl_add_u64 v[2:3], v[2:3], 1, s[22:23]
	v_or_b32_e32 v58, 0xc0, v61
	global_store_short v[2:3], v60, off
	v_add_u32_e32 v2, v58, v174
	v_ashrrev_i32_e32 v3, 31, v2
	v_lshl_add_u64 v[2:3], v[2:3], 1, s[22:23]
	global_store_short v[2:3], v15, off
	v_add_u32_e32 v2, v58, v175
	v_ashrrev_i32_e32 v3, 31, v2
	v_lshl_add_u64 v[2:3], v[2:3], 1, s[22:23]
	v_or_b32_e32 v58, 0x180, v61
	global_store_short v[2:3], v60, off
	v_add_u32_e32 v2, v58, v174
	v_ashrrev_i32_e32 v3, 31, v2
	v_lshl_add_u64 v[2:3], v[2:3], 1, s[22:23]
	global_store_short v[2:3], v15, off
	v_add_u32_e32 v2, v58, v175
	v_ashrrev_i32_e32 v3, 31, v2
	v_lshl_add_u64 v[2:3], v[2:3], 1, s[22:23]
	v_add_u32_e32 v58, 0x240, v61
	global_store_short v[2:3], v60, off
	v_or_b32_e32 v2, v58, v174
	v_ashrrev_i32_e32 v3, 31, v2
	v_lshl_add_u64 v[2:3], v[2:3], 1, s[22:23]
	global_store_short v[2:3], v15, off
	v_or_b32_e32 v2, v58, v175
	v_ashrrev_i32_e32 v3, 31, v2
	v_lshl_add_u64 v[2:3], v[2:3], 1, s[22:23]
	v_add_u32_e32 v58, 0x300, v61
	global_store_short v[2:3], v60, off
	v_or_b32_e32 v2, v58, v174
	v_ashrrev_i32_e32 v3, 31, v2
	v_lshl_add_u64 v[2:3], v[2:3], 1, s[22:23]
	global_store_short v[2:3], v15, off
	v_or_b32_e32 v2, v58, v175
	v_pk_mul_f32 v[58:59], v[36:37], v[36:37]
	v_ashrrev_i32_e32 v3, 31, v2
	v_add_f32_e32 v58, v59, v58
	ds_bpermute_b32 v59, v14, v58
	v_lshl_add_u64 v[2:3], v[2:3], 1, s[22:23]
	v_add_u32_e32 v62, 0x3c0, v61
	global_store_short v[2:3], v60, off
	v_add_u32_e32 v2, v62, v174
	s_waitcnt lgkmcnt(0)
	v_add_f32_e32 v58, v58, v59
	ds_bpermute_b32 v59, v10, v58
	v_ashrrev_i32_e32 v3, 31, v2
	v_lshl_add_u64 v[2:3], v[2:3], 1, s[22:23]
	global_store_short v[2:3], v15, off
	v_add_u32_e32 v2, v62, v175
	s_waitcnt lgkmcnt(0)
	v_add_f32_e32 v58, v58, v59
	ds_bpermute_b32 v59, v11, v58
	v_ashrrev_i32_e32 v3, 31, v2
	v_lshl_add_u64 v[2:3], v[2:3], 1, s[22:23]
	v_add_u32_e32 v62, 0x480, v61
	global_store_short v[2:3], v60, off
	s_waitcnt lgkmcnt(0)
	v_add_f32_e32 v58, v58, v59
	ds_bpermute_b32 v59, v12, v58
	v_add_u32_e32 v2, v62, v174
	v_ashrrev_i32_e32 v3, 31, v2
	v_lshl_add_u64 v[2:3], v[2:3], 1, s[22:23]
	global_store_short v[2:3], v15, off
	v_add_u32_e32 v2, v62, v175
	s_waitcnt lgkmcnt(0)
	v_add_f32_e32 v58, v58, v59
	v_ashrrev_i32_e32 v3, 31, v2
	ds_bpermute_b32 v59, v13, v58
	v_lshl_add_u64 v[2:3], v[2:3], 1, s[22:23]
	v_add_u32_e32 v61, 0x540, v61
	global_store_short v[2:3], v60, off
	v_or_b32_e32 v2, v61, v174
	v_ashrrev_i32_e32 v3, 31, v2
	v_lshl_add_u64 v[2:3], v[2:3], 1, s[22:23]
	global_store_short v[2:3], v15, off
	s_waitcnt lgkmcnt(0)
	v_add_f32_e32 v3, v58, v59
	v_fmamk_f32 v3, v3, 0x3c800000, v209
	v_rsq_f32_e32 v58, v3
	v_or_b32_e32 v2, v61, v175
	v_ashrrev_i32_e32 v3, 31, v2
	v_lshl_add_u64 v[2:3], v[2:3], 1, s[22:23]
	global_store_short v[2:3], v60, off
	v_pk_mul_f32 v[2:3], v[0:1], v[58:59] op_sel_hi:[1,0]
	s_and_b64 vcc, exec, s[4:5]
	v_pk_mul_f32 v[2:3], v[36:37], v[2:3]
	s_mov_b64 s[80:81], -1
	s_cbranch_vccnz .LBB0_322
	v_add_u32_e32 v15, s76, v188
	v_lshl_or_b32 v58, v15, 6, v156
	v_ashrrev_i32_e32 v59, 31, v58
	v_lshl_add_u64 v[58:59], v[58:59], 2, s[24:25]
	s_mov_b64 s[80:81], 0
	global_store_dword v[58:59], v3, off sc1
	global_store_dword v[58:59], v2, off offset:128 sc1

.LBB0_324:
	v_cvt_pk_bf16_f32 v60, v2, s0
	v_add_u32_e32 v2, s11, v188
	v_mul_lo_u32 v61, v2, s94
	v_or_b32_e32 v2, v61, v174
	v_cvt_pk_bf16_f32 v15, v3, s0
	v_ashrrev_i32_e32 v3, 31, v2
	v_lshl_add_u64 v[2:3], v[2:3], 1, s[22:23]
	global_store_short v[2:3], v15, off
	v_or_b32_e32 v2, v61, v175
	v_ashrrev_i32_e32 v3, 31, v2
	v_lshl_add_u64 v[2:3], v[2:3], 1, s[22:23]
	v_or_b32_e32 v58, 0xc0, v61
	global_store_short v[2:3], v60, off
	v_add_u32_e32 v2, v58, v174
	v_ashrrev_i32_e32 v3, 31, v2
	v_lshl_add_u64 v[2:3], v[2:3], 1, s[22:23]
	global_store_short v[2:3], v15, off
	v_add_u32_e32 v2, v58, v175
	v_ashrrev_i32_e32 v3, 31, v2
	v_lshl_add_u64 v[2:3], v[2:3], 1, s[22:23]
	v_or_b32_e32 v58, 0x180, v61
	global_store_short v[2:3], v60, off
	v_add_u32_e32 v2, v58, v174
	v_ashrrev_i32_e32 v3, 31, v2
	v_lshl_add_u64 v[2:3], v[2:3], 1, s[22:23]
	global_store_short v[2:3], v15, off
	v_add_u32_e32 v2, v58, v175
	v_ashrrev_i32_e32 v3, 31, v2
	v_lshl_add_u64 v[2:3], v[2:3], 1, s[22:23]
	v_add_u32_e32 v58, 0x240, v61
	global_store_short v[2:3], v60, off
	v_or_b32_e32 v2, v58, v174
	v_ashrrev_i32_e32 v3, 31, v2
	v_lshl_add_u64 v[2:3], v[2:3], 1, s[22:23]
	global_store_short v[2:3], v15, off
	v_or_b32_e32 v2, v58, v175
	v_ashrrev_i32_e32 v3, 31, v2
	v_lshl_add_u64 v[2:3], v[2:3], 1, s[22:23]
	v_add_u32_e32 v58, 0x300, v61
	global_store_short v[2:3], v60, off
	v_or_b32_e32 v2, v58, v174
	v_ashrrev_i32_e32 v3, 31, v2
	v_lshl_add_u64 v[2:3], v[2:3], 1, s[22:23]
	global_store_short v[2:3], v15, off
	v_or_b32_e32 v2, v58, v175
	v_pk_mul_f32 v[58:59], v[34:35], v[34:35]
	v_ashrrev_i32_e32 v3, 31, v2
	v_add_f32_e32 v58, v59, v58
	ds_bpermute_b32 v59, v14, v58
	v_lshl_add_u64 v[2:3], v[2:3], 1, s[22:23]
	v_add_u32_e32 v62, 0x3c0, v61
	global_store_short v[2:3], v60, off
	v_add_u32_e32 v2, v62, v174
	s_waitcnt lgkmcnt(0)
	v_add_f32_e32 v58, v58, v59
	ds_bpermute_b32 v59, v10, v58
	v_ashrrev_i32_e32 v3, 31, v2
	v_lshl_add_u64 v[2:3], v[2:3], 1, s[22:23]
	global_store_short v[2:3], v15, off
	v_add_u32_e32 v2, v62, v175
	s_waitcnt lgkmcnt(0)
	v_add_f32_e32 v58, v58, v59
	ds_bpermute_b32 v59, v11, v58
	v_ashrrev_i32_e32 v3, 31, v2
	v_lshl_add_u64 v[2:3], v[2:3], 1, s[22:23]
	v_add_u32_e32 v62, 0x480, v61
	global_store_short v[2:3], v60, off
	s_waitcnt lgkmcnt(0)
	v_add_f32_e32 v58, v58, v59
	ds_bpermute_b32 v59, v12, v58
	v_add_u32_e32 v2, v62, v174
	v_ashrrev_i32_e32 v3, 31, v2
	v_lshl_add_u64 v[2:3], v[2:3], 1, s[22:23]
	global_store_short v[2:3], v15, off
	v_add_u32_e32 v2, v62, v175
	s_waitcnt lgkmcnt(0)
	v_add_f32_e32 v58, v58, v59
	v_ashrrev_i32_e32 v3, 31, v2
	ds_bpermute_b32 v59, v13, v58
	v_lshl_add_u64 v[2:3], v[2:3], 1, s[22:23]
	v_add_u32_e32 v61, 0x540, v61
	global_store_short v[2:3], v60, off
	v_or_b32_e32 v2, v61, v174
	v_ashrrev_i32_e32 v3, 31, v2
	v_lshl_add_u64 v[2:3], v[2:3], 1, s[22:23]
	global_store_short v[2:3], v15, off
	s_waitcnt lgkmcnt(0)
	v_add_f32_e32 v3, v58, v59
	v_fmamk_f32 v3, v3, 0x3c800000, v209
	v_rsq_f32_e32 v58, v3
	v_or_b32_e32 v2, v61, v175
	v_ashrrev_i32_e32 v3, 31, v2
	v_lshl_add_u64 v[2:3], v[2:3], 1, s[22:23]
	global_store_short v[2:3], v60, off
	v_pk_mul_f32 v[2:3], v[0:1], v[58:59] op_sel_hi:[1,0]
	s_and_b64 vcc, exec, s[4:5]
	v_pk_mul_f32 v[2:3], v[34:35], v[2:3]
	s_mov_b64 s[80:81], -1
	s_cbranch_vccnz .LBB0_326
	v_add_u32_e32 v15, s76, v189
	v_lshl_or_b32 v58, v15, 6, v156
	v_ashrrev_i32_e32 v59, 31, v58
	v_lshl_add_u64 v[58:59], v[58:59], 2, s[24:25]
	s_mov_b64 s[80:81], 0
	global_store_dword v[58:59], v3, off sc1
	global_store_dword v[58:59], v2, off offset:128 sc1

.LBB0_328:
	v_cvt_pk_bf16_f32 v60, v2, s0
	v_add_u32_e32 v2, s11, v189
	v_mul_lo_u32 v61, v2, s94
	v_or_b32_e32 v2, v61, v174
	v_cvt_pk_bf16_f32 v15, v3, s0
	v_ashrrev_i32_e32 v3, 31, v2
	v_lshl_add_u64 v[2:3], v[2:3], 1, s[22:23]
	global_store_short v[2:3], v15, off
	v_or_b32_e32 v2, v61, v175
	v_ashrrev_i32_e32 v3, 31, v2
	v_lshl_add_u64 v[2:3], v[2:3], 1, s[22:23]
	v_or_b32_e32 v58, 0xc0, v61
	global_store_short v[2:3], v60, off
	v_add_u32_e32 v2, v58, v174
	v_ashrrev_i32_e32 v3, 31, v2
	v_lshl_add_u64 v[2:3], v[2:3], 1, s[22:23]
	global_store_short v[2:3], v15, off
	v_add_u32_e32 v2, v58, v175
	v_ashrrev_i32_e32 v3, 31, v2
	v_lshl_add_u64 v[2:3], v[2:3], 1, s[22:23]
	v_or_b32_e32 v58, 0x180, v61
	global_store_short v[2:3], v60, off
	v_add_u32_e32 v2, v58, v174
	v_ashrrev_i32_e32 v3, 31, v2
	v_lshl_add_u64 v[2:3], v[2:3], 1, s[22:23]
	global_store_short v[2:3], v15, off
	v_add_u32_e32 v2, v58, v175
	v_ashrrev_i32_e32 v3, 31, v2
	v_lshl_add_u64 v[2:3], v[2:3], 1, s[22:23]
	v_add_u32_e32 v58, 0x240, v61
	global_store_short v[2:3], v60, off
	v_or_b32_e32 v2, v58, v174
	v_ashrrev_i32_e32 v3, 31, v2
	v_lshl_add_u64 v[2:3], v[2:3], 1, s[22:23]
	global_store_short v[2:3], v15, off
	v_or_b32_e32 v2, v58, v175
	v_ashrrev_i32_e32 v3, 31, v2
	v_lshl_add_u64 v[2:3], v[2:3], 1, s[22:23]
	v_add_u32_e32 v58, 0x300, v61
	global_store_short v[2:3], v60, off
	v_or_b32_e32 v2, v58, v174
	v_ashrrev_i32_e32 v3, 31, v2
	v_lshl_add_u64 v[2:3], v[2:3], 1, s[22:23]
	global_store_short v[2:3], v15, off
	v_or_b32_e32 v2, v58, v175
	v_pk_mul_f32 v[58:59], v[32:33], v[32:33]
	v_ashrrev_i32_e32 v3, 31, v2
	v_add_f32_e32 v58, v59, v58
	ds_bpermute_b32 v14, v14, v58
	v_lshl_add_u64 v[2:3], v[2:3], 1, s[22:23]
	v_add_u32_e32 v62, 0x3c0, v61
	global_store_short v[2:3], v60, off
	v_add_u32_e32 v2, v62, v174
	s_waitcnt lgkmcnt(0)
	v_add_f32_e32 v14, v58, v14
	ds_bpermute_b32 v10, v10, v14
	v_ashrrev_i32_e32 v3, 31, v2
	v_lshl_add_u64 v[2:3], v[2:3], 1, s[22:23]
	global_store_short v[2:3], v15, off
	v_add_u32_e32 v2, v62, v175
	s_waitcnt lgkmcnt(0)
	v_add_f32_e32 v10, v14, v10
	ds_bpermute_b32 v11, v11, v10
	v_ashrrev_i32_e32 v3, 31, v2
	v_lshl_add_u64 v[2:3], v[2:3], 1, s[22:23]
	v_add_u32_e32 v58, 0x480, v61
	global_store_short v[2:3], v60, off
	s_waitcnt lgkmcnt(0)
	v_add_f32_e32 v10, v10, v11
	ds_bpermute_b32 v11, v12, v10
	v_add_u32_e32 v2, v58, v174
	v_ashrrev_i32_e32 v3, 31, v2
	v_lshl_add_u64 v[2:3], v[2:3], 1, s[22:23]
	global_store_short v[2:3], v15, off
	v_add_u32_e32 v2, v58, v175
	s_waitcnt lgkmcnt(0)
	v_add_f32_e32 v10, v10, v11
	v_ashrrev_i32_e32 v3, 31, v2
	ds_bpermute_b32 v11, v13, v10
	v_lshl_add_u64 v[2:3], v[2:3], 1, s[22:23]
	v_add_u32_e32 v12, 0x540, v61
	global_store_short v[2:3], v60, off
	v_or_b32_e32 v2, v12, v174
	v_ashrrev_i32_e32 v3, 31, v2
	v_lshl_add_u64 v[2:3], v[2:3], 1, s[22:23]
	global_store_short v[2:3], v15, off
	s_waitcnt lgkmcnt(0)
	v_add_f32_e32 v3, v10, v11
	v_fmamk_f32 v3, v3, 0x3c800000, v209
	v_rsq_f32_e32 v10, v3
	v_or_b32_e32 v2, v12, v175
	v_ashrrev_i32_e32 v3, 31, v2
	v_lshl_add_u64 v[2:3], v[2:3], 1, s[22:23]
	v_pk_mul_f32 v[0:1], v[0:1], v[10:11] op_sel_hi:[1,0]
	s_and_b64 vcc, exec, s[4:5]
	v_pk_mul_f32 v[0:1], v[32:33], v[0:1]
	s_mov_b64 s[80:81], -1
	global_store_short v[2:3], v60, off
	s_cbranch_vccnz .LBB0_330
	v_add_u32_e32 v2, s76, v190
	v_lshl_or_b32 v2, v2, 6, v156
	v_ashrrev_i32_e32 v3, 31, v2
	v_lshl_add_u64 v[2:3], v[2:3], 2, s[24:25]
	s_mov_b64 s[80:81], 0
	global_store_dword v[2:3], v1, off sc1
	global_store_dword v[2:3], v0, off offset:128 sc1

.LBB0_333:
	s_and_b64 vcc, exec, s[80:81]
	s_cbranch_vccz .LBB0_495
	v_mov_b32_e32 v0, s96
	ds_read_b64 v[0:1], v0
	v_lshl_add_u64 v[2:3], s[78:79], 0, v[156:157]
	v_add_lshl_u32 v10, s11, v173, 8
	s_and_b64 vcc, exec, s[4:5]
	s_waitcnt lgkmcnt(0)
	v_readfirstlane_b32 s8, v0
	v_readfirstlane_b32 s77, v1
	s_nop 0
	v_mov_b32_e32 v0, s8
	v_mov_b32_e32 v1, s77
	v_lshl_add_u64 v[0:1], v[2:3], 2, v[0:1]
	global_load_dword v96, v[0:1], off offset:-1536
	v_add_u32_e32 v3, s78, v166
	v_add_u32_e32 v12, v10, v3
	v_ashrrev_i32_e32 v13, 31, v12
	v_lshl_add_u64 v[12:13], v[12:13], 1, s[26:27]
	s_waitcnt vmcnt(0)
	v_mul_f32_e32 v2, v79, v96
	v_cvt_pk_bf16_f32 v11, v2, s0
	global_store_short v[12:13], v11, off
	s_cbranch_vccnz .LBB0_336
	v_lshl_add_u32 v12, v164, 8, v3
	v_ashrrev_i32_e32 v13, 31, v12
	v_lshl_add_u64 v[12:13], v[12:13], 2, s[28:29]
	global_store_dword v[12:13], v2, off sc1
.LBB0_336:
	v_add_lshl_u32 v13, s11, v176, 8
	v_add_u32_e32 v14, v13, v3
	v_mul_f32_e32 v11, v75, v96
	v_ashrrev_i32_e32 v15, 31, v14
	v_cvt_pk_bf16_f32 v2, v11, s0
	v_lshl_add_u64 v[14:15], v[14:15], 1, s[26:27]
	global_store_short v[14:15], v2, off
	s_and_b64 vcc, exec, s[4:5]
	v_add_u32_e32 v2, s76, v176
	s_cbranch_vccnz .LBB0_338
	v_lshl_add_u32 v14, v2, 8, v3
	v_ashrrev_i32_e32 v15, 31, v14
	v_lshl_add_u64 v[14:15], v[14:15], 2, s[28:29]
	global_store_dword v[14:15], v11, off sc1
.LBB0_338:
	v_add_lshl_u32 v15, s11, v177, 8
	v_add_u32_e32 v58, v15, v3
	v_mul_f32_e32 v12, v73, v96
	v_ashrrev_i32_e32 v59, 31, v58
	v_cvt_pk_bf16_f32 v11, v12, s0
	v_lshl_add_u64 v[58:59], v[58:59], 1, s[26:27]
	global_store_short v[58:59], v11, off
	s_and_b64 vcc, exec, s[4:5]
	v_add_u32_e32 v11, s76, v177
	s_cbranch_vccnz .LBB0_340
	v_lshl_add_u32 v58, v11, 8, v3
	v_ashrrev_i32_e32 v59, 31, v58
	v_lshl_add_u64 v[58:59], v[58:59], 2, s[28:29]
	global_store_dword v[58:59], v12, off sc1
.LBB0_340:
	v_add_lshl_u32 v59, s11, v178, 8
	v_add_u32_e32 v60, v59, v3
	v_mul_f32_e32 v14, v71, v96
	v_ashrrev_i32_e32 v61, 31, v60
	v_cvt_pk_bf16_f32 v12, v14, s0
	v_lshl_add_u64 v[60:61], v[60:61], 1, s[26:27]
	global_store_short v[60:61], v12, off
	s_and_b64 vcc, exec, s[4:5]
	v_add_u32_e32 v12, s76, v178
	s_cbranch_vccnz .LBB0_342
	v_lshl_add_u32 v60, v12, 8, v3
	v_ashrrev_i32_e32 v61, 31, v60
	v_lshl_add_u64 v[60:61], v[60:61], 2, s[28:29]
	global_store_dword v[60:61], v14, off sc1
.LBB0_342:
	v_add_lshl_u32 v61, s11, v179, 8
	v_add_u32_e32 v62, v61, v3
	v_mul_f32_e32 v58, v69, v96
	v_ashrrev_i32_e32 v63, 31, v62
	v_cvt_pk_bf16_f32 v14, v58, s0
	v_lshl_add_u64 v[62:63], v[62:63], 1, s[26:27]
	global_store_short v[62:63], v14, off
	s_and_b64 vcc, exec, s[4:5]
	v_add_u32_e32 v14, s76, v179
	s_cbranch_vccnz .LBB0_344
	v_lshl_add_u32 v62, v14, 8, v3
	v_ashrrev_i32_e32 v63, 31, v62
	v_lshl_add_u64 v[62:63], v[62:63], 2, s[28:29]
	global_store_dword v[62:63], v58, off sc1
.LBB0_344:
	v_add_lshl_u32 v63, s11, v180, 8
	v_add_u32_e32 v80, v63, v3
	v_mul_f32_e32 v60, v67, v96
	v_ashrrev_i32_e32 v81, 31, v80
	v_cvt_pk_bf16_f32 v58, v60, s0
	v_lshl_add_u64 v[80:81], v[80:81], 1, s[26:27]
	global_store_short v[80:81], v58, off
	s_and_b64 vcc, exec, s[4:5]
	v_add_u32_e32 v58, s76, v180
	s_cbranch_vccnz .LBB0_346
	v_lshl_add_u32 v80, v58, 8, v3
	v_ashrrev_i32_e32 v81, 31, v80
	v_lshl_add_u64 v[80:81], v[80:81], 2, s[28:29]
	global_store_dword v[80:81], v60, off sc1
.LBB0_346:
	v_add_lshl_u32 v81, s11, v181, 8
	v_add_u32_e32 v84, v81, v3
	v_mul_f32_e32 v62, v65, v96
	v_ashrrev_i32_e32 v85, 31, v84
	v_cvt_pk_bf16_f32 v60, v62, s0
	v_lshl_add_u64 v[84:85], v[84:85], 1, s[26:27]
	global_store_short v[84:85], v60, off
	s_and_b64 vcc, exec, s[4:5]
	v_add_u32_e32 v60, s76, v181
	s_cbranch_vccnz .LBB0_348
	v_lshl_add_u32 v84, v60, 8, v3
	v_ashrrev_i32_e32 v85, 31, v84
	v_lshl_add_u64 v[84:85], v[84:85], 2, s[28:29]
	global_store_dword v[84:85], v62, off sc1
.LBB0_348:
	v_add_lshl_u32 v85, s11, v182, 8
	v_add_u32_e32 v86, v85, v3
	v_mul_f32_e32 v80, v55, v96
	v_ashrrev_i32_e32 v87, 31, v86
	v_cvt_pk_bf16_f32 v62, v80, s0
	v_lshl_add_u64 v[86:87], v[86:87], 1, s[26:27]
	global_store_short v[86:87], v62, off
	s_and_b64 vcc, exec, s[4:5]
	v_add_u32_e32 v62, s76, v182
	s_cbranch_vccnz .LBB0_350
	v_lshl_add_u32 v86, v62, 8, v3
	v_ashrrev_i32_e32 v87, 31, v86
	v_lshl_add_u64 v[86:87], v[86:87], 2, s[28:29]
	global_store_dword v[86:87], v80, off sc1
.LBB0_350:
	v_add_lshl_u32 v87, s11, v183, 8
	v_add_u32_e32 v88, v87, v3
	v_mul_f32_e32 v84, v53, v96
	v_ashrrev_i32_e32 v89, 31, v88
	v_cvt_pk_bf16_f32 v80, v84, s0
	v_lshl_add_u64 v[88:89], v[88:89], 1, s[26:27]
	global_store_short v[88:89], v80, off
	s_and_b64 vcc, exec, s[4:5]
	v_add_u32_e32 v80, s76, v183
	s_cbranch_vccnz .LBB0_352
	v_lshl_add_u32 v88, v80, 8, v3
	v_ashrrev_i32_e32 v89, 31, v88
	v_lshl_add_u64 v[88:89], v[88:89], 2, s[28:29]
	global_store_dword v[88:89], v84, off sc1
.LBB0_352:
	v_add_lshl_u32 v89, s11, v184, 8
	v_add_u32_e32 v90, v89, v3
	v_mul_f32_e32 v86, v51, v96
	v_ashrrev_i32_e32 v91, 31, v90
	v_cvt_pk_bf16_f32 v84, v86, s0
	v_lshl_add_u64 v[90:91], v[90:91], 1, s[26:27]
	global_store_short v[90:91], v84, off
	s_and_b64 vcc, exec, s[4:5]
	v_add_u32_e32 v84, s76, v184
	s_cbranch_vccnz .LBB0_354
	v_lshl_add_u32 v90, v84, 8, v3
	v_ashrrev_i32_e32 v91, 31, v90
	v_lshl_add_u64 v[90:91], v[90:91], 2, s[28:29]
	global_store_dword v[90:91], v86, off sc1
.LBB0_354:
	v_add_lshl_u32 v91, s11, v185, 8
	v_add_u32_e32 v92, v91, v3
	v_mul_f32_e32 v88, v49, v96
	v_ashrrev_i32_e32 v93, 31, v92
	v_cvt_pk_bf16_f32 v86, v88, s0
	v_lshl_add_u64 v[92:93], v[92:93], 1, s[26:27]
	global_store_short v[92:93], v86, off
	s_and_b64 vcc, exec, s[4:5]
	v_add_u32_e32 v86, s76, v185
	s_cbranch_vccnz .LBB0_356
	v_lshl_add_u32 v92, v86, 8, v3
	v_ashrrev_i32_e32 v93, 31, v92
	v_lshl_add_u64 v[92:93], v[92:93], 2, s[28:29]
	global_store_dword v[92:93], v88, off sc1
.LBB0_356:
	v_add_lshl_u32 v93, s11, v186, 8
	v_add_u32_e32 v94, v93, v3
	v_mul_f32_e32 v90, v41, v96
	v_ashrrev_i32_e32 v95, 31, v94
	v_cvt_pk_bf16_f32 v88, v90, s0
	v_lshl_add_u64 v[94:95], v[94:95], 1, s[26:27]
	global_store_short v[94:95], v88, off
	s_and_b64 vcc, exec, s[4:5]
	v_add_u32_e32 v88, s76, v186
	s_cbranch_vccnz .LBB0_358
	v_lshl_add_u32 v94, v88, 8, v3
	v_ashrrev_i32_e32 v95, 31, v94
	v_lshl_add_u64 v[94:95], v[94:95], 2, s[28:29]
	global_store_dword v[94:95], v90, off sc1
.LBB0_358:
	v_add_lshl_u32 v95, s11, v187, 8
	v_add_u32_e32 v98, v95, v3
	v_mul_f32_e32 v92, v39, v96
	v_ashrrev_i32_e32 v99, 31, v98
	v_cvt_pk_bf16_f32 v90, v92, s0
	v_lshl_add_u64 v[98:99], v[98:99], 1, s[26:27]
	global_store_short v[98:99], v90, off
	s_and_b64 vcc, exec, s[4:5]
	v_add_u32_e32 v90, s76, v187
	s_cbranch_vccnz .LBB0_360
	v_lshl_add_u32 v98, v90, 8, v3
	v_ashrrev_i32_e32 v99, 31, v98
	v_lshl_add_u64 v[98:99], v[98:99], 2, s[28:29]
	global_store_dword v[98:99], v92, off sc1
.LBB0_360:
	v_add_lshl_u32 v97, s11, v188, 8
	v_add_u32_e32 v98, v97, v3
	v_mul_f32_e32 v94, v37, v96
	v_ashrrev_i32_e32 v99, 31, v98
	v_cvt_pk_bf16_f32 v92, v94, s0
	v_lshl_add_u64 v[98:99], v[98:99], 1, s[26:27]
	global_store_short v[98:99], v92, off
	s_and_b64 vcc, exec, s[4:5]
	v_add_u32_e32 v92, s76, v188
	s_cbranch_vccnz .LBB0_362
	v_lshl_add_u32 v98, v92, 8, v3
	v_ashrrev_i32_e32 v99, 31, v98
	v_lshl_add_u64 v[98:99], v[98:99], 2, s[28:29]
	global_store_dword v[98:99], v94, off sc1
.LBB0_362:
	v_add_lshl_u32 v98, s11, v189, 8
	v_add_u32_e32 v100, v98, v3
	v_mul_f32_e32 v99, v35, v96
	v_ashrrev_i32_e32 v101, 31, v100
	v_cvt_pk_bf16_f32 v94, v99, s0
	v_lshl_add_u64 v[100:101], v[100:101], 1, s[26:27]
	global_store_short v[100:101], v94, off
	s_and_b64 vcc, exec, s[4:5]
	v_add_u32_e32 v94, s76, v189
	s_cbranch_vccnz .LBB0_364
	v_lshl_add_u32 v100, v94, 8, v3
	v_ashrrev_i32_e32 v101, 31, v100
	v_lshl_add_u64 v[100:101], v[100:101], 2, s[28:29]
	global_store_dword v[100:101], v99, off sc1
.LBB0_364:
	v_add_lshl_u32 v99, s11, v190, 8
	v_add_u32_e32 v102, v99, v3
	v_mul_f32_e32 v100, v33, v96
	v_ashrrev_i32_e32 v103, 31, v102
	v_cvt_pk_bf16_f32 v96, v100, s0
	v_lshl_add_u64 v[102:103], v[102:103], 1, s[26:27]
	global_store_short v[102:103], v96, off
	s_and_b64 vcc, exec, s[4:5]
	v_add_u32_e32 v96, s76, v190
	s_cbranch_vccnz .LBB0_366
	v_lshl_add_u32 v102, v96, 8, v3
	v_ashrrev_i32_e32 v103, 31, v102
	v_lshl_add_u64 v[102:103], v[102:103], 2, s[28:29]
	global_store_dword v[102:103], v100, off sc1
.LBB0_366:
	global_load_dword v101, v[0:1], off offset:-1408
	v_or_b32_e32 v100, 32, v3
	v_add_u32_e32 v102, v10, v100
	v_ashrrev_i32_e32 v103, 31, v102
	v_lshl_add_u64 v[104:105], v[102:103], 1, s[26:27]
	s_and_b64 vcc, exec, s[4:5]
	s_waitcnt vmcnt(0)
	v_mul_f32_e32 v102, v78, v101
	v_cvt_pk_bf16_f32 v103, v102, s0
	global_store_short v[104:105], v103, off
	s_cbranch_vccnz .LBB0_368
	v_lshl_add_u32 v104, v164, 8, v100
	v_ashrrev_i32_e32 v105, 31, v104
	v_lshl_add_u64 v[104:105], v[104:105], 2, s[28:29]
	global_store_dword v[104:105], v102, off sc1
.LBB0_368:
	v_add_u32_e32 v104, v13, v100
	v_mul_f32_e32 v102, v74, v101
	v_ashrrev_i32_e32 v105, 31, v104
	v_cvt_pk_bf16_f32 v103, v102, s0
	v_lshl_add_u64 v[104:105], v[104:105], 1, s[26:27]
	s_and_b64 vcc, exec, s[4:5]
	global_store_short v[104:105], v103, off
	s_cbranch_vccnz .LBB0_370
	v_lshl_add_u32 v104, v2, 8, v100
	v_ashrrev_i32_e32 v105, 31, v104
	v_lshl_add_u64 v[104:105], v[104:105], 2, s[28:29]
	global_store_dword v[104:105], v102, off sc1
.LBB0_370:
	v_add_u32_e32 v104, v15, v100
	v_mul_f32_e32 v102, v72, v101
	v_ashrrev_i32_e32 v105, 31, v104
	v_cvt_pk_bf16_f32 v103, v102, s0
	v_lshl_add_u64 v[104:105], v[104:105], 1, s[26:27]
	s_and_b64 vcc, exec, s[4:5]
	global_store_short v[104:105], v103, off
	s_cbranch_vccnz .LBB0_372
	v_lshl_add_u32 v104, v11, 8, v100
	v_ashrrev_i32_e32 v105, 31, v104
	v_lshl_add_u64 v[104:105], v[104:105], 2, s[28:29]
	global_store_dword v[104:105], v102, off sc1
.LBB0_372:
	v_add_u32_e32 v104, v59, v100
	v_mul_f32_e32 v102, v70, v101
	v_ashrrev_i32_e32 v105, 31, v104
	v_cvt_pk_bf16_f32 v103, v102, s0
	v_lshl_add_u64 v[104:105], v[104:105], 1, s[26:27]
	s_and_b64 vcc, exec, s[4:5]
	global_store_short v[104:105], v103, off
	s_cbranch_vccnz .LBB0_374
	v_lshl_add_u32 v104, v12, 8, v100
	v_ashrrev_i32_e32 v105, 31, v104
	v_lshl_add_u64 v[104:105], v[104:105], 2, s[28:29]
	global_store_dword v[104:105], v102, off sc1
.LBB0_374:
	v_add_u32_e32 v104, v61, v100
	v_mul_f32_e32 v102, v68, v101
	v_ashrrev_i32_e32 v105, 31, v104
	v_cvt_pk_bf16_f32 v103, v102, s0
	v_lshl_add_u64 v[104:105], v[104:105], 1, s[26:27]
	s_and_b64 vcc, exec, s[4:5]
	global_store_short v[104:105], v103, off
	s_cbranch_vccnz .LBB0_376
	v_lshl_add_u32 v104, v14, 8, v100
	v_ashrrev_i32_e32 v105, 31, v104
	v_lshl_add_u64 v[104:105], v[104:105], 2, s[28:29]
	global_store_dword v[104:105], v102, off sc1
.LBB0_376:
	v_add_u32_e32 v104, v63, v100
	v_mul_f32_e32 v102, v66, v101
	v_ashrrev_i32_e32 v105, 31, v104
	v_cvt_pk_bf16_f32 v103, v102, s0
	v_lshl_add_u64 v[104:105], v[104:105], 1, s[26:27]
	s_and_b64 vcc, exec, s[4:5]
	global_store_short v[104:105], v103, off
	s_cbranch_vccnz .LBB0_378
	v_lshl_add_u32 v104, v58, 8, v100
	v_ashrrev_i32_e32 v105, 31, v104
	v_lshl_add_u64 v[104:105], v[104:105], 2, s[28:29]
	global_store_dword v[104:105], v102, off sc1
.LBB0_378:
	v_add_u32_e32 v104, v81, v100
	v_mul_f32_e32 v102, v64, v101
	v_ashrrev_i32_e32 v105, 31, v104
	v_cvt_pk_bf16_f32 v103, v102, s0
	v_lshl_add_u64 v[104:105], v[104:105], 1, s[26:27]
	s_and_b64 vcc, exec, s[4:5]
	global_store_short v[104:105], v103, off
	s_cbranch_vccnz .LBB0_380
	v_lshl_add_u32 v104, v60, 8, v100
	v_ashrrev_i32_e32 v105, 31, v104
	v_lshl_add_u64 v[104:105], v[104:105], 2, s[28:29]
	global_store_dword v[104:105], v102, off sc1
.LBB0_380:
	v_add_u32_e32 v104, v85, v100
	v_mul_f32_e32 v102, v54, v101
	v_ashrrev_i32_e32 v105, 31, v104
	v_cvt_pk_bf16_f32 v103, v102, s0
	v_lshl_add_u64 v[104:105], v[104:105], 1, s[26:27]
	s_and_b64 vcc, exec, s[4:5]
	global_store_short v[104:105], v103, off
	s_cbranch_vccnz .LBB0_382
	v_lshl_add_u32 v104, v62, 8, v100
	v_ashrrev_i32_e32 v105, 31, v104
	v_lshl_add_u64 v[104:105], v[104:105], 2, s[28:29]
	global_store_dword v[104:105], v102, off sc1
.LBB0_382:
	v_add_u32_e32 v104, v87, v100
	v_mul_f32_e32 v102, v52, v101
	v_ashrrev_i32_e32 v105, 31, v104
	v_cvt_pk_bf16_f32 v103, v102, s0
	v_lshl_add_u64 v[104:105], v[104:105], 1, s[26:27]
	s_and_b64 vcc, exec, s[4:5]
	global_store_short v[104:105], v103, off
	s_cbranch_vccnz .LBB0_384
	v_lshl_add_u32 v104, v80, 8, v100
	v_ashrrev_i32_e32 v105, 31, v104
	v_lshl_add_u64 v[104:105], v[104:105], 2, s[28:29]
	global_store_dword v[104:105], v102, off sc1
.LBB0_384:
	v_add_u32_e32 v104, v89, v100
	v_mul_f32_e32 v102, v50, v101
	v_ashrrev_i32_e32 v105, 31, v104
	v_cvt_pk_bf16_f32 v103, v102, s0
	v_lshl_add_u64 v[104:105], v[104:105], 1, s[26:27]
	s_and_b64 vcc, exec, s[4:5]
	global_store_short v[104:105], v103, off
	s_cbranch_vccnz .LBB0_386
	v_lshl_add_u32 v104, v84, 8, v100
	v_ashrrev_i32_e32 v105, 31, v104
	v_lshl_add_u64 v[104:105], v[104:105], 2, s[28:29]
	global_store_dword v[104:105], v102, off sc1
.LBB0_386:
	v_add_u32_e32 v104, v91, v100
	v_mul_f32_e32 v102, v48, v101
	v_ashrrev_i32_e32 v105, 31, v104
	v_cvt_pk_bf16_f32 v103, v102, s0
	v_lshl_add_u64 v[104:105], v[104:105], 1, s[26:27]
	s_and_b64 vcc, exec, s[4:5]
	global_store_short v[104:105], v103, off
	s_cbranch_vccnz .LBB0_388
	v_lshl_add_u32 v104, v86, 8, v100
	v_ashrrev_i32_e32 v105, 31, v104
	v_lshl_add_u64 v[104:105], v[104:105], 2, s[28:29]
	global_store_dword v[104:105], v102, off sc1
.LBB0_388:
	v_add_u32_e32 v104, v93, v100
	v_mul_f32_e32 v102, v40, v101
	v_ashrrev_i32_e32 v105, 31, v104
	v_cvt_pk_bf16_f32 v103, v102, s0
	v_lshl_add_u64 v[104:105], v[104:105], 1, s[26:27]
	s_and_b64 vcc, exec, s[4:5]
	global_store_short v[104:105], v103, off
	s_cbranch_vccnz .LBB0_390
	v_lshl_add_u32 v104, v88, 8, v100
	v_ashrrev_i32_e32 v105, 31, v104
	v_lshl_add_u64 v[104:105], v[104:105], 2, s[28:29]
	global_store_dword v[104:105], v102, off sc1
.LBB0_390:
	v_add_u32_e32 v104, v95, v100
	v_mul_f32_e32 v102, v38, v101
	v_ashrrev_i32_e32 v105, 31, v104
	v_cvt_pk_bf16_f32 v103, v102, s0
	v_lshl_add_u64 v[104:105], v[104:105], 1, s[26:27]
	s_and_b64 vcc, exec, s[4:5]
	global_store_short v[104:105], v103, off
	s_cbranch_vccnz .LBB0_392
	v_lshl_add_u32 v104, v90, 8, v100
	v_ashrrev_i32_e32 v105, 31, v104
	v_lshl_add_u64 v[104:105], v[104:105], 2, s[28:29]
	global_store_dword v[104:105], v102, off sc1
.LBB0_392:
	v_add_u32_e32 v104, v97, v100
	v_mul_f32_e32 v102, v36, v101
	v_ashrrev_i32_e32 v105, 31, v104
	v_cvt_pk_bf16_f32 v103, v102, s0
	v_lshl_add_u64 v[104:105], v[104:105], 1, s[26:27]
	s_and_b64 vcc, exec, s[4:5]
	global_store_short v[104:105], v103, off
	s_cbranch_vccnz .LBB0_394
	v_lshl_add_u32 v104, v92, 8, v100
	v_ashrrev_i32_e32 v105, 31, v104
	v_lshl_add_u64 v[104:105], v[104:105], 2, s[28:29]
	global_store_dword v[104:105], v102, off sc1
.LBB0_394:
	v_add_u32_e32 v104, v98, v100
	v_mul_f32_e32 v102, v34, v101
	v_ashrrev_i32_e32 v105, 31, v104
	v_cvt_pk_bf16_f32 v103, v102, s0
	v_lshl_add_u64 v[104:105], v[104:105], 1, s[26:27]
	s_and_b64 vcc, exec, s[4:5]
	global_store_short v[104:105], v103, off
	s_cbranch_vccnz .LBB0_396
	v_lshl_add_u32 v104, v94, 8, v100
	v_ashrrev_i32_e32 v105, 31, v104
	v_lshl_add_u64 v[104:105], v[104:105], 2, s[28:29]
	global_store_dword v[104:105], v102, off sc1
.LBB0_396:
	v_add_u32_e32 v102, v99, v100
	v_mul_f32_e32 v101, v32, v101
	v_ashrrev_i32_e32 v103, 31, v102
	v_cvt_pk_bf16_f32 v104, v101, s0
	v_lshl_add_u64 v[102:103], v[102:103], 1, s[26:27]
	s_and_b64 vcc, exec, s[4:5]
	global_store_short v[102:103], v104, off
	s_cbranch_vccnz .LBB0_398
	v_lshl_add_u32 v102, v96, 8, v100
	v_ashrrev_i32_e32 v103, 31, v102
	v_lshl_add_u64 v[102:103], v[102:103], 2, s[28:29]
	global_store_dword v[102:103], v101, off sc1
.LBB0_398:
	global_load_dword v101, v[0:1], off offset:-1280
	v_or_b32_e32 v100, 64, v3
	v_add_u32_e32 v102, v10, v100
	v_ashrrev_i32_e32 v103, 31, v102
	v_lshl_add_u64 v[104:105], v[102:103], 1, s[26:27]
	s_and_b64 vcc, exec, s[4:5]
	s_waitcnt vmcnt(0)
	v_mul_f32_e32 v102, v57, v101
	v_cvt_pk_bf16_f32 v103, v102, s0
	global_store_short v[104:105], v103, off
	s_cbranch_vccnz .LBB0_400
	v_lshl_add_u32 v104, v164, 8, v100
	v_ashrrev_i32_e32 v105, 31, v104
	v_lshl_add_u64 v[104:105], v[104:105], 2, s[28:29]
	global_store_dword v[104:105], v102, off sc1
.LBB0_400:
	v_add_u32_e32 v104, v13, v100
	v_mul_f32_e32 v102, v47, v101
	v_ashrrev_i32_e32 v105, 31, v104
	v_cvt_pk_bf16_f32 v103, v102, s0
	v_lshl_add_u64 v[104:105], v[104:105], 1, s[26:27]
	s_and_b64 vcc, exec, s[4:5]
	global_store_short v[104:105], v103, off
	s_cbranch_vccnz .LBB0_402
	v_lshl_add_u32 v104, v2, 8, v100
	v_ashrrev_i32_e32 v105, 31, v104
	v_lshl_add_u64 v[104:105], v[104:105], 2, s[28:29]
	global_store_dword v[104:105], v102, off sc1
.LBB0_402:
	v_add_u32_e32 v104, v15, v100
	v_mul_f32_e32 v102, v46, v101
	v_ashrrev_i32_e32 v105, 31, v104
	v_cvt_pk_bf16_f32 v103, v102, s0
	v_lshl_add_u64 v[104:105], v[104:105], 1, s[26:27]
	s_and_b64 vcc, exec, s[4:5]
	global_store_short v[104:105], v103, off
	s_cbranch_vccnz .LBB0_404
	v_lshl_add_u32 v104, v11, 8, v100
	v_ashrrev_i32_e32 v105, 31, v104
	v_lshl_add_u64 v[104:105], v[104:105], 2, s[28:29]
	global_store_dword v[104:105], v102, off sc1
.LBB0_404:
	v_add_u32_e32 v104, v59, v100
	v_mul_f32_e32 v102, v45, v101
	v_ashrrev_i32_e32 v105, 31, v104
	v_cvt_pk_bf16_f32 v103, v102, s0
	v_lshl_add_u64 v[104:105], v[104:105], 1, s[26:27]
	s_and_b64 vcc, exec, s[4:5]
	global_store_short v[104:105], v103, off
	s_cbranch_vccnz .LBB0_406
	v_lshl_add_u32 v104, v12, 8, v100
	v_ashrrev_i32_e32 v105, 31, v104
	v_lshl_add_u64 v[104:105], v[104:105], 2, s[28:29]
	global_store_dword v[104:105], v102, off sc1
.LBB0_406:
	v_add_u32_e32 v104, v61, v100
	v_mul_f32_e32 v102, v44, v101
	v_ashrrev_i32_e32 v105, 31, v104
	v_cvt_pk_bf16_f32 v103, v102, s0
	v_lshl_add_u64 v[104:105], v[104:105], 1, s[26:27]
	s_and_b64 vcc, exec, s[4:5]
	global_store_short v[104:105], v103, off
	s_cbranch_vccnz .LBB0_408
	v_lshl_add_u32 v104, v14, 8, v100
	v_ashrrev_i32_e32 v105, 31, v104
	v_lshl_add_u64 v[104:105], v[104:105], 2, s[28:29]
	global_store_dword v[104:105], v102, off sc1
.LBB0_408:
	v_add_u32_e32 v104, v63, v100
	v_mul_f32_e32 v102, v43, v101
	v_ashrrev_i32_e32 v105, 31, v104
	v_cvt_pk_bf16_f32 v103, v102, s0
	v_lshl_add_u64 v[104:105], v[104:105], 1, s[26:27]
	s_and_b64 vcc, exec, s[4:5]
	global_store_short v[104:105], v103, off
	s_cbranch_vccnz .LBB0_410
	v_lshl_add_u32 v104, v58, 8, v100
	v_ashrrev_i32_e32 v105, 31, v104
	v_lshl_add_u64 v[104:105], v[104:105], 2, s[28:29]
	global_store_dword v[104:105], v102, off sc1
.LBB0_410:
	v_add_u32_e32 v104, v81, v100
	v_mul_f32_e32 v102, v42, v101
	v_ashrrev_i32_e32 v105, 31, v104
	v_cvt_pk_bf16_f32 v103, v102, s0
	v_lshl_add_u64 v[104:105], v[104:105], 1, s[26:27]
	s_and_b64 vcc, exec, s[4:5]
	global_store_short v[104:105], v103, off
	s_cbranch_vccnz .LBB0_412
	v_lshl_add_u32 v104, v60, 8, v100
	v_ashrrev_i32_e32 v105, 31, v104
	v_lshl_add_u64 v[104:105], v[104:105], 2, s[28:29]
	global_store_dword v[104:105], v102, off sc1
.LBB0_412:
	v_add_u32_e32 v104, v85, v100
	v_mul_f32_e32 v102, v23, v101
	v_ashrrev_i32_e32 v105, 31, v104
	v_cvt_pk_bf16_f32 v103, v102, s0
	v_lshl_add_u64 v[104:105], v[104:105], 1, s[26:27]
	s_and_b64 vcc, exec, s[4:5]
	global_store_short v[104:105], v103, off
	s_cbranch_vccnz .LBB0_414
	v_lshl_add_u32 v104, v62, 8, v100
	v_ashrrev_i32_e32 v105, 31, v104
	v_lshl_add_u64 v[104:105], v[104:105], 2, s[28:29]
	global_store_dword v[104:105], v102, off sc1
.LBB0_414:
	v_add_u32_e32 v104, v87, v100
	v_mul_f32_e32 v102, v22, v101
	v_ashrrev_i32_e32 v105, 31, v104
	v_cvt_pk_bf16_f32 v103, v102, s0
	v_lshl_add_u64 v[104:105], v[104:105], 1, s[26:27]
	s_and_b64 vcc, exec, s[4:5]
	global_store_short v[104:105], v103, off
	s_cbranch_vccnz .LBB0_416
	v_lshl_add_u32 v104, v80, 8, v100
	v_ashrrev_i32_e32 v105, 31, v104
	v_lshl_add_u64 v[104:105], v[104:105], 2, s[28:29]
	global_store_dword v[104:105], v102, off sc1
.LBB0_416:
	v_add_u32_e32 v104, v89, v100
	v_mul_f32_e32 v102, v21, v101
	v_ashrrev_i32_e32 v105, 31, v104
	v_cvt_pk_bf16_f32 v103, v102, s0
	v_lshl_add_u64 v[104:105], v[104:105], 1, s[26:27]
	s_and_b64 vcc, exec, s[4:5]
	global_store_short v[104:105], v103, off
	s_cbranch_vccnz .LBB0_418
	v_lshl_add_u32 v104, v84, 8, v100
	v_ashrrev_i32_e32 v105, 31, v104
	v_lshl_add_u64 v[104:105], v[104:105], 2, s[28:29]
	global_store_dword v[104:105], v102, off sc1
.LBB0_418:
	v_add_u32_e32 v104, v91, v100
	v_mul_f32_e32 v102, v20, v101
	v_ashrrev_i32_e32 v105, 31, v104
	v_cvt_pk_bf16_f32 v103, v102, s0
	v_lshl_add_u64 v[104:105], v[104:105], 1, s[26:27]
	s_and_b64 vcc, exec, s[4:5]
	global_store_short v[104:105], v103, off
	s_cbranch_vccnz .LBB0_420
	v_lshl_add_u32 v104, v86, 8, v100
	v_ashrrev_i32_e32 v105, 31, v104
	v_lshl_add_u64 v[104:105], v[104:105], 2, s[28:29]
	global_store_dword v[104:105], v102, off sc1
.LBB0_420:
	v_add_u32_e32 v104, v93, v100
	v_mul_f32_e32 v102, v19, v101
	v_ashrrev_i32_e32 v105, 31, v104
	v_cvt_pk_bf16_f32 v103, v102, s0
	v_lshl_add_u64 v[104:105], v[104:105], 1, s[26:27]
	s_and_b64 vcc, exec, s[4:5]
	global_store_short v[104:105], v103, off
	s_cbranch_vccnz .LBB0_422
	v_lshl_add_u32 v104, v88, 8, v100
	v_ashrrev_i32_e32 v105, 31, v104
	v_lshl_add_u64 v[104:105], v[104:105], 2, s[28:29]
	global_store_dword v[104:105], v102, off sc1
.LBB0_422:
	v_add_u32_e32 v104, v95, v100
	v_mul_f32_e32 v102, v18, v101
	v_ashrrev_i32_e32 v105, 31, v104
	v_cvt_pk_bf16_f32 v103, v102, s0
	v_lshl_add_u64 v[104:105], v[104:105], 1, s[26:27]
	s_and_b64 vcc, exec, s[4:5]
	global_store_short v[104:105], v103, off
	s_cbranch_vccnz .LBB0_424
	v_lshl_add_u32 v104, v90, 8, v100
	v_ashrrev_i32_e32 v105, 31, v104
	v_lshl_add_u64 v[104:105], v[104:105], 2, s[28:29]
	global_store_dword v[104:105], v102, off sc1
.LBB0_424:
	v_add_u32_e32 v104, v97, v100
	v_mul_f32_e32 v102, v17, v101
	v_ashrrev_i32_e32 v105, 31, v104
	v_cvt_pk_bf16_f32 v103, v102, s0
	v_lshl_add_u64 v[104:105], v[104:105], 1, s[26:27]
	s_and_b64 vcc, exec, s[4:5]
	global_store_short v[104:105], v103, off
	s_cbranch_vccnz .LBB0_426
	v_lshl_add_u32 v104, v92, 8, v100
	v_ashrrev_i32_e32 v105, 31, v104
	v_lshl_add_u64 v[104:105], v[104:105], 2, s[28:29]
	global_store_dword v[104:105], v102, off sc1
.LBB0_426:
	v_add_u32_e32 v104, v98, v100
	v_mul_f32_e32 v102, v16, v101
	v_ashrrev_i32_e32 v105, 31, v104
	v_cvt_pk_bf16_f32 v103, v102, s0
	v_lshl_add_u64 v[104:105], v[104:105], 1, s[26:27]
	s_and_b64 vcc, exec, s[4:5]
	global_store_short v[104:105], v103, off
	s_cbranch_vccnz .LBB0_428
	v_lshl_add_u32 v104, v94, 8, v100
	v_ashrrev_i32_e32 v105, 31, v104
	v_lshl_add_u64 v[104:105], v[104:105], 2, s[28:29]
	global_store_dword v[104:105], v102, off sc1
.LBB0_428:
	v_add_u32_e32 v102, v99, v100
	v_mul_f32_e32 v101, v82, v101
	v_ashrrev_i32_e32 v103, 31, v102
	v_cvt_pk_bf16_f32 v104, v101, s0
	v_lshl_add_u64 v[102:103], v[102:103], 1, s[26:27]
	s_and_b64 vcc, exec, s[4:5]
	global_store_short v[102:103], v104, off
	s_cbranch_vccnz .LBB0_430
	v_lshl_add_u32 v102, v96, 8, v100
	v_ashrrev_i32_e32 v103, 31, v102
	v_lshl_add_u64 v[102:103], v[102:103], 2, s[28:29]
	global_store_dword v[102:103], v101, off sc1
.LBB0_430:
	global_load_dword v1, v[0:1], off offset:-1152
	v_or_b32_e32 v0, 0x60, v3
	v_add_u32_e32 v100, v10, v0
	v_ashrrev_i32_e32 v101, 31, v100
	v_lshl_add_u64 v[100:101], v[100:101], 1, s[26:27]
	s_and_b64 vcc, exec, s[4:5]
	s_waitcnt vmcnt(0)
	v_mul_f32_e32 v3, v56, v1
	v_cvt_pk_bf16_f32 v10, v3, s0
	global_store_short v[100:101], v10, off
	s_cbranch_vccnz .LBB0_432
	v_lshl_add_u32 v100, v164, 8, v0
	v_ashrrev_i32_e32 v101, 31, v100
	v_lshl_add_u64 v[100:101], v[100:101], 2, s[28:29]
	global_store_dword v[100:101], v3, off sc1
.LBB0_432:
	v_add_u32_e32 v100, v13, v0
	v_mul_f32_e32 v3, v31, v1
	v_ashrrev_i32_e32 v101, 31, v100
	v_cvt_pk_bf16_f32 v10, v3, s0
	v_lshl_add_u64 v[100:101], v[100:101], 1, s[26:27]
	s_and_b64 vcc, exec, s[4:5]
	global_store_short v[100:101], v10, off
	s_cbranch_vccnz .LBB0_434
	v_lshl_add_u32 v100, v2, 8, v0
	v_ashrrev_i32_e32 v101, 31, v100
	v_lshl_add_u64 v[100:101], v[100:101], 2, s[28:29]
	global_store_dword v[100:101], v3, off sc1
.LBB0_434:
	v_add_u32_e32 v100, v15, v0
	v_mul_f32_e32 v2, v30, v1
	v_ashrrev_i32_e32 v101, 31, v100
	v_cvt_pk_bf16_f32 v3, v2, s0
	v_lshl_add_u64 v[100:101], v[100:101], 1, s[26:27]
	s_and_b64 vcc, exec, s[4:5]
	global_store_short v[100:101], v3, off
	s_cbranch_vccnz .LBB0_436
	v_lshl_add_u32 v10, v11, 8, v0
	v_ashrrev_i32_e32 v11, 31, v10
	v_lshl_add_u64 v[10:11], v[10:11], 2, s[28:29]
	global_store_dword v[10:11], v2, off sc1
.LBB0_436:
	v_add_u32_e32 v10, v59, v0
	v_mul_f32_e32 v2, v29, v1
	v_ashrrev_i32_e32 v11, 31, v10
	v_cvt_pk_bf16_f32 v3, v2, s0
	v_lshl_add_u64 v[10:11], v[10:11], 1, s[26:27]
	s_and_b64 vcc, exec, s[4:5]
	global_store_short v[10:11], v3, off
	s_cbranch_vccnz .LBB0_438
	v_lshl_add_u32 v10, v12, 8, v0
	v_ashrrev_i32_e32 v11, 31, v10
	v_lshl_add_u64 v[10:11], v[10:11], 2, s[28:29]
	global_store_dword v[10:11], v2, off sc1
.LBB0_438:
	v_add_u32_e32 v10, v61, v0
	v_mul_f32_e32 v2, v28, v1
	v_ashrrev_i32_e32 v11, 31, v10
	v_cvt_pk_bf16_f32 v3, v2, s0
	v_lshl_add_u64 v[10:11], v[10:11], 1, s[26:27]
	s_and_b64 vcc, exec, s[4:5]
	global_store_short v[10:11], v3, off
	s_cbranch_vccnz .LBB0_440
	v_lshl_add_u32 v10, v14, 8, v0
	v_ashrrev_i32_e32 v11, 31, v10
	v_lshl_add_u64 v[10:11], v[10:11], 2, s[28:29]
	global_store_dword v[10:11], v2, off sc1
.LBB0_440:
	v_add_u32_e32 v10, v63, v0
	v_mul_f32_e32 v2, v27, v1
	v_ashrrev_i32_e32 v11, 31, v10
	v_cvt_pk_bf16_f32 v3, v2, s0
	v_lshl_add_u64 v[10:11], v[10:11], 1, s[26:27]
	s_and_b64 vcc, exec, s[4:5]
	global_store_short v[10:11], v3, off
	s_cbranch_vccnz .LBB0_442
	v_lshl_add_u32 v10, v58, 8, v0
	v_ashrrev_i32_e32 v11, 31, v10
	v_lshl_add_u64 v[10:11], v[10:11], 2, s[28:29]
	global_store_dword v[10:11], v2, off sc1
.LBB0_442:
	v_add_u32_e32 v10, v81, v0
	v_mul_f32_e32 v2, v26, v1
	v_ashrrev_i32_e32 v11, 31, v10
	v_cvt_pk_bf16_f32 v3, v2, s0
	v_lshl_add_u64 v[10:11], v[10:11], 1, s[26:27]
	s_and_b64 vcc, exec, s[4:5]
	global_store_short v[10:11], v3, off
	s_cbranch_vccnz .LBB0_444
	v_lshl_add_u32 v10, v60, 8, v0
	v_ashrrev_i32_e32 v11, 31, v10
	v_lshl_add_u64 v[10:11], v[10:11], 2, s[28:29]
	global_store_dword v[10:11], v2, off sc1
.LBB0_444:
	v_add_u32_e32 v10, v85, v0
	v_mul_f32_e32 v2, v25, v1
	v_ashrrev_i32_e32 v11, 31, v10
	v_cvt_pk_bf16_f32 v3, v2, s0
	v_lshl_add_u64 v[10:11], v[10:11], 1, s[26:27]
	s_and_b64 vcc, exec, s[4:5]
	global_store_short v[10:11], v3, off
	s_cbranch_vccnz .LBB0_446
	v_lshl_add_u32 v10, v62, 8, v0
	v_ashrrev_i32_e32 v11, 31, v10
	v_lshl_add_u64 v[10:11], v[10:11], 2, s[28:29]
	global_store_dword v[10:11], v2, off sc1
.LBB0_446:
	v_add_u32_e32 v10, v87, v0
	v_mul_f32_e32 v2, v24, v1
	v_ashrrev_i32_e32 v11, 31, v10
	v_cvt_pk_bf16_f32 v3, v2, s0
	v_lshl_add_u64 v[10:11], v[10:11], 1, s[26:27]
	s_and_b64 vcc, exec, s[4:5]
	global_store_short v[10:11], v3, off
	s_cbranch_vccnz .LBB0_448
	v_lshl_add_u32 v10, v80, 8, v0
	v_ashrrev_i32_e32 v11, 31, v10
	v_lshl_add_u64 v[10:11], v[10:11], 2, s[28:29]
	global_store_dword v[10:11], v2, off sc1
.LBB0_448:
	v_add_u32_e32 v10, v89, v0
	v_mul_f32_e32 v2, v9, v1
	v_ashrrev_i32_e32 v11, 31, v10
	v_cvt_pk_bf16_f32 v3, v2, s0
	v_lshl_add_u64 v[10:11], v[10:11], 1, s[26:27]
	s_and_b64 vcc, exec, s[4:5]
	global_store_short v[10:11], v3, off
	s_cbranch_vccnz .LBB0_450
	v_lshl_add_u32 v10, v84, 8, v0
	v_ashrrev_i32_e32 v11, 31, v10
	v_lshl_add_u64 v[10:11], v[10:11], 2, s[28:29]
	global_store_dword v[10:11], v2, off sc1
.LBB0_450:
	v_add_u32_e32 v10, v91, v0
	v_mul_f32_e32 v2, v8, v1
	v_ashrrev_i32_e32 v11, 31, v10
	v_cvt_pk_bf16_f32 v3, v2, s0
	v_lshl_add_u64 v[10:11], v[10:11], 1, s[26:27]
	s_and_b64 vcc, exec, s[4:5]
	global_store_short v[10:11], v3, off
	s_cbranch_vccnz .LBB0_452
	v_lshl_add_u32 v10, v86, 8, v0
	v_ashrrev_i32_e32 v11, 31, v10
	v_lshl_add_u64 v[10:11], v[10:11], 2, s[28:29]
	global_store_dword v[10:11], v2, off sc1
.LBB0_452:
	v_add_u32_e32 v10, v93, v0
	v_mul_f32_e32 v2, v7, v1
	v_ashrrev_i32_e32 v11, 31, v10
	v_cvt_pk_bf16_f32 v3, v2, s0
	v_lshl_add_u64 v[10:11], v[10:11], 1, s[26:27]
	s_and_b64 vcc, exec, s[4:5]
	global_store_short v[10:11], v3, off
	s_cbranch_vccnz .LBB0_454
	v_lshl_add_u32 v10, v88, 8, v0
	v_ashrrev_i32_e32 v11, 31, v10
	v_lshl_add_u64 v[10:11], v[10:11], 2, s[28:29]
	global_store_dword v[10:11], v2, off sc1
.LBB0_454:
	v_add_u32_e32 v10, v95, v0
	v_mul_f32_e32 v2, v6, v1
	v_ashrrev_i32_e32 v11, 31, v10
	v_cvt_pk_bf16_f32 v3, v2, s0
	v_lshl_add_u64 v[10:11], v[10:11], 1, s[26:27]
	s_and_b64 vcc, exec, s[4:5]
	global_store_short v[10:11], v3, off
	s_cbranch_vccnz .LBB0_456
	v_lshl_add_u32 v10, v90, 8, v0
	v_ashrrev_i32_e32 v11, 31, v10
	v_lshl_add_u64 v[10:11], v[10:11], 2, s[28:29]
	global_store_dword v[10:11], v2, off sc1
.LBB0_456:
	v_add_u32_e32 v10, v97, v0
	v_mul_f32_e32 v2, v5, v1
	v_ashrrev_i32_e32 v11, 31, v10
	v_cvt_pk_bf16_f32 v3, v2, s0
	v_lshl_add_u64 v[10:11], v[10:11], 1, s[26:27]
	s_and_b64 vcc, exec, s[4:5]
	global_store_short v[10:11], v3, off
	s_cbranch_vccnz .LBB0_458
	v_lshl_add_u32 v10, v92, 8, v0
	v_ashrrev_i32_e32 v11, 31, v10
	v_lshl_add_u64 v[10:11], v[10:11], 2, s[28:29]
	global_store_dword v[10:11], v2, off sc1
.LBB0_458:
	v_add_u32_e32 v10, v98, v0
	v_mul_f32_e32 v2, v4, v1
	v_ashrrev_i32_e32 v11, 31, v10
	v_cvt_pk_bf16_f32 v3, v2, s0
	v_lshl_add_u64 v[10:11], v[10:11], 1, s[26:27]
	s_and_b64 vcc, exec, s[4:5]
	global_store_short v[10:11], v3, off
	s_cbranch_vccnz .LBB0_460
	v_lshl_add_u32 v10, v94, 8, v0
	v_ashrrev_i32_e32 v11, 31, v10
	v_lshl_add_u64 v[10:11], v[10:11], 2, s[28:29]
	global_store_dword v[10:11], v2, off sc1
.LBB0_460:
	v_add_u32_e32 v2, v99, v0
	v_mul_f32_e32 v1, v83, v1
	v_ashrrev_i32_e32 v3, 31, v2
	v_cvt_pk_bf16_f32 v10, v1, s0
	v_lshl_add_u64 v[2:3], v[2:3], 1, s[26:27]
	s_and_b64 vcc, exec, s[4:5]
	global_store_short v[2:3], v10, off
	s_cbranch_vccnz .LBB0_462
	v_lshl_add_u32 v2, v96, 8, v0
	v_ashrrev_i32_e32 v3, 31, v2
	v_lshl_add_u64 v[2:3], v[2:3], 2, s[28:29]
	global_store_dword v[2:3], v1, off sc1

.LBB0_497:
	v_mov_b32_e32 v0, s97
	ds_read_b64 v[0:1], v0
	s_waitcnt lgkmcnt(1)
	v_pk_mul_f32 v[2:3], v[78:79], v[78:79]
	v_or_b32_e32 v88, 32, v76
	v_or_b32_e32 v85, 64, v76
	v_or_b32_e32 v10, 0x60, v76
	s_waitcnt lgkmcnt(0)
	v_readfirstlane_b32 s4, v0
	v_readfirstlane_b32 s5, v1
	v_add_f32_e32 v2, v3, v2
	v_mov_b32_e32 v0, s4
	v_mov_b32_e32 v1, s5
	v_lshl_add_u64 v[0:1], v[76:77], 2, v[0:1]
	global_load_dword v77, v[0:1], off
	s_movk_i32 s4, 0x180
	v_fmac_f32_e32 v2, v57, v57
	v_fmac_f32_e32 v2, v56, v56
	s_waitcnt vmcnt(0)
	v_mul_f32_e32 v11, v79, v77
	v_cvt_pk_bf16_f32 v14, v11, s0
	v_mul_lo_u32 v11, v164, s4
	v_add_u32_e32 v12, v11, v76
	v_ashrrev_i32_e32 v13, 31, v12
	v_lshl_add_u64 v[12:13], v[12:13], 1, s[34:35]
	global_store_short v[12:13], v14, off
	v_mul_f32_e32 v12, v75, v77
	v_cvt_pk_bf16_f32 v13, v12, s0
	v_add_u32_e32 v12, 0x180, v11
	v_add_u32_e32 v14, v12, v76
	v_ashrrev_i32_e32 v15, 31, v14
	v_lshl_add_u64 v[14:15], v[14:15], 1, s[34:35]
	global_store_short v[14:15], v13, off
	v_mul_f32_e32 v13, v73, v77
	v_cvt_pk_bf16_f32 v58, v13, s0
	v_add_u32_e32 v13, 0x300, v11
	v_add_u32_e32 v14, v13, v76
	v_ashrrev_i32_e32 v15, 31, v14
	v_lshl_add_u64 v[14:15], v[14:15], 1, s[34:35]
	global_store_short v[14:15], v58, off
	v_mul_f32_e32 v14, v71, v77
	v_cvt_pk_bf16_f32 v15, v14, s0
	v_add_u32_e32 v14, 0x480, v11
	v_add_u32_e32 v58, v14, v76
	v_ashrrev_i32_e32 v59, 31, v58
	v_lshl_add_u64 v[58:59], v[58:59], 1, s[34:35]
	global_store_short v[58:59], v15, off
	v_mul_f32_e32 v15, v69, v77
	v_cvt_pk_bf16_f32 v60, v15, s0
	v_add_u32_e32 v15, 0xc00, v11
	v_add_u32_e32 v58, v15, v76
	v_ashrrev_i32_e32 v59, 31, v58
	v_lshl_add_u64 v[58:59], v[58:59], 1, s[34:35]
	global_store_short v[58:59], v60, off
	v_mul_f32_e32 v58, v67, v77
	v_cvt_pk_bf16_f32 v59, v58, s0
	v_add_u32_e32 v58, 0xd80, v11
	v_add_u32_e32 v60, v58, v76
	v_ashrrev_i32_e32 v61, 31, v60
	v_lshl_add_u64 v[60:61], v[60:61], 1, s[34:35]
	global_store_short v[60:61], v59, off
	v_mul_f32_e32 v59, v65, v77
	v_cvt_pk_bf16_f32 v62, v59, s0
	v_add_u32_e32 v59, 0xf00, v11
	v_add_u32_e32 v60, v59, v76
	v_ashrrev_i32_e32 v61, 31, v60
	v_lshl_add_u64 v[60:61], v[60:61], 1, s[34:35]
	global_store_short v[60:61], v62, off
	v_mul_f32_e32 v60, v55, v77
	v_cvt_pk_bf16_f32 v61, v60, s0
	v_add_u32_e32 v60, 0x1080, v11
	v_add_u32_e32 v62, v60, v76
	v_ashrrev_i32_e32 v63, 31, v62
	v_lshl_add_u64 v[62:63], v[62:63], 1, s[34:35]
	global_store_short v[62:63], v61, off
	v_mul_f32_e32 v61, v53, v77
	v_cvt_pk_bf16_f32 v79, v61, s0
	v_add_u32_e32 v61, 0x1800, v11
	v_add_u32_e32 v62, v61, v76
	v_ashrrev_i32_e32 v63, 31, v62
	v_lshl_add_u64 v[62:63], v[62:63], 1, s[34:35]
	global_store_short v[62:63], v79, off
	v_mul_f32_e32 v62, v51, v77
	v_cvt_pk_bf16_f32 v63, v62, s0
	v_add_u32_e32 v62, 0x1980, v11
	v_add_u32_e32 v80, v62, v76
	v_ashrrev_i32_e32 v81, 31, v80
	v_lshl_add_u64 v[80:81], v[80:81], 1, s[34:35]
	global_store_short v[80:81], v63, off
	v_mul_f32_e32 v63, v49, v77
	v_cvt_pk_bf16_f32 v79, v63, s0
	v_add_u32_e32 v63, 0x1b00, v11
	v_add_u32_e32 v80, v63, v76
	v_ashrrev_i32_e32 v81, 31, v80
	v_lshl_add_u64 v[80:81], v[80:81], 1, s[34:35]
	v_add_u32_e32 v84, 0x1c80, v11
	global_store_short v[80:81], v79, off
	v_add_u32_e32 v80, v84, v76
	v_mul_f32_e32 v79, v41, v77
	v_ashrrev_i32_e32 v81, 31, v80
	v_cvt_pk_bf16_f32 v79, v79, s0
	v_lshl_add_u64 v[80:81], v[80:81], 1, s[34:35]
	global_store_short v[80:81], v79, off
	v_add_u32_e32 v81, 0x2400, v11
	v_add_u32_e32 v86, v81, v76
	v_mul_f32_e32 v79, v39, v77
	v_ashrrev_i32_e32 v87, 31, v86
	v_cvt_pk_bf16_f32 v79, v79, s0
	v_lshl_add_u64 v[86:87], v[86:87], 1, s[34:35]
	v_add_u32_e32 v80, 0x2580, v11
	global_store_short v[86:87], v79, off
	v_add_u32_e32 v86, v80, v76
	v_mul_f32_e32 v79, v37, v77
	v_ashrrev_i32_e32 v87, 31, v86
	v_cvt_pk_bf16_f32 v79, v79, s0
	v_lshl_add_u64 v[86:87], v[86:87], 1, s[34:35]
	global_store_short v[86:87], v79, off
	v_mul_f32_e32 v79, v35, v77
	v_cvt_pk_bf16_f32 v89, v79, s0
	v_add_u32_e32 v79, 0x2700, v11
	v_add_u32_e32 v86, v79, v76
	v_ashrrev_i32_e32 v87, 31, v86
	v_lshl_add_u64 v[86:87], v[86:87], 1, s[34:35]
	v_mul_f32_e32 v77, v33, v77
	global_store_short v[86:87], v89, off
	v_cvt_pk_bf16_f32 v89, v77, s0
	v_add_u32_e32 v77, 0x2880, v11
	v_add_u32_e32 v86, v77, v76
	global_load_dword v76, v[0:1], off offset:128
	v_ashrrev_i32_e32 v87, 31, v86
	v_lshl_add_u64 v[86:87], v[86:87], 1, s[34:35]
	global_store_short v[86:87], v89, off
	v_add_u32_e32 v86, v11, v88
	v_ashrrev_i32_e32 v87, 31, v86
	v_lshl_add_u64 v[86:87], v[86:87], 1, s[34:35]
	s_waitcnt vmcnt(1)
	v_mul_f32_e32 v3, v78, v76
	v_cvt_pk_bf16_f32 v3, v3, s0
	global_store_short v[86:87], v3, off
	v_add_u32_e32 v86, v12, v88
	v_mul_f32_e32 v3, v74, v76
	v_ashrrev_i32_e32 v87, 31, v86
	v_cvt_pk_bf16_f32 v3, v3, s0
	v_lshl_add_u64 v[86:87], v[86:87], 1, s[34:35]
	global_store_short v[86:87], v3, off
	v_add_u32_e32 v86, v13, v88
	v_mul_f32_e32 v3, v72, v76
	v_ashrrev_i32_e32 v87, 31, v86
	v_cvt_pk_bf16_f32 v3, v3, s0
	v_lshl_add_u64 v[86:87], v[86:87], 1, s[34:35]
	global_store_short v[86:87], v3, off
	v_add_u32_e32 v86, v14, v88
	v_mul_f32_e32 v3, v70, v76
	v_ashrrev_i32_e32 v87, 31, v86
	v_cvt_pk_bf16_f32 v3, v3, s0
	v_lshl_add_u64 v[86:87], v[86:87], 1, s[34:35]
	global_store_short v[86:87], v3, off
	v_add_u32_e32 v86, v15, v88
	v_mul_f32_e32 v3, v68, v76
	v_ashrrev_i32_e32 v87, 31, v86
	v_cvt_pk_bf16_f32 v3, v3, s0
	v_lshl_add_u64 v[86:87], v[86:87], 1, s[34:35]
	global_store_short v[86:87], v3, off
	v_add_u32_e32 v86, v58, v88
	v_mul_f32_e32 v3, v66, v76
	v_ashrrev_i32_e32 v87, 31, v86
	v_cvt_pk_bf16_f32 v3, v3, s0
	v_lshl_add_u64 v[86:87], v[86:87], 1, s[34:35]
	global_store_short v[86:87], v3, off
	v_add_u32_e32 v86, v59, v88
	v_mul_f32_e32 v3, v64, v76
	v_ashrrev_i32_e32 v87, 31, v86
	v_cvt_pk_bf16_f32 v3, v3, s0
	v_lshl_add_u64 v[86:87], v[86:87], 1, s[34:35]
	global_store_short v[86:87], v3, off
	v_add_u32_e32 v86, v60, v88
	v_mul_f32_e32 v3, v54, v76
	v_ashrrev_i32_e32 v87, 31, v86
	v_cvt_pk_bf16_f32 v3, v3, s0
	v_lshl_add_u64 v[86:87], v[86:87], 1, s[34:35]
	global_store_short v[86:87], v3, off
	v_add_u32_e32 v86, v61, v88
	v_mul_f32_e32 v3, v52, v76
	v_ashrrev_i32_e32 v87, 31, v86
	v_cvt_pk_bf16_f32 v3, v3, s0
	v_lshl_add_u64 v[86:87], v[86:87], 1, s[34:35]
	global_store_short v[86:87], v3, off
	v_add_u32_e32 v86, v62, v88
	v_mul_f32_e32 v3, v50, v76
	v_ashrrev_i32_e32 v87, 31, v86
	v_cvt_pk_bf16_f32 v3, v3, s0
	v_lshl_add_u64 v[86:87], v[86:87], 1, s[34:35]
	global_store_short v[86:87], v3, off
	v_add_u32_e32 v86, v63, v88
	v_mul_f32_e32 v3, v48, v76
	v_ashrrev_i32_e32 v87, 31, v86
	v_cvt_pk_bf16_f32 v3, v3, s0
	v_lshl_add_u64 v[86:87], v[86:87], 1, s[34:35]
	global_store_short v[86:87], v3, off
	v_add_u32_e32 v86, v84, v88
	v_mul_f32_e32 v3, v40, v76
	v_ashrrev_i32_e32 v87, 31, v86
	v_cvt_pk_bf16_f32 v3, v3, s0
	v_lshl_add_u64 v[86:87], v[86:87], 1, s[34:35]
	global_store_short v[86:87], v3, off
	v_add_u32_e32 v86, v81, v88
	v_mul_f32_e32 v3, v38, v76
	v_ashrrev_i32_e32 v87, 31, v86
	v_cvt_pk_bf16_f32 v3, v3, s0
	v_lshl_add_u64 v[86:87], v[86:87], 1, s[34:35]
	global_store_short v[86:87], v3, off
	v_add_u32_e32 v86, v80, v88
	v_mul_f32_e32 v3, v36, v76
	v_ashrrev_i32_e32 v87, 31, v86
	v_cvt_pk_bf16_f32 v3, v3, s0
	v_lshl_add_u64 v[86:87], v[86:87], 1, s[34:35]
	global_store_short v[86:87], v3, off
	v_add_u32_e32 v86, v79, v88
	v_mul_f32_e32 v3, v34, v76
	v_ashrrev_i32_e32 v87, 31, v86
	v_cvt_pk_bf16_f32 v3, v3, s0
	v_lshl_add_u64 v[86:87], v[86:87], 1, s[34:35]
	global_store_short v[86:87], v3, off
	v_add_u32_e32 v86, v77, v88
	v_mul_f32_e32 v3, v32, v76
	v_ashrrev_i32_e32 v87, 31, v86
	v_cvt_pk_bf16_f32 v3, v3, s0
	v_lshl_add_u64 v[86:87], v[86:87], 1, s[34:35]
	global_store_short v[86:87], v3, off
	global_load_dword v3, v[0:1], off offset:256
	v_add_u32_e32 v86, v11, v85
	v_ashrrev_i32_e32 v87, 31, v86
	v_lshl_add_u64 v[86:87], v[86:87], 1, s[34:35]
	s_waitcnt vmcnt(0)
	v_mul_f32_e32 v57, v57, v3
	v_cvt_pk_bf16_f32 v57, v57, s0
	global_store_short v[86:87], v57, off
	v_add_u32_e32 v86, v12, v85
	v_mul_f32_e32 v57, v47, v3
	v_ashrrev_i32_e32 v87, 31, v86
	v_cvt_pk_bf16_f32 v57, v57, s0
	v_lshl_add_u64 v[86:87], v[86:87], 1, s[34:35]
	global_store_short v[86:87], v57, off
	v_add_u32_e32 v86, v13, v85
	v_mul_f32_e32 v57, v46, v3
	v_ashrrev_i32_e32 v87, 31, v86
	v_cvt_pk_bf16_f32 v57, v57, s0
	v_lshl_add_u64 v[86:87], v[86:87], 1, s[34:35]
	global_store_short v[86:87], v57, off
	v_add_u32_e32 v86, v14, v85
	v_mul_f32_e32 v57, v45, v3
	v_ashrrev_i32_e32 v87, 31, v86
	v_cvt_pk_bf16_f32 v57, v57, s0
	v_lshl_add_u64 v[86:87], v[86:87], 1, s[34:35]
	global_store_short v[86:87], v57, off
	v_add_u32_e32 v86, v15, v85
	v_mul_f32_e32 v57, v44, v3
	v_ashrrev_i32_e32 v87, 31, v86
	v_cvt_pk_bf16_f32 v57, v57, s0
	v_lshl_add_u64 v[86:87], v[86:87], 1, s[34:35]
	global_store_short v[86:87], v57, off
	v_add_u32_e32 v86, v58, v85
	v_mul_f32_e32 v57, v43, v3
	v_ashrrev_i32_e32 v87, 31, v86
	v_cvt_pk_bf16_f32 v57, v57, s0
	v_lshl_add_u64 v[86:87], v[86:87], 1, s[34:35]
	global_store_short v[86:87], v57, off
	v_add_u32_e32 v86, v59, v85
	v_mul_f32_e32 v57, v42, v3
	v_ashrrev_i32_e32 v87, 31, v86
	v_cvt_pk_bf16_f32 v57, v57, s0
	v_lshl_add_u64 v[86:87], v[86:87], 1, s[34:35]
	global_store_short v[86:87], v57, off
	v_add_u32_e32 v86, v60, v85
	v_mul_f32_e32 v57, v23, v3
	v_ashrrev_i32_e32 v87, 31, v86
	v_cvt_pk_bf16_f32 v57, v57, s0
	v_lshl_add_u64 v[86:87], v[86:87], 1, s[34:35]
	global_store_short v[86:87], v57, off
	v_add_u32_e32 v86, v61, v85
	v_mul_f32_e32 v57, v22, v3
	v_ashrrev_i32_e32 v87, 31, v86
	v_cvt_pk_bf16_f32 v57, v57, s0
	v_lshl_add_u64 v[86:87], v[86:87], 1, s[34:35]
	global_store_short v[86:87], v57, off
	v_add_u32_e32 v86, v62, v85
	v_mul_f32_e32 v57, v21, v3
	v_ashrrev_i32_e32 v87, 31, v86
	v_cvt_pk_bf16_f32 v57, v57, s0
	v_lshl_add_u64 v[86:87], v[86:87], 1, s[34:35]
	global_store_short v[86:87], v57, off
	v_add_u32_e32 v86, v63, v85
	v_mul_f32_e32 v57, v20, v3
	v_ashrrev_i32_e32 v87, 31, v86
	v_cvt_pk_bf16_f32 v57, v57, s0
	v_lshl_add_u64 v[86:87], v[86:87], 1, s[34:35]
	global_store_short v[86:87], v57, off
	v_add_u32_e32 v86, v84, v85
	v_mul_f32_e32 v57, v19, v3
	v_ashrrev_i32_e32 v87, 31, v86
	v_cvt_pk_bf16_f32 v57, v57, s0
	v_lshl_add_u64 v[86:87], v[86:87], 1, s[34:35]
	global_store_short v[86:87], v57, off
	v_add_u32_e32 v86, v81, v85
	v_mul_f32_e32 v57, v18, v3
	v_ashrrev_i32_e32 v87, 31, v86
	v_cvt_pk_bf16_f32 v57, v57, s0
	v_lshl_add_u64 v[86:87], v[86:87], 1, s[34:35]
	global_store_short v[86:87], v57, off
	v_add_u32_e32 v86, v80, v85
	v_mul_f32_e32 v57, v17, v3
	v_ashrrev_i32_e32 v87, 31, v86
	v_cvt_pk_bf16_f32 v57, v57, s0
	v_lshl_add_u64 v[86:87], v[86:87], 1, s[34:35]
	global_store_short v[86:87], v57, off
	v_add_u32_e32 v86, v79, v85
	v_mul_f32_e32 v57, v16, v3
	v_ashrrev_i32_e32 v87, 31, v86
	v_cvt_pk_bf16_f32 v57, v57, s0
	v_lshl_add_u64 v[86:87], v[86:87], 1, s[34:35]
	global_store_short v[86:87], v57, off
	v_add_u32_e32 v86, v77, v85
	v_mul_f32_e32 v3, v82, v3
	v_ashrrev_i32_e32 v87, 31, v86
	v_cvt_pk_bf16_f32 v3, v3, s0
	v_lshl_add_u64 v[86:87], v[86:87], 1, s[34:35]
	global_store_short v[86:87], v3, off
	global_load_dword v3, v[0:1], off offset:384
	s_waitcnt vmcnt(0)
	v_mul_f32_e32 v0, v56, v3
	v_cvt_pk_bf16_f32 v56, v0, s0
	v_add_u32_e32 v0, v11, v10
	v_ashrrev_i32_e32 v1, 31, v0
	v_lshl_add_u64 v[0:1], v[0:1], 1, s[34:35]
	global_store_short v[0:1], v56, off
	v_mul_f32_e32 v0, v31, v3
	v_cvt_pk_bf16_f32 v11, v0, s0
	v_add_u32_e32 v0, v12, v10
	v_ashrrev_i32_e32 v1, 31, v0
	v_lshl_add_u64 v[0:1], v[0:1], 1, s[34:35]
	global_store_short v[0:1], v11, off
	v_mul_f32_e32 v0, v30, v3
	v_cvt_pk_bf16_f32 v11, v0, s0
	v_add_u32_e32 v0, v13, v10
	v_ashrrev_i32_e32 v1, 31, v0
	v_lshl_add_u64 v[0:1], v[0:1], 1, s[34:35]
	global_store_short v[0:1], v11, off
	v_mul_f32_e32 v0, v29, v3
	v_cvt_pk_bf16_f32 v11, v0, s0
	v_add_u32_e32 v0, v14, v10
	v_ashrrev_i32_e32 v1, 31, v0
	v_lshl_add_u64 v[0:1], v[0:1], 1, s[34:35]
	global_store_short v[0:1], v11, off
	v_mul_f32_e32 v0, v28, v3
	v_cvt_pk_bf16_f32 v11, v0, s0
	v_add_u32_e32 v0, v15, v10
	v_ashrrev_i32_e32 v1, 31, v0
	v_lshl_add_u64 v[0:1], v[0:1], 1, s[34:35]
	global_store_short v[0:1], v11, off
	v_mul_f32_e32 v0, v27, v3
	v_cvt_pk_bf16_f32 v11, v0, s0
	v_add_u32_e32 v0, v58, v10
	v_ashrrev_i32_e32 v1, 31, v0
	v_lshl_add_u64 v[0:1], v[0:1], 1, s[34:35]
	global_store_short v[0:1], v11, off
	v_mul_f32_e32 v0, v26, v3
	v_cvt_pk_bf16_f32 v11, v0, s0
	v_add_u32_e32 v0, v59, v10
	v_ashrrev_i32_e32 v1, 31, v0
	v_lshl_add_u64 v[0:1], v[0:1], 1, s[34:35]
	global_store_short v[0:1], v11, off
	v_mul_f32_e32 v0, v25, v3
	v_cvt_pk_bf16_f32 v11, v0, s0
	v_add_u32_e32 v0, v60, v10
	v_ashrrev_i32_e32 v1, 31, v0
	v_lshl_add_u64 v[0:1], v[0:1], 1, s[34:35]
	global_store_short v[0:1], v11, off
	v_mul_f32_e32 v0, v24, v3
	v_cvt_pk_bf16_f32 v11, v0, s0
	v_add_u32_e32 v0, v61, v10
	v_ashrrev_i32_e32 v1, 31, v0
	v_lshl_add_u64 v[0:1], v[0:1], 1, s[34:35]
	global_store_short v[0:1], v11, off
	v_mul_f32_e32 v0, v9, v3
	v_cvt_pk_bf16_f32 v11, v0, s0
	v_add_u32_e32 v0, v62, v10
	v_ashrrev_i32_e32 v1, 31, v0
	v_lshl_add_u64 v[0:1], v[0:1], 1, s[34:35]
	global_store_short v[0:1], v11, off
	v_mul_f32_e32 v0, v8, v3
	v_cvt_pk_bf16_f32 v11, v0, s0
	v_add_u32_e32 v0, v63, v10
	v_ashrrev_i32_e32 v1, 31, v0
	v_lshl_add_u64 v[0:1], v[0:1], 1, s[34:35]
	global_store_short v[0:1], v11, off
	v_mul_f32_e32 v0, v7, v3
	v_cvt_pk_bf16_f32 v11, v0, s0
	v_add_u32_e32 v0, v84, v10
	v_ashrrev_i32_e32 v1, 31, v0
	v_lshl_add_u64 v[0:1], v[0:1], 1, s[34:35]
	global_store_short v[0:1], v11, off
	v_mul_f32_e32 v0, v6, v3
	v_cvt_pk_bf16_f32 v11, v0, s0
	v_add_u32_e32 v0, v81, v10
	v_ashrrev_i32_e32 v1, 31, v0
	v_lshl_add_u64 v[0:1], v[0:1], 1, s[34:35]
	global_store_short v[0:1], v11, off
	v_mul_f32_e32 v0, v5, v3
	v_cvt_pk_bf16_f32 v11, v0, s0
	v_add_u32_e32 v0, v80, v10
	v_ashrrev_i32_e32 v1, 31, v0
	v_lshl_add_u64 v[0:1], v[0:1], 1, s[34:35]
	global_store_short v[0:1], v11, off
	v_mul_f32_e32 v0, v4, v3
	v_cvt_pk_bf16_f32 v11, v0, s0
	v_add_u32_e32 v0, v79, v10
	v_ashrrev_i32_e32 v1, 31, v0
	v_lshl_add_u64 v[0:1], v[0:1], 1, s[34:35]
	global_store_short v[0:1], v11, off
	v_mul_f32_e32 v0, v83, v3
	v_cvt_pk_bf16_f32 v3, v0, s0
	v_add_u32_e32 v0, v77, v10
	v_ashrrev_i32_e32 v1, 31, v0
	v_lshl_add_u64 v[0:1], v[0:1], 1, s[34:35]
	global_store_short v[0:1], v3, off
	v_and_b32_e32 v1, 64, v214
	v_xor_b32_e32 v0, 1, v214
	v_add_u32_e32 v1, 64, v1
	v_cmp_lt_i32_e32 vcc, v0, v1
	s_nop 1
	v_cndmask_b32_e32 v0, v214, v0, vcc
	v_lshlrev_b32_e32 v3, 2, v0
	v_xor_b32_e32 v0, 2, v214
	v_cmp_lt_i32_e32 vcc, v0, v1
	s_nop 1
	v_cndmask_b32_e32 v0, v214, v0, vcc
	v_lshlrev_b32_e32 v10, 2, v0
	v_xor_b32_e32 v0, 4, v214
	v_cmp_lt_i32_e32 vcc, v0, v1
	s_nop 1
	v_cndmask_b32_e32 v0, v214, v0, vcc
	v_lshlrev_b32_e32 v11, 2, v0
	v_xor_b32_e32 v0, 8, v214
	v_cmp_lt_i32_e32 vcc, v0, v1
	s_nop 1
	v_cndmask_b32_e32 v0, v214, v0, vcc
	v_lshlrev_b32_e32 v12, 2, v0
	v_xor_b32_e32 v0, 16, v214
	v_cmp_lt_i32_e32 vcc, v0, v1
	ds_bpermute_b32 v1, v3, v2
	s_waitcnt lgkmcnt(0)
	v_add_f32_e32 v1, v2, v1
	ds_bpermute_b32 v2, v10, v1
	v_cndmask_b32_e32 v0, v214, v0, vcc
	v_lshlrev_b32_e32 v13, 2, v0
	v_lshl_add_u32 v0, s10, 14, v164
	s_waitcnt lgkmcnt(0)
	v_add_f32_e32 v1, v1, v2
	ds_bpermute_b32 v2, v11, v1
	s_waitcnt lgkmcnt(0)
	v_add_f32_e32 v1, v1, v2
	ds_bpermute_b32 v2, v12, v1
	s_waitcnt lgkmcnt(0)
	v_add_f32_e32 v2, v1, v2
	ds_bpermute_b32 v14, v13, v2
	v_ashrrev_i32_e32 v1, 31, v0
	s_and_saveexec_b64 s[4:5], s[0:1]
	s_cbranch_execz .LBB0_499
	s_waitcnt lgkmcnt(0)
	v_add_f32_e32 v2, v2, v14
	v_lshl_add_u64 v[14:15], v[0:1], 2, s[36:37]
	global_store_dword v[14:15], v2, off sc1

.LBB0_836:
	v_add_u32_e32 v148, s68, v160
	v_ashrrev_i32_e32 v149, 31, v148
	v_lshl_add_u64 v[64:65], v[148:149], 2, s[18:19]
	v_add_co_u32_e32 v66, vcc, 0x10000, v64
	v_or_b32_e32 v150, 8, v148
	s_nop 0
	v_addc_co_u32_e32 v67, vcc, 0, v65, vcc
	global_load_dwordx4 v[92:95], v[64:65], off
	global_load_dwordx4 v[96:99], v[66:67], off
	v_add_co_u32_e32 v66, vcc, 0x20000, v64
	v_ashrrev_i32_e32 v151, 31, v150
	s_nop 0
	v_addc_co_u32_e32 v67, vcc, 0, v65, vcc
	v_add_co_u32_e32 v68, vcc, 0x30000, v64
	v_lshl_add_u64 v[88:89], v[150:151], 2, s[18:19]
	s_nop 0
	v_addc_co_u32_e32 v69, vcc, 0, v65, vcc
	global_load_dwordx4 v[100:103], v[66:67], off
	global_load_dwordx4 v[104:107], v[68:69], off
	v_add_co_u32_e32 v66, vcc, 0x40000, v64
	v_or_b32_e32 v152, 9, v148
	s_nop 0
	v_addc_co_u32_e32 v67, vcc, 0, v65, vcc
	v_add_co_u32_e32 v68, vcc, 0x50000, v64
	v_ashrrev_i32_e32 v153, 31, v152
	s_nop 0
	v_addc_co_u32_e32 v69, vcc, 0, v65, vcc
	global_load_dwordx4 v[108:111], v[66:67], off
	global_load_dwordx4 v[112:115], v[68:69], off
	v_add_co_u32_e32 v66, vcc, 0x60000, v64
	v_lshl_add_u64 v[126:127], v[152:153], 2, s[18:19]
	s_nop 0
	v_addc_co_u32_e32 v67, vcc, 0, v65, vcc
	v_add_co_u32_e32 v64, vcc, 0x70000, v64
	global_load_dwordx4 v[116:119], v[66:67], off
	s_nop 0
	v_addc_co_u32_e32 v65, vcc, 0, v65, vcc
	global_load_dwordx4 v[120:123], v[64:65], off
	v_add_co_u32_e32 v64, vcc, s77, v88
	v_or_b32_e32 v154, 16, v148
	s_nop 0
	v_addc_co_u32_e32 v65, vcc, 0, v89, vcc
	v_add_co_u32_e32 v68, vcc, s78, v88
	global_load_dword v124, v[88:89], off
	s_nop 0
	global_load_dwordx4 v[64:67], v[64:65], off
	v_addc_co_u32_e32 v69, vcc, 0, v89, vcc
	v_add_co_u32_e32 v72, vcc, s79, v88
	v_ashrrev_i32_e32 v155, 31, v154
	s_nop 0
	v_addc_co_u32_e32 v73, vcc, 0, v89, vcc
	v_add_co_u32_e32 v76, vcc, s80, v88
	global_load_dwordx4 v[68:71], v[68:69], off
	s_nop 0
	global_load_dwordx4 v[72:75], v[72:73], off
	v_addc_co_u32_e32 v77, vcc, 0, v89, vcc
	v_add_co_u32_e32 v80, vcc, s81, v88
	s_lshl_b64 s[72:73], s[72:73], 2
	s_nop 0
	v_addc_co_u32_e32 v81, vcc, 0, v89, vcc
	v_add_co_u32_e32 v84, vcc, s82, v88
	global_load_dwordx4 v[76:79], v[76:77], off
	s_nop 0
	global_load_dwordx4 v[80:83], v[80:81], off
	v_addc_co_u32_e32 v85, vcc, 0, v89, vcc
	v_add_co_u32_e32 v88, vcc, s83, v88
	global_load_dwordx4 v[84:87], v[84:85], off
	s_nop 0
	v_addc_co_u32_e32 v89, vcc, 0, v89, vcc
	global_load_dwordx4 v[88:91], v[88:89], off
	s_add_u32 s72, s10, s72
	global_load_dwordx3 v[132:134], v[126:127], off
	s_addc_u32 s73, s11, s73
	s_ashr_i32 s8, s86, 3
	s_waitcnt vmcnt(0)
	v_mov_b32_e32 v126, v92
	v_mov_b32_e32 v128, v96
	v_mov_b32_e32 v130, v104
	v_mov_b32_e32 v127, v108
	v_mov_b32_e32 v129, v112
	v_pk_add_f32 v[126:127], v[126:127], v[128:129]
	v_mov_b32_e32 v108, v93
	v_mov_b32_e32 v112, v97
	v_pk_add_f32 v[92:93], v[108:109], v[112:113]
	v_mov_b32_e32 v128, v100
	v_mov_b32_e32 v100, v106
	v_mov_b32_e32 v129, v116
	v_mov_b32_e32 v116, v101
	v_mov_b32_e32 v131, v120
	v_mov_b32_e32 v120, v105
	v_pk_add_f32 v[96:97], v[116:117], v[120:121]
	v_mov_b32_e32 v101, v122
	v_pk_add_f32 v[92:93], v[92:93], v[96:97]
	v_mov_b32_e32 v96, v98
	v_add_f32_e32 v151, v92, v93
	v_mov_b32_e32 v92, v94
	v_mov_b32_e32 v93, v110
	v_mov_b32_e32 v97, v114
	v_pk_add_f32 v[92:93], v[92:93], v[96:97]
	v_mov_b32_e32 v96, v102
	v_mov_b32_e32 v97, v118
	v_pk_add_f32 v[96:97], v[96:97], v[100:101]
	v_mov_b32_e32 v110, v95
	v_pk_add_f32 v[92:93], v[92:93], v[96:97]
	v_mov_b32_e32 v114, v99
	v_mov_b32_e32 v118, v103
	v_mov_b32_e32 v122, v107
	v_add_f32_e32 v153, v92, v93
	v_pk_add_f32 v[92:93], v[110:111], v[114:115]
	v_pk_add_f32 v[94:95], v[118:119], v[122:123]
	v_mov_b32_e32 v96, v72
	v_pk_add_f32 v[92:93], v[92:93], v[94:95]
	v_mov_b32_e32 v94, v68
	v_add_f32_e32 v205, v92, v93
	v_mov_b32_e32 v92, v64
	v_mov_b32_e32 v125, v76
	v_mov_b32_e32 v93, v80
	v_pk_add_f32 v[92:93], v[124:125], v[92:93]
	v_mov_b32_e32 v80, v65
	v_pk_add_f32 v[128:129], v[128:129], v[130:131]
	v_mov_b32_e32 v95, v84
	v_pk_add_f32 v[126:127], v[126:127], v[128:129]
	v_mov_b32_e32 v84, v69
	v_mov_b32_e32 v97, v88
	v_pk_add_f32 v[94:95], v[94:95], v[96:97]
	v_mov_b32_e32 v76, v132
	v_pk_add_f32 v[92:93], v[92:93], v[94:95]
	v_pk_add_f32 v[76:77], v[76:77], v[80:81]
	v_add_f32_e32 v225, v92, v93
	v_lshl_add_u64 v[92:93], v[154:155], 2, s[18:19]
	v_add_co_u32_e32 v80, vcc, s77, v92
	global_load_dword v64, v[92:93], off
	s_nop 0
	v_addc_co_u32_e32 v81, vcc, 0, v93, vcc
	v_add_co_u32_e32 v94, vcc, s78, v92
	v_mov_b32_e32 v88, v73
	s_nop 0
	v_addc_co_u32_e32 v95, vcc, 0, v93, vcc
	global_load_dwordx4 v[206:209], v[80:81], off
	global_load_dwordx4 v[210:213], v[94:95], off
	v_add_co_u32_e32 v80, vcc, s79, v92
	v_pk_add_f32 v[68:69], v[84:85], v[88:89]
	s_nop 0
	v_addc_co_u32_e32 v81, vcc, 0, v93, vcc
	v_add_co_u32_e32 v94, vcc, s80, v92
	v_or_b32_e32 v84, 24, v148
	s_nop 0
	v_addc_co_u32_e32 v95, vcc, 0, v93, vcc
	global_load_dwordx4 v[104:107], v[80:81], off
	global_load_dwordx4 v[214:217], v[94:95], off
	v_add_co_u32_e32 v80, vcc, s81, v92
	v_ashrrev_i32_e32 v85, 31, v84
	s_nop 0
	v_addc_co_u32_e32 v81, vcc, 0, v93, vcc
	v_add_co_u32_e32 v94, vcc, s82, v92
	v_lshl_add_u64 v[72:73], v[84:85], 2, s[18:19]
	s_nop 0
	v_addc_co_u32_e32 v95, vcc, 0, v93, vcc
	global_load_dwordx4 v[218:221], v[80:81], off
	global_load_dwordx4 v[120:123], v[94:95], off
	v_add_co_u32_e32 v80, vcc, s83, v92
	v_pk_add_f32 v[68:69], v[76:77], v[68:69]
	s_nop 0
	v_addc_co_u32_e32 v81, vcc, 0, v93, vcc
	global_load_dwordx4 v[128:131], v[80:81], off
	v_or_b32_e32 v80, 17, v148
	v_ashrrev_i32_e32 v81, 31, v80
	v_lshl_add_u64 v[92:93], v[80:81], 2, s[18:19]
	global_load_dwordx3 v[222:224], v[92:93], off
	v_add_co_u32_e32 v76, vcc, s77, v72
	v_add_f32_e32 v149, v126, v127
	s_nop 0
	v_addc_co_u32_e32 v77, vcc, 0, v73, vcc
	global_load_dword v132, v[72:73], off
	global_load_dwordx4 v[92:95], v[76:77], off
	v_add_co_u32_e32 v76, vcc, s78, v72
	v_add_f32_e32 v81, v68, v69
	s_nop 0
	v_addc_co_u32_e32 v77, vcc, 0, v73, vcc
	v_add_co_u32_e32 v88, vcc, s79, v72
	s_waitcnt vmcnt(6)
	v_mov_b32_e32 v65, v214
	v_addc_co_u32_e32 v89, vcc, 0, v73, vcc
	global_load_dwordx4 v[96:99], v[76:77], off
	global_load_dwordx4 v[100:103], v[88:89], off
	v_add_co_u32_e32 v76, vcc, s80, v72
	s_waitcnt vmcnt(4)
	v_mov_b32_e32 v214, v222
	v_addc_co_u32_e32 v77, vcc, 0, v73, vcc
	v_add_co_u32_e32 v88, vcc, s81, v72
	s_nop 1
	v_addc_co_u32_e32 v89, vcc, 0, v73, vcc
	global_load_dwordx4 v[108:111], v[76:77], off
	global_load_dwordx4 v[112:115], v[88:89], off
	v_add_co_u32_e32 v76, vcc, s82, v72
	v_or_b32_e32 v88, 25, v148
	s_nop 0
	v_addc_co_u32_e32 v77, vcc, 0, v73, vcc
	v_add_co_u32_e32 v72, vcc, s83, v72
	global_load_dwordx4 v[116:119], v[76:77], off
	s_nop 0
	v_addc_co_u32_e32 v73, vcc, 0, v73, vcc
	global_load_dwordx4 v[124:127], v[72:73], off
	v_ashrrev_i32_e32 v89, 31, v88
	v_lshl_add_u64 v[68:69], v[88:89], 2, s[18:19]
	global_load_dwordx3 v[136:138], v[68:69], off
	v_mov_b32_e32 v68, v133
	v_mov_b32_e32 v69, v78
	v_mov_b32_e32 v72, v66
	v_mov_b32_e32 v73, v82
	v_pk_add_f32 v[68:69], v[68:69], v[72:73]
	v_mov_b32_e32 v72, v70
	v_mov_b32_e32 v73, v86
	v_mov_b32_e32 v76, v74
	v_mov_b32_e32 v77, v90
	v_pk_add_f32 v[72:73], v[72:73], v[76:77]
	v_mov_b32_e32 v78, v134
	v_pk_add_f32 v[68:69], v[68:69], v[72:73]
	v_mov_b32_e32 v82, v67
	v_mov_b32_e32 v86, v71
	v_mov_b32_e32 v90, v75
	v_add_f32_e32 v72, v68, v69
	v_pk_add_f32 v[66:67], v[78:79], v[82:83]
	v_pk_add_f32 v[68:69], v[86:87], v[90:91]
	s_waitcnt vmcnt(5)
	v_mov_b32_e32 v70, v100
	v_pk_add_f32 v[66:67], v[66:67], v[68:69]
	v_mov_b32_e32 v68, v104
	v_add_f32_e32 v73, v66, v67
	v_mov_b32_e32 v66, v206
	v_mov_b32_e32 v67, v218
	v_pk_add_f32 v[64:65], v[64:65], v[66:67]
	v_mov_b32_e32 v66, v210
	v_mov_b32_e32 v67, v120
	v_mov_b32_e32 v69, v128
	v_pk_add_f32 v[66:67], v[66:67], v[68:69]
	v_mov_b32_e32 v218, v207
	v_pk_add_f32 v[64:65], v[64:65], v[66:67]
	v_mov_b32_e32 v120, v211
	v_mov_b32_e32 v128, v105
	v_add_f32_e32 v74, v64, v65
	v_pk_add_f32 v[64:65], v[214:215], v[218:219]
	v_pk_add_f32 v[66:67], v[120:121], v[128:129]
	v_mov_b32_e32 v68, v106
	v_pk_add_f32 v[64:65], v[64:65], v[66:67]
	v_mov_b32_e32 v66, v208
	v_add_f32_e32 v75, v64, v65
	v_mov_b32_e32 v64, v223
	v_mov_b32_e32 v65, v216
	v_mov_b32_e32 v67, v220
	v_pk_add_f32 v[64:65], v[64:65], v[66:67]
	v_mov_b32_e32 v66, v212
	v_mov_b32_e32 v67, v122
	v_mov_b32_e32 v69, v130
	v_pk_add_f32 v[66:67], v[66:67], v[68:69]
	v_mov_b32_e32 v216, v224
	v_pk_add_f32 v[64:65], v[64:65], v[66:67]
	v_or_b32_e32 v66, s0, v140
	v_ashrrev_i32_e32 v67, 31, v66
	v_lshl_add_u64 v[66:67], v[66:67], 2, s[72:73]
	global_load_dword v91, v[66:67], off
	global_load_dword v90, v[66:67], off offset:128
	global_load_dword v105, v[66:67], off offset:256
	global_load_dword v104, v[66:67], off offset:384
	v_mov_b32_e32 v220, v209
	v_mov_b32_e32 v122, v213
	v_mov_b32_e32 v130, v107
	v_add_f32_e32 v76, v64, v65
	v_pk_add_f32 v[64:65], v[216:217], v[220:221]
	v_pk_add_f32 v[68:69], v[122:123], v[130:131]
	s_waitcnt vmcnt(8)
	v_mov_b32_e32 v133, v108
	v_pk_add_f32 v[64:65], v[64:65], v[68:69]
	v_mov_b32_e32 v68, v96
	v_add_f32_e32 v77, v64, v65
	v_mov_b32_e32 v64, v92
	s_waitcnt vmcnt(7)
	v_mov_b32_e32 v65, v112
	s_waitcnt vmcnt(6)
	v_mov_b32_e32 v69, v116
	s_waitcnt vmcnt(5)
	v_mov_b32_e32 v71, v124
	v_pk_add_f32 v[64:65], v[132:133], v[64:65]
	v_pk_add_f32 v[68:69], v[68:69], v[70:71]
	s_waitcnt vmcnt(4)
	v_mov_b32_e32 v108, v136
	v_pk_add_f32 v[64:65], v[64:65], v[68:69]
	v_mov_b32_e32 v112, v93
	v_mov_b32_e32 v116, v97
	v_mov_b32_e32 v124, v101
	v_add_f32_e32 v78, v64, v65
	v_pk_add_f32 v[64:65], v[108:109], v[112:113]
	v_pk_add_f32 v[68:69], v[116:117], v[124:125]
	v_mov_b32_e32 v70, v102
	v_pk_add_f32 v[64:65], v[64:65], v[68:69]
	v_mov_b32_e32 v68, v94
	v_add_f32_e32 v79, v64, v65
	v_mov_b32_e32 v64, v137
	v_mov_b32_e32 v65, v110
	v_mov_b32_e32 v69, v114
	v_pk_add_f32 v[64:65], v[64:65], v[68:69]
	v_mov_b32_e32 v68, v98
	v_mov_b32_e32 v69, v118
	v_mov_b32_e32 v71, v126
	v_pk_add_f32 v[68:69], v[68:69], v[70:71]
	v_mov_b32_e32 v110, v138
	v_pk_add_f32 v[64:65], v[64:65], v[68:69]
	v_mov_b32_e32 v114, v95
	v_mov_b32_e32 v118, v99
	v_mov_b32_e32 v126, v103
	v_add_f32_e32 v68, v64, v65
	v_pk_add_f32 v[64:65], v[110:111], v[114:115]
	v_pk_add_f32 v[66:67], v[118:119], v[126:127]
	s_and_b32 s72, s86, 7
	v_pk_add_f32 v[64:65], v[64:65], v[66:67]
	s_cmp_gt_i32 s8, 1
	v_add_f32_e32 v64, v64, v65
	v_fmamk_f32 v65, v149, 0x3a800000, v196
	v_rsq_f32_e32 v92, v65
	v_fmamk_f32 v65, v151, 0x3a800000, v196
	v_rsq_f32_e32 v94, v65
	v_fmamk_f32 v65, v153, 0x3a800000, v196
	v_rsq_f32_e32 v96, v65
	v_fmamk_f32 v65, v205, 0x3a800000, v196
	v_rsq_f32_e32 v98, v65
	v_fmamk_f32 v65, v225, 0x3a800000, v196
	v_rsq_f32_e32 v100, v65
	v_fmamk_f32 v65, v81, 0x3a800000, v196
	v_rsq_f32_e32 v102, v65
	v_fmamk_f32 v65, v72, 0x3a800000, v196
	v_rsq_f32_e32 v106, v65
	v_fmamk_f32 v65, v73, 0x3a800000, v196
	v_rsq_f32_e32 v108, v65
	v_fmamk_f32 v65, v74, 0x3a800000, v196
	v_rsq_f32_e32 v110, v65
	v_fmamk_f32 v65, v75, 0x3a800000, v196
	v_rsq_f32_e32 v112, v65
	v_fmamk_f32 v65, v76, 0x3a800000, v196
	v_rsq_f32_e32 v114, v65
	v_fmamk_f32 v65, v77, 0x3a800000, v196
	v_rsq_f32_e32 v116, v65
	v_fmamk_f32 v65, v78, 0x3a800000, v196
	v_rsq_f32_e32 v118, v65
	v_fmamk_f32 v65, v79, 0x3a800000, v196
	v_rsq_f32_e32 v120, v65
	v_fmamk_f32 v65, v68, 0x3a800000, v196
	v_fmamk_f32 v64, v64, 0x3a800000, v196
	v_rsq_f32_e32 v122, v65
	v_rsq_f32_e32 v124, v64
	v_mov_b32_e32 v64, v32
	v_mov_b32_e32 v65, v48
	v_mov_b32_e32 v48, v33
	v_mov_b32_e32 v32, v34
	v_mov_b32_e32 v33, v50
	s_waitcnt vmcnt(2)
	v_pk_fma_f32 v[78:79], v[32:33], v[96:97], v[90:91] op_sel_hi:[1,0,1]
	v_mov_b32_e32 v32, v36
	v_mov_b32_e32 v33, v52
	v_pk_fma_f32 v[70:71], v[32:33], v[100:101], v[90:91] op_sel_hi:[1,0,1]
	v_mov_b32_e32 v32, v38
	v_mov_b32_e32 v33, v54
	v_pk_fma_f32 v[76:77], v[32:33], v[106:107], v[90:91] op_sel_hi:[1,0,1]
	v_mov_b32_e32 v32, v40
	v_mov_b32_e32 v33, v56
	v_pk_fma_f32 v[66:67], v[32:33], v[110:111], v[90:91] op_sel_hi:[1,0,1]
	v_mov_b32_e32 v56, v41
	v_mov_b32_e32 v32, v42
	v_mov_b32_e32 v33, v58
	v_pk_fma_f32 v[86:87], v[64:65], v[92:93], v[90:91] op_sel_hi:[1,0,1]
	v_mov_b32_e32 v52, v37
	v_pk_fma_f32 v[64:65], v[56:57], v[112:113], v[90:91] op_sel_hi:[1,0,1]
	v_pk_fma_f32 v[56:57], v[32:33], v[114:115], v[90:91] op_sel_hi:[1,0,1]
	v_mov_b32_e32 v32, v44
	v_mov_b32_e32 v33, v60
	v_pk_fma_f32 v[72:73], v[52:53], v[102:103], v[90:91] op_sel_hi:[1,0,1]
	v_pk_fma_f32 v[52:53], v[32:33], v[118:119], v[90:91] op_sel_hi:[1,0,1]
	v_mov_b32_e32 v32, v46
	v_mov_b32_e32 v33, v62
	v_pk_fma_f32 v[82:83], v[48:49], v[94:95], v[90:91] op_sel_hi:[1,0,1]
	v_pk_fma_f32 v[48:49], v[32:33], v[122:123], v[90:91] op_sel_hi:[1,0,1]
	v_mov_b32_e32 v32, v0
	v_mov_b32_e32 v33, v16
	v_mov_b32_e32 v16, v1
	v_mov_b32_e32 v0, v2
	v_mov_b32_e32 v1, v18
	s_waitcnt vmcnt(0)
	v_pk_fma_f32 v[40:41], v[0:1], v[96:97], v[104:105] op_sel_hi:[1,0,1]
	v_mov_b32_e32 v0, v4
	v_mov_b32_e32 v1, v20
	v_pk_fma_f32 v[36:37], v[0:1], v[100:101], v[104:105] op_sel_hi:[1,0,1]
	v_mov_b32_e32 v0, v6
	v_mov_b32_e32 v1, v22
	v_mov_b32_e32 v60, v45
	v_pk_fma_f32 v[44:45], v[32:33], v[92:93], v[104:105] op_sel_hi:[1,0,1]
	v_mov_b32_e32 v20, v5
	v_pk_fma_f32 v[32:33], v[0:1], v[106:107], v[104:105] op_sel_hi:[1,0,1]
	v_mov_b32_e32 v0, v8
	v_mov_b32_e32 v1, v24
	v_mov_b32_e32 v50, v35
	v_pk_fma_f32 v[34:35], v[20:21], v[102:103], v[104:105] op_sel_hi:[1,0,1]
	v_pk_fma_f32 v[20:21], v[0:1], v[110:111], v[104:105] op_sel_hi:[1,0,1]
	v_mov_b32_e32 v0, v10
	v_mov_b32_e32 v1, v26
	v_mov_b32_e32 v58, v43
	v_pk_fma_f32 v[42:43], v[16:17], v[94:95], v[104:105] op_sel_hi:[1,0,1]
	v_pk_fma_f32 v[16:17], v[0:1], v[114:115], v[104:105] op_sel_hi:[1,0,1]
	v_mov_b32_e32 v0, v12
	v_mov_b32_e32 v1, v28
	v_mov_b32_e32 v54, v39
	v_mov_b32_e32 v62, v47
	v_mov_b32_e32 v18, v3
	v_mov_b32_e32 v22, v7
	v_mov_b32_e32 v24, v9
	v_mov_b32_e32 v26, v11
	v_pk_fma_f32 v[6:7], v[0:1], v[118:119], v[104:105] op_sel_hi:[1,0,1]
	v_mov_b32_e32 v28, v13
	v_mov_b32_e32 v0, v14
	v_mov_b32_e32 v1, v30
	v_mov_b32_e32 v30, v15
	v_pk_fma_f32 v[74:75], v[50:51], v[98:99], v[90:91] op_sel_hi:[1,0,1]
	v_pk_fma_f32 v[68:69], v[54:55], v[108:109], v[90:91] op_sel_hi:[1,0,1]
	v_pk_fma_f32 v[54:55], v[58:59], v[116:117], v[90:91] op_sel_hi:[1,0,1]
	v_pk_fma_f32 v[50:51], v[60:61], v[120:121], v[90:91] op_sel_hi:[1,0,1]
	v_pk_fma_f32 v[46:47], v[62:63], v[124:125], v[90:91] op_sel_hi:[1,0,1]
	v_pk_fma_f32 v[38:39], v[18:19], v[98:99], v[104:105] op_sel_hi:[1,0,1]
	v_pk_fma_f32 v[22:23], v[22:23], v[108:109], v[104:105] op_sel_hi:[1,0,1]
	v_pk_fma_f32 v[18:19], v[24:25], v[112:113], v[104:105] op_sel_hi:[1,0,1]
	v_pk_fma_f32 v[8:9], v[26:27], v[116:117], v[104:105] op_sel_hi:[1,0,1]
	v_pk_fma_f32 v[4:5], v[28:29], v[120:121], v[104:105] op_sel_hi:[1,0,1]
	v_pk_fma_f32 v[2:3], v[0:1], v[122:123], v[104:105] op_sel_hi:[1,0,1]
	v_pk_fma_f32 v[0:1], v[30:31], v[124:125], v[104:105] op_sel_hi:[1,0,1]
	s_mov_b64 s[0:1], -1
	s_cbranch_scc0 .LBB0_846
	s_and_b64 s[0:1], s[4:5], exec
	s_cselect_b32 s0, 0x100, 0
	s_add_i32 s0, s69, s0
	v_add_u32_e32 v27, s0, v160
	s_lshl_b32 s0, s87, 18
	s_lshl_b32 s1, s72, 15
	s_or_b32 s75, s0, s1
	s_lshl_b32 s0, s87, 10
	s_lshl_b32 s73, s72, 7
	s_or_b32 s87, s0, s73
	v_or_b32_e32 v29, s87, v140
	v_mul_lo_u32 v29, v29, s76
	v_or_b32_e32 v28, s75, v161
	v_add_u32_e32 v29, 0x800000, v29
	v_cndmask_b32_e64 v60, v28, v29, s[4:5]
	v_add_u32_e32 v28, v60, v27
	v_ashrrev_i32_e32 v29, 31, v28
	v_cvt_pk_bf16_f32 v30, v87, v83
	v_cvt_pk_bf16_f32 v31, v79, v75
	v_lshl_add_u64 v[28:29], v[28:29], 1, s[20:21]
	global_store_dwordx2 v[28:29], v[30:31], off
	v_or_b32_e32 v28, 8, v27
	v_add_u32_e32 v30, v60, v28
	v_ashrrev_i32_e32 v31, 31, v30
	v_cvt_pk_bf16_f32 v58, v71, v73
	v_cvt_pk_bf16_f32 v59, v77, v69
	v_lshl_add_u64 v[30:31], v[30:31], 1, s[20:21]
	v_or_b32_e32 v29, 16, v27
	global_store_dwordx2 v[30:31], v[58:59], off
	v_add_u32_e32 v30, v60, v29
	v_ashrrev_i32_e32 v31, 31, v30
	v_cvt_pk_bf16_f32 v58, v67, v65
	v_cvt_pk_bf16_f32 v59, v57, v55
	v_lshl_add_u64 v[30:31], v[30:31], 1, s[20:21]
	global_store_dwordx2 v[30:31], v[58:59], off
	v_or_b32_e32 v30, 24, v27
	v_add_u32_e32 v58, v60, v30
	v_ashrrev_i32_e32 v59, 31, v58
	v_cndmask_b32_e64 v31, 0, 1, s[70:71]
	v_or_b32_e32 v26, 1, v148
	v_or_b32_e32 v25, 2, v148
	v_or_b32_e32 v24, 3, v148
	v_or_b32_e32 v15, 10, v148
	v_or_b32_e32 v14, 11, v148
	v_or_b32_e32 v13, 18, v148
	v_or_b32_e32 v12, 19, v148
	v_or_b32_e32 v11, 26, v148
	v_or_b32_e32 v10, 27, v148
	v_cvt_pk_bf16_f32 v60, v53, v51
	v_cvt_pk_bf16_f32 v61, v49, v47
	v_lshl_add_u64 v[58:59], v[58:59], 1, s[20:21]
	v_cmp_ne_u32_e64 s[0:1], 1, v31
	s_andn2_b64 vcc, exec, s[70:71]
	global_store_dwordx2 v[58:59], v[60:61], off
	s_cbranch_vccnz .LBB0_839
	v_or_b32_e32 v31, s73, v140
	v_lshl_or_b32 v58, v148, 10, v31
	v_ashrrev_i32_e32 v59, 31, v58
	v_lshl_add_u64 v[58:59], v[58:59], 2, s[22:23]
	global_store_dword v[58:59], v87, off sc1
	v_lshl_or_b32 v58, v26, 10, v31
	v_ashrrev_i32_e32 v59, 31, v58
	v_lshl_add_u64 v[58:59], v[58:59], 2, s[22:23]
	global_store_dword v[58:59], v83, off sc1
	v_lshl_or_b32 v58, v25, 10, v31
	v_ashrrev_i32_e32 v59, 31, v58
	v_lshl_add_u64 v[58:59], v[58:59], 2, s[22:23]
	global_store_dword v[58:59], v79, off sc1
	v_lshl_or_b32 v58, v24, 10, v31
	v_ashrrev_i32_e32 v59, 31, v58
	v_lshl_add_u64 v[58:59], v[58:59], 2, s[22:23]
	global_store_dword v[58:59], v75, off sc1
	v_lshl_or_b32 v58, v150, 10, v31
	v_ashrrev_i32_e32 v59, 31, v58
	v_lshl_add_u64 v[58:59], v[58:59], 2, s[22:23]
	global_store_dword v[58:59], v71, off sc1
	v_lshl_or_b32 v58, v152, 10, v31
	v_ashrrev_i32_e32 v59, 31, v58
	v_lshl_add_u64 v[58:59], v[58:59], 2, s[22:23]
	global_store_dword v[58:59], v73, off sc1
	v_lshl_or_b32 v58, v15, 10, v31
	v_ashrrev_i32_e32 v59, 31, v58
	v_lshl_add_u64 v[58:59], v[58:59], 2, s[22:23]
	global_store_dword v[58:59], v77, off sc1
	v_lshl_or_b32 v58, v14, 10, v31
	v_ashrrev_i32_e32 v59, 31, v58
	v_lshl_add_u64 v[58:59], v[58:59], 2, s[22:23]
	global_store_dword v[58:59], v69, off sc1
	v_lshl_or_b32 v58, v154, 10, v31
	v_ashrrev_i32_e32 v59, 31, v58
	v_lshl_add_u64 v[58:59], v[58:59], 2, s[22:23]
	global_store_dword v[58:59], v67, off sc1
	v_lshl_or_b32 v58, v80, 10, v31
	v_ashrrev_i32_e32 v59, 31, v58
	v_lshl_add_u64 v[58:59], v[58:59], 2, s[22:23]
	global_store_dword v[58:59], v65, off sc1
	v_lshl_or_b32 v58, v13, 10, v31
	v_ashrrev_i32_e32 v59, 31, v58
	v_lshl_add_u64 v[58:59], v[58:59], 2, s[22:23]
	global_store_dword v[58:59], v57, off sc1
	v_lshl_or_b32 v58, v12, 10, v31
	v_ashrrev_i32_e32 v59, 31, v58
	v_lshl_add_u64 v[58:59], v[58:59], 2, s[22:23]
	global_store_dword v[58:59], v55, off sc1
	v_lshl_or_b32 v58, v84, 10, v31
	v_ashrrev_i32_e32 v59, 31, v58
	v_lshl_add_u64 v[58:59], v[58:59], 2, s[22:23]
	global_store_dword v[58:59], v53, off sc1
	v_lshl_or_b32 v58, v88, 10, v31
	v_ashrrev_i32_e32 v59, 31, v58
	v_lshl_add_u64 v[58:59], v[58:59], 2, s[22:23]
	global_store_dword v[58:59], v51, off sc1
	v_lshl_or_b32 v58, v11, 10, v31
	v_ashrrev_i32_e32 v59, 31, v58
	v_lshl_add_u64 v[58:59], v[58:59], 2, s[22:23]
	global_store_dword v[58:59], v49, off sc1
	v_lshl_or_b32 v58, v10, 10, v31
	v_ashrrev_i32_e32 v59, 31, v58
	v_lshl_add_u64 v[58:59], v[58:59], 2, s[22:23]
	global_store_dword v[58:59], v47, off sc1
.LBB0_839:
	v_or_b32_e32 v58, s87, v162
	v_mul_lo_u32 v58, v58, s76
	v_or_b32_e32 v31, s75, v163
	v_add_u32_e32 v58, 0x800000, v58
	v_cndmask_b32_e64 v31, v31, v58, s[4:5]
	v_add_u32_e32 v58, v31, v27
	v_ashrrev_i32_e32 v59, 31, v58
	v_cvt_pk_bf16_f32 v60, v86, v82
	v_cvt_pk_bf16_f32 v61, v78, v74
	v_lshl_add_u64 v[58:59], v[58:59], 1, s[20:21]
	global_store_dwordx2 v[58:59], v[60:61], off
	v_add_u32_e32 v58, v31, v28
	v_ashrrev_i32_e32 v59, 31, v58
	v_cvt_pk_bf16_f32 v60, v70, v72
	v_cvt_pk_bf16_f32 v61, v76, v68
	v_lshl_add_u64 v[58:59], v[58:59], 1, s[20:21]
	global_store_dwordx2 v[58:59], v[60:61], off
	v_add_u32_e32 v58, v31, v29
	v_ashrrev_i32_e32 v59, 31, v58
	v_cvt_pk_bf16_f32 v60, v66, v64
	v_cvt_pk_bf16_f32 v61, v56, v54
	v_lshl_add_u64 v[58:59], v[58:59], 1, s[20:21]
	global_store_dwordx2 v[58:59], v[60:61], off
	v_add_u32_e32 v58, v31, v30
	v_ashrrev_i32_e32 v59, 31, v58
	v_cvt_pk_bf16_f32 v60, v52, v50
	v_cvt_pk_bf16_f32 v61, v48, v46
	v_lshl_add_u64 v[58:59], v[58:59], 1, s[20:21]
	s_and_b64 vcc, exec, s[0:1]
	global_store_dwordx2 v[58:59], v[60:61], off
	s_cbranch_vccnz .LBB0_841
	v_or_b32_e32 v31, s73, v162
	v_lshl_or_b32 v58, v148, 10, v31
	v_ashrrev_i32_e32 v59, 31, v58
	v_lshl_add_u64 v[58:59], v[58:59], 2, s[22:23]
	global_store_dword v[58:59], v86, off sc1
	v_lshl_or_b32 v58, v26, 10, v31
	v_ashrrev_i32_e32 v59, 31, v58
	v_lshl_add_u64 v[58:59], v[58:59], 2, s[22:23]
	global_store_dword v[58:59], v82, off sc1
	v_lshl_or_b32 v58, v25, 10, v31
	v_ashrrev_i32_e32 v59, 31, v58
	v_lshl_add_u64 v[58:59], v[58:59], 2, s[22:23]
	global_store_dword v[58:59], v78, off sc1
	v_lshl_or_b32 v58, v24, 10, v31
	v_ashrrev_i32_e32 v59, 31, v58
	v_lshl_add_u64 v[58:59], v[58:59], 2, s[22:23]
	global_store_dword v[58:59], v74, off sc1
	v_lshl_or_b32 v58, v150, 10, v31
	v_ashrrev_i32_e32 v59, 31, v58
	v_lshl_add_u64 v[58:59], v[58:59], 2, s[22:23]
	global_store_dword v[58:59], v70, off sc1
	v_lshl_or_b32 v58, v152, 10, v31
	v_ashrrev_i32_e32 v59, 31, v58
	v_lshl_add_u64 v[58:59], v[58:59], 2, s[22:23]
	global_store_dword v[58:59], v72, off sc1
	v_lshl_or_b32 v58, v15, 10, v31
	v_ashrrev_i32_e32 v59, 31, v58
	v_lshl_add_u64 v[58:59], v[58:59], 2, s[22:23]
	global_store_dword v[58:59], v76, off sc1
	v_lshl_or_b32 v58, v14, 10, v31
	v_ashrrev_i32_e32 v59, 31, v58
	v_lshl_add_u64 v[58:59], v[58:59], 2, s[22:23]
	global_store_dword v[58:59], v68, off sc1
	v_lshl_or_b32 v58, v154, 10, v31
	v_ashrrev_i32_e32 v59, 31, v58
	v_lshl_add_u64 v[58:59], v[58:59], 2, s[22:23]
	global_store_dword v[58:59], v66, off sc1
	v_lshl_or_b32 v58, v80, 10, v31
	v_ashrrev_i32_e32 v59, 31, v58
	v_lshl_add_u64 v[58:59], v[58:59], 2, s[22:23]
	global_store_dword v[58:59], v64, off sc1
	v_lshl_or_b32 v58, v13, 10, v31
	v_ashrrev_i32_e32 v59, 31, v58
	v_lshl_add_u64 v[58:59], v[58:59], 2, s[22:23]
	global_store_dword v[58:59], v56, off sc1
	v_lshl_or_b32 v58, v12, 10, v31
	v_ashrrev_i32_e32 v59, 31, v58
	v_lshl_add_u64 v[58:59], v[58:59], 2, s[22:23]
	global_store_dword v[58:59], v54, off sc1
	v_lshl_or_b32 v58, v84, 10, v31
	v_ashrrev_i32_e32 v59, 31, v58
	v_lshl_add_u64 v[58:59], v[58:59], 2, s[22:23]
	global_store_dword v[58:59], v52, off sc1
	v_lshl_or_b32 v58, v88, 10, v31
	v_ashrrev_i32_e32 v59, 31, v58
	v_lshl_add_u64 v[58:59], v[58:59], 2, s[22:23]
	global_store_dword v[58:59], v50, off sc1
	v_lshl_or_b32 v58, v11, 10, v31
	v_ashrrev_i32_e32 v59, 31, v58
	v_lshl_add_u64 v[58:59], v[58:59], 2, s[22:23]
	global_store_dword v[58:59], v48, off sc1
	v_lshl_or_b32 v58, v10, 10, v31
	v_ashrrev_i32_e32 v59, 31, v58
	v_lshl_add_u64 v[58:59], v[58:59], 2, s[22:23]
	global_store_dword v[58:59], v46, off sc1
.LBB0_841:
	v_or_b32_e32 v58, s87, v164
	v_mul_lo_u32 v58, v58, s76
	v_or_b32_e32 v31, s75, v165
	v_add_u32_e32 v58, 0x800000, v58
	v_cndmask_b32_e64 v31, v31, v58, s[4:5]
	v_add_u32_e32 v58, v31, v27
	v_ashrrev_i32_e32 v59, 31, v58
	v_cvt_pk_bf16_f32 v60, v45, v43
	v_cvt_pk_bf16_f32 v61, v41, v39
	v_lshl_add_u64 v[58:59], v[58:59], 1, s[20:21]
	global_store_dwordx2 v[58:59], v[60:61], off
	v_add_u32_e32 v58, v31, v28
	v_ashrrev_i32_e32 v59, 31, v58
	v_cvt_pk_bf16_f32 v60, v37, v35
	v_cvt_pk_bf16_f32 v61, v33, v23
	v_lshl_add_u64 v[58:59], v[58:59], 1, s[20:21]
	global_store_dwordx2 v[58:59], v[60:61], off
	v_add_u32_e32 v58, v31, v29
	v_ashrrev_i32_e32 v59, 31, v58
	v_cvt_pk_bf16_f32 v60, v21, v19
	v_cvt_pk_bf16_f32 v61, v17, v9
	v_lshl_add_u64 v[58:59], v[58:59], 1, s[20:21]
	global_store_dwordx2 v[58:59], v[60:61], off
	v_add_u32_e32 v58, v31, v30
	v_ashrrev_i32_e32 v59, 31, v58
	v_cvt_pk_bf16_f32 v60, v7, v5
	v_cvt_pk_bf16_f32 v61, v3, v1
	v_lshl_add_u64 v[58:59], v[58:59], 1, s[20:21]
	s_and_b64 vcc, exec, s[0:1]
	global_store_dwordx2 v[58:59], v[60:61], off
	s_cbranch_vccnz .LBB0_843
	v_or_b32_e32 v31, s73, v164
	v_lshl_or_b32 v58, v148, 10, v31
	v_ashrrev_i32_e32 v59, 31, v58
	v_lshl_add_u64 v[58:59], v[58:59], 2, s[22:23]
	global_store_dword v[58:59], v45, off sc1
	v_lshl_or_b32 v58, v26, 10, v31
	v_ashrrev_i32_e32 v59, 31, v58
	v_lshl_add_u64 v[58:59], v[58:59], 2, s[22:23]
	global_store_dword v[58:59], v43, off sc1
	v_lshl_or_b32 v58, v25, 10, v31
	v_ashrrev_i32_e32 v59, 31, v58
	v_lshl_add_u64 v[58:59], v[58:59], 2, s[22:23]
	global_store_dword v[58:59], v41, off sc1
	v_lshl_or_b32 v58, v24, 10, v31
	v_ashrrev_i32_e32 v59, 31, v58
	v_lshl_add_u64 v[58:59], v[58:59], 2, s[22:23]
	global_store_dword v[58:59], v39, off sc1
	v_lshl_or_b32 v58, v150, 10, v31
	v_ashrrev_i32_e32 v59, 31, v58
	v_lshl_add_u64 v[58:59], v[58:59], 2, s[22:23]
	global_store_dword v[58:59], v37, off sc1
	v_lshl_or_b32 v58, v152, 10, v31
	v_ashrrev_i32_e32 v59, 31, v58
	v_lshl_add_u64 v[58:59], v[58:59], 2, s[22:23]
	global_store_dword v[58:59], v35, off sc1
	v_lshl_or_b32 v58, v15, 10, v31
	v_ashrrev_i32_e32 v59, 31, v58
	v_lshl_add_u64 v[58:59], v[58:59], 2, s[22:23]
	global_store_dword v[58:59], v33, off sc1
	v_lshl_or_b32 v58, v14, 10, v31
	v_ashrrev_i32_e32 v59, 31, v58
	v_lshl_add_u64 v[58:59], v[58:59], 2, s[22:23]
	global_store_dword v[58:59], v23, off sc1
	v_lshl_or_b32 v58, v154, 10, v31
	v_ashrrev_i32_e32 v59, 31, v58
	v_lshl_add_u64 v[58:59], v[58:59], 2, s[22:23]
	global_store_dword v[58:59], v21, off sc1
	v_lshl_or_b32 v58, v80, 10, v31
	v_ashrrev_i32_e32 v59, 31, v58
	v_lshl_add_u64 v[58:59], v[58:59], 2, s[22:23]
	global_store_dword v[58:59], v19, off sc1
	v_lshl_or_b32 v58, v13, 10, v31
	v_ashrrev_i32_e32 v59, 31, v58
	v_lshl_add_u64 v[58:59], v[58:59], 2, s[22:23]
	global_store_dword v[58:59], v17, off sc1
	v_lshl_or_b32 v58, v12, 10, v31
	v_ashrrev_i32_e32 v59, 31, v58
	v_lshl_add_u64 v[58:59], v[58:59], 2, s[22:23]
	global_store_dword v[58:59], v9, off sc1
	v_lshl_or_b32 v58, v84, 10, v31
	v_ashrrev_i32_e32 v59, 31, v58
	v_lshl_add_u64 v[58:59], v[58:59], 2, s[22:23]
	global_store_dword v[58:59], v7, off sc1
	v_lshl_or_b32 v58, v88, 10, v31
	v_ashrrev_i32_e32 v59, 31, v58
	v_lshl_add_u64 v[58:59], v[58:59], 2, s[22:23]
	global_store_dword v[58:59], v5, off sc1
	v_lshl_or_b32 v58, v11, 10, v31
	v_ashrrev_i32_e32 v59, 31, v58
	v_lshl_add_u64 v[58:59], v[58:59], 2, s[22:23]
	global_store_dword v[58:59], v3, off sc1
	v_lshl_or_b32 v58, v10, 10, v31
	v_ashrrev_i32_e32 v59, 31, v58
	v_lshl_add_u64 v[58:59], v[58:59], 2, s[22:23]
	global_store_dword v[58:59], v1, off sc1
.LBB0_843:
	v_or_b32_e32 v58, s87, v166
	v_mul_lo_u32 v58, v58, s76
	v_or_b32_e32 v31, s75, v167
	v_add_u32_e32 v58, 0x800000, v58
	v_cndmask_b32_e64 v31, v31, v58, s[4:5]
	v_add_u32_e32 v58, v31, v27
	v_ashrrev_i32_e32 v59, 31, v58
	v_cvt_pk_bf16_f32 v60, v44, v42
	v_cvt_pk_bf16_f32 v61, v40, v38
	v_lshl_add_u64 v[58:59], v[58:59], 1, s[20:21]
	global_store_dwordx2 v[58:59], v[60:61], off
	v_add_u32_e32 v58, v31, v28
	v_ashrrev_i32_e32 v59, 31, v58
	v_add_u32_e32 v28, v31, v29
	v_cvt_pk_bf16_f32 v60, v36, v34
	v_cvt_pk_bf16_f32 v61, v32, v22
	v_lshl_add_u64 v[58:59], v[58:59], 1, s[20:21]
	v_ashrrev_i32_e32 v29, 31, v28
	global_store_dwordx2 v[58:59], v[60:61], off
	v_cvt_pk_bf16_f32 v58, v20, v18
	v_cvt_pk_bf16_f32 v59, v16, v8
	v_lshl_add_u64 v[28:29], v[28:29], 1, s[20:21]
	global_store_dwordx2 v[28:29], v[58:59], off
	v_add_u32_e32 v28, v31, v30
	v_ashrrev_i32_e32 v29, 31, v28
	v_cvt_pk_bf16_f32 v30, v6, v4
	v_cvt_pk_bf16_f32 v31, v2, v0
	v_lshl_add_u64 v[28:29], v[28:29], 1, s[20:21]
	s_and_b64 vcc, exec, s[0:1]
	global_store_dwordx2 v[28:29], v[30:31], off
	s_cbranch_vccnz .LBB0_845
	v_or_b32_e32 v30, s73, v166
	v_lshl_or_b32 v26, v26, 10, v30
	v_ashrrev_i32_e32 v27, 31, v26
	v_lshl_add_u64 v[26:27], v[26:27], 2, s[22:23]
	v_lshl_or_b32 v24, v24, 10, v30
	global_store_dword v[26:27], v42, off sc1
	v_lshl_or_b32 v26, v25, 10, v30
	v_ashrrev_i32_e32 v25, 31, v24
	v_lshl_add_u64 v[24:25], v[24:25], 2, s[22:23]
	global_store_dword v[24:25], v38, off sc1
	v_lshl_or_b32 v24, v150, 10, v30
	v_ashrrev_i32_e32 v25, 31, v24
	v_lshl_add_u64 v[24:25], v[24:25], 2, s[22:23]
	global_store_dword v[24:25], v36, off sc1
	v_lshl_or_b32 v24, v152, 10, v30
	v_ashrrev_i32_e32 v25, 31, v24
	v_lshl_add_u64 v[24:25], v[24:25], 2, s[22:23]
	v_lshl_or_b32 v14, v14, 10, v30
	global_store_dword v[24:25], v34, off sc1
	v_lshl_or_b32 v24, v15, 10, v30
	v_ashrrev_i32_e32 v15, 31, v14
	v_lshl_add_u64 v[14:15], v[14:15], 2, s[22:23]
	global_store_dword v[14:15], v22, off sc1
	v_lshl_or_b32 v14, v154, 10, v30
	v_ashrrev_i32_e32 v15, 31, v14
	v_lshl_add_u64 v[14:15], v[14:15], 2, s[22:23]
	global_store_dword v[14:15], v20, off sc1
	v_lshl_or_b32 v14, v80, 10, v30
	v_ashrrev_i32_e32 v15, 31, v14
	v_lshl_add_u64 v[14:15], v[14:15], 2, s[22:23]
	v_lshl_or_b32 v12, v12, 10, v30
	global_store_dword v[14:15], v18, off sc1
	v_lshl_or_b32 v14, v13, 10, v30
	v_ashrrev_i32_e32 v13, 31, v12
	v_lshl_add_u64 v[12:13], v[12:13], 2, s[22:23]
	global_store_dword v[12:13], v8, off sc1
	v_lshl_or_b32 v12, v84, 10, v30
	v_ashrrev_i32_e32 v13, 31, v12
	v_lshl_add_u64 v[12:13], v[12:13], 2, s[22:23]
	global_store_dword v[12:13], v6, off sc1
	v_lshl_or_b32 v12, v88, 10, v30
	v_ashrrev_i32_e32 v13, 31, v12
	v_lshl_add_u64 v[12:13], v[12:13], 2, s[22:23]
	v_lshl_or_b32 v28, v148, 10, v30
	global_store_dword v[12:13], v4, off sc1
	v_lshl_or_b32 v12, v11, 10, v30
	v_lshl_or_b32 v10, v10, 10, v30
	v_ashrrev_i32_e32 v29, 31, v28
	v_ashrrev_i32_e32 v27, 31, v26
	v_ashrrev_i32_e32 v25, 31, v24
	v_ashrrev_i32_e32 v15, 31, v14
	v_ashrrev_i32_e32 v13, 31, v12
	v_ashrrev_i32_e32 v11, 31, v10
	v_lshl_add_u64 v[28:29], v[28:29], 2, s[22:23]
	v_lshl_add_u64 v[26:27], v[26:27], 2, s[22:23]
	v_lshl_add_u64 v[24:25], v[24:25], 2, s[22:23]
	v_lshl_add_u64 v[14:15], v[14:15], 2, s[22:23]
	v_lshl_add_u64 v[12:13], v[12:13], 2, s[22:23]
	v_lshl_add_u64 v[10:11], v[10:11], 2, s[22:23]
	global_store_dword v[28:29], v44, off sc1
	global_store_dword v[26:27], v40, off sc1
	global_store_dword v[24:25], v32, off sc1
	global_store_dword v[14:15], v16, off sc1
	global_store_dword v[12:13], v2, off sc1
	global_store_dword v[10:11], v0, off sc1

.LBB0_851:
	v_pk_mul_f32 v[24:25], v[82:83], v[82:83]
	v_cvt_pk_bf16_f32 v28, v14, s0
	v_add_f32_e32 v13, v25, v24
	ds_bpermute_b32 v24, v100, v13
	s_cmp_lt_u32 s86, 8
	s_cselect_b64 s[4:5], -1, 0
	s_and_b64 s[4:5], s[4:5], exec
	s_cselect_b32 s8, s68, s74
	s_waitcnt lgkmcnt(0)
	v_add_f32_e32 v13, v13, v24
	ds_bpermute_b32 v24, v101, v13
	s_cselect_b32 s4, s85, 0xdf9f000
	s_add_u32 s4, s14, s4
	s_addc_u32 s5, s15, 0
	v_cvt_pk_bf16_f32 v25, v15, s0
	s_waitcnt lgkmcnt(0)
	v_add_f32_e32 v13, v13, v24
	ds_bpermute_b32 v24, v102, v13
	v_add_u32_e32 v15, s68, v168
	s_and_b64 vcc, exec, s[70:71]
	s_waitcnt lgkmcnt(0)
	v_add_f32_e32 v13, v13, v24
	ds_bpermute_b32 v14, v103, v13
	v_add_lshl_u32 v24, s8, v160, 10
	v_or_b32_e32 v26, v24, v134
	v_ashrrev_i32_e32 v27, 31, v26
	v_lshl_add_u64 v[26:27], v[26:27], 1, s[4:5]
	s_waitcnt lgkmcnt(0)
	v_add_f32_e32 v13, v13, v14
	ds_bpermute_b32 v14, v104, v13
	global_store_short v[26:27], v25, off
	global_store_short v[26:27], v28, off offset:64
	s_waitcnt lgkmcnt(0)
	v_add_f32_e32 v13, v13, v14
	v_fmamk_f32 v13, v13, 0x3c800000, v196
	v_rsq_f32_e32 v14, v13
	s_nop 0
	v_pk_mul_f32 v[26:27], v[10:11], v[14:15] op_sel_hi:[1,0]
	s_nop 0
	v_pk_mul_f32 v[28:29], v[82:83], v[26:27]
	s_cbranch_vccz .LBB0_853
	v_lshl_or_b32 v26, v15, 10, v134
	v_ashrrev_i32_e32 v27, 31, v26
	v_lshl_add_u64 v[26:27], v[26:27], 2, s[26:27]
	global_store_dword v[26:27], v29, off sc1
	global_store_dword v[26:27], v28, off offset:128 sc1

.LBB0_855:
	v_pk_mul_f32 v[30:31], v[78:79], v[78:79]
	v_cvt_pk_bf16_f32 v58, v28, s0
	v_add_f32_e32 v13, v31, v30
	ds_bpermute_b32 v14, v100, v13
	v_cvt_pk_bf16_f32 v27, v29, s0
	v_add_u32_e32 v29, s68, v169
	s_and_b64 vcc, exec, s[70:71]
	s_waitcnt lgkmcnt(0)
	v_add_f32_e32 v13, v13, v14
	ds_bpermute_b32 v14, v101, v13
	s_waitcnt lgkmcnt(0)
	v_add_f32_e32 v13, v13, v14
	ds_bpermute_b32 v14, v102, v13
	s_waitcnt lgkmcnt(0)
	v_add_f32_e32 v13, v13, v14
	ds_bpermute_b32 v25, v103, v13
	v_add_lshl_u32 v14, s8, v168, 10
	v_or_b32_e32 v30, v14, v134
	v_ashrrev_i32_e32 v31, 31, v30
	v_lshl_add_u64 v[30:31], v[30:31], 1, s[4:5]
	s_waitcnt lgkmcnt(0)
	v_add_f32_e32 v13, v13, v25
	ds_bpermute_b32 v25, v104, v13
	global_store_short v[30:31], v27, off
	global_store_short v[30:31], v58, off offset:64
	s_waitcnt lgkmcnt(0)
	v_add_f32_e32 v13, v13, v25
	v_fmamk_f32 v13, v13, 0x3c800000, v196
	v_rsq_f32_e32 v28, v13
	s_nop 0
	v_pk_mul_f32 v[30:31], v[10:11], v[28:29] op_sel_hi:[1,0]
	s_nop 0
	v_pk_mul_f32 v[58:59], v[78:79], v[30:31]
	s_cbranch_vccz .LBB0_857
	v_lshl_or_b32 v30, v29, 10, v134
	v_ashrrev_i32_e32 v31, 31, v30
	v_lshl_add_u64 v[30:31], v[30:31], 2, s[26:27]
	global_store_dword v[30:31], v59, off sc1
	global_store_dword v[30:31], v58, off offset:128 sc1

.LBB0_859:
	v_pk_mul_f32 v[60:61], v[74:75], v[74:75]
	v_add_lshl_u32 v28, s8, v169, 10
	v_add_f32_e32 v13, v61, v60
	ds_bpermute_b32 v25, v100, v13
	v_cvt_pk_bf16_f32 v31, v58, s0
	v_or_b32_e32 v60, v28, v134
	v_ashrrev_i32_e32 v61, 31, v60
	v_cvt_pk_bf16_f32 v27, v59, s0
	s_waitcnt lgkmcnt(0)
	v_add_f32_e32 v13, v13, v25
	ds_bpermute_b32 v25, v101, v13
	v_add_u32_e32 v59, s68, v170
	v_lshl_add_u64 v[60:61], v[60:61], 1, s[4:5]
	global_store_short v[60:61], v27, off
	global_store_short v[60:61], v31, off offset:64
	s_and_b64 vcc, exec, s[70:71]
	s_waitcnt lgkmcnt(0)
	v_add_f32_e32 v13, v13, v25
	ds_bpermute_b32 v25, v102, v13
	s_waitcnt lgkmcnt(0)
	v_add_f32_e32 v13, v13, v25
	ds_bpermute_b32 v25, v103, v13
	s_waitcnt lgkmcnt(0)
	v_add_f32_e32 v13, v13, v25
	ds_bpermute_b32 v25, v104, v13
	s_waitcnt lgkmcnt(0)
	v_add_f32_e32 v13, v13, v25
	v_fmamk_f32 v13, v13, 0x3c800000, v196
	v_rsq_f32_e32 v58, v13
	s_nop 0
	v_pk_mul_f32 v[60:61], v[10:11], v[58:59] op_sel_hi:[1,0]
	s_nop 0
	v_pk_mul_f32 v[62:63], v[74:75], v[60:61]
	s_cbranch_vccz .LBB0_861
	v_lshl_or_b32 v60, v59, 10, v134
	v_ashrrev_i32_e32 v61, 31, v60
	v_lshl_add_u64 v[60:61], v[60:61], 2, s[26:27]
	global_store_dword v[60:61], v63, off sc1
	global_store_dword v[60:61], v62, off offset:128 sc1

.LBB0_863:
	v_pk_mul_f32 v[74:75], v[70:71], v[70:71]
	v_add_lshl_u32 v58, s8, v170, 10
	v_add_f32_e32 v13, v75, v74
	ds_bpermute_b32 v25, v100, v13
	v_cvt_pk_bf16_f32 v31, v62, s0
	v_or_b32_e32 v74, v58, v134
	v_ashrrev_i32_e32 v75, 31, v74
	v_cvt_pk_bf16_f32 v27, v63, s0
	s_waitcnt lgkmcnt(0)
	v_add_f32_e32 v13, v13, v25
	ds_bpermute_b32 v25, v101, v13
	v_add_u32_e32 v63, s68, v171
	v_lshl_add_u64 v[74:75], v[74:75], 1, s[4:5]
	global_store_short v[74:75], v27, off
	global_store_short v[74:75], v31, off offset:64
	s_and_b64 vcc, exec, s[70:71]
	s_waitcnt lgkmcnt(0)
	v_add_f32_e32 v13, v13, v25
	ds_bpermute_b32 v25, v102, v13
	s_waitcnt lgkmcnt(0)
	v_add_f32_e32 v13, v13, v25
	ds_bpermute_b32 v25, v103, v13
	s_waitcnt lgkmcnt(0)
	v_add_f32_e32 v13, v13, v25
	ds_bpermute_b32 v25, v104, v13
	s_waitcnt lgkmcnt(0)
	v_add_f32_e32 v13, v13, v25
	v_fmamk_f32 v13, v13, 0x3c800000, v196
	v_rsq_f32_e32 v62, v13
	s_nop 0
	v_pk_mul_f32 v[74:75], v[10:11], v[62:63] op_sel_hi:[1,0]
	s_nop 0
	v_pk_mul_f32 v[74:75], v[70:71], v[74:75]
	s_cbranch_vccz .LBB0_865
	v_lshl_or_b32 v70, v63, 10, v134
	v_ashrrev_i32_e32 v71, 31, v70
	v_lshl_add_u64 v[70:71], v[70:71], 2, s[26:27]
	global_store_dword v[70:71], v75, off sc1
	global_store_dword v[70:71], v74, off offset:128 sc1

.LBB0_867:
	v_pk_mul_f32 v[78:79], v[72:73], v[72:73]
	v_add_lshl_u32 v62, s8, v171, 10
	v_add_f32_e32 v13, v79, v78
	ds_bpermute_b32 v25, v100, v13
	v_cvt_pk_bf16_f32 v31, v74, s0
	v_or_b32_e32 v74, v62, v134
	v_cvt_pk_bf16_f32 v27, v75, s0
	v_ashrrev_i32_e32 v75, 31, v74
	s_waitcnt lgkmcnt(0)
	v_add_f32_e32 v13, v13, v25
	ds_bpermute_b32 v25, v101, v13
	v_lshl_add_u64 v[74:75], v[74:75], 1, s[4:5]
	global_store_short v[74:75], v27, off
	global_store_short v[74:75], v31, off offset:64
	s_and_b64 vcc, exec, s[70:71]
	v_add_u32_e32 v105, s68, v172
	s_waitcnt lgkmcnt(0)
	v_add_f32_e32 v13, v13, v25
	ds_bpermute_b32 v25, v102, v13
	s_waitcnt lgkmcnt(0)
	v_add_f32_e32 v13, v13, v25
	ds_bpermute_b32 v25, v103, v13
	s_waitcnt lgkmcnt(0)
	v_add_f32_e32 v13, v13, v25
	ds_bpermute_b32 v25, v104, v13
	s_waitcnt lgkmcnt(0)
	v_add_f32_e32 v13, v13, v25
	v_fmamk_f32 v13, v13, 0x3c800000, v196
	v_rsq_f32_e32 v78, v13
	s_nop 0
	v_pk_mul_f32 v[74:75], v[10:11], v[78:79] op_sel_hi:[1,0]
	s_nop 0
	v_pk_mul_f32 v[78:79], v[72:73], v[74:75]
	s_cbranch_vccz .LBB0_869
	v_lshl_or_b32 v72, v105, 10, v134
	v_ashrrev_i32_e32 v73, 31, v72
	v_lshl_add_u64 v[72:73], v[72:73], 2, s[26:27]
	global_store_dword v[72:73], v79, off sc1
	global_store_dword v[72:73], v78, off offset:128 sc1

.LBB0_871:
	v_pk_mul_f32 v[72:73], v[76:77], v[76:77]
	v_cvt_pk_bf16_f32 v31, v78, s0
	v_add_f32_e32 v13, v73, v72
	ds_bpermute_b32 v25, v100, v13
	v_add_lshl_u32 v72, s8, v172, 10
	v_or_b32_e32 v78, v72, v134
	v_cvt_pk_bf16_f32 v27, v79, s0
	v_ashrrev_i32_e32 v79, 31, v78
	s_waitcnt lgkmcnt(0)
	v_add_f32_e32 v13, v13, v25
	ds_bpermute_b32 v25, v101, v13
	v_lshl_add_u64 v[78:79], v[78:79], 1, s[4:5]
	global_store_short v[78:79], v27, off
	global_store_short v[78:79], v31, off offset:64
	s_and_b64 vcc, exec, s[70:71]
	v_add_u32_e32 v106, s68, v173
	s_waitcnt lgkmcnt(0)
	v_add_f32_e32 v13, v13, v25
	ds_bpermute_b32 v25, v102, v13
	s_waitcnt lgkmcnt(0)
	v_add_f32_e32 v13, v13, v25
	ds_bpermute_b32 v25, v103, v13
	s_waitcnt lgkmcnt(0)
	v_add_f32_e32 v13, v13, v25
	ds_bpermute_b32 v25, v104, v13
	s_waitcnt lgkmcnt(0)
	v_add_f32_e32 v13, v13, v25
	v_fmamk_f32 v13, v13, 0x3c800000, v196
	v_rsq_f32_e32 v80, v13
	s_nop 0
	v_pk_mul_f32 v[78:79], v[10:11], v[80:81] op_sel_hi:[1,0]
	s_nop 0
	v_pk_mul_f32 v[80:81], v[76:77], v[78:79]
	s_cbranch_vccz .LBB0_873
	v_lshl_or_b32 v76, v106, 10, v134
	v_ashrrev_i32_e32 v77, 31, v76
	v_lshl_add_u64 v[76:77], v[76:77], 2, s[26:27]
	global_store_dword v[76:77], v81, off sc1
	global_store_dword v[76:77], v80, off offset:128 sc1

.LBB0_875:
	v_pk_mul_f32 v[76:77], v[68:69], v[68:69]
	v_cvt_pk_bf16_f32 v31, v80, s0
	v_add_f32_e32 v13, v77, v76
	ds_bpermute_b32 v25, v100, v13
	v_add_lshl_u32 v76, s8, v173, 10
	v_or_b32_e32 v80, v76, v134
	v_cvt_pk_bf16_f32 v27, v81, s0
	v_ashrrev_i32_e32 v81, 31, v80
	s_waitcnt lgkmcnt(0)
	v_add_f32_e32 v13, v13, v25
	ds_bpermute_b32 v25, v101, v13
	v_lshl_add_u64 v[80:81], v[80:81], 1, s[4:5]
	global_store_short v[80:81], v27, off
	global_store_short v[80:81], v31, off offset:64
	s_and_b64 vcc, exec, s[70:71]
	v_add_u32_e32 v107, s68, v174
	s_waitcnt lgkmcnt(0)
	v_add_f32_e32 v13, v13, v25
	ds_bpermute_b32 v25, v102, v13
	s_waitcnt lgkmcnt(0)
	v_add_f32_e32 v13, v13, v25
	ds_bpermute_b32 v25, v103, v13
	s_waitcnt lgkmcnt(0)
	v_add_f32_e32 v13, v13, v25
	ds_bpermute_b32 v25, v104, v13
	s_waitcnt lgkmcnt(0)
	v_add_f32_e32 v13, v13, v25
	v_fmamk_f32 v13, v13, 0x3c800000, v196
	v_rsq_f32_e32 v82, v13
	s_nop 0
	v_pk_mul_f32 v[80:81], v[10:11], v[82:83] op_sel_hi:[1,0]
	s_nop 0
	v_pk_mul_f32 v[82:83], v[68:69], v[80:81]
	s_cbranch_vccz .LBB0_877
	v_lshl_or_b32 v68, v107, 10, v134
	v_ashrrev_i32_e32 v69, 31, v68
	v_lshl_add_u64 v[68:69], v[68:69], 2, s[26:27]
	global_store_dword v[68:69], v83, off sc1
	global_store_dword v[68:69], v82, off offset:128 sc1

.LBB0_879:
	v_pk_mul_f32 v[68:69], v[66:67], v[66:67]
	v_cvt_pk_bf16_f32 v31, v82, s0
	v_add_f32_e32 v13, v69, v68
	ds_bpermute_b32 v25, v100, v13
	v_add_lshl_u32 v68, s8, v174, 10
	v_or_b32_e32 v82, v68, v134
	v_cvt_pk_bf16_f32 v27, v83, s0
	v_ashrrev_i32_e32 v83, 31, v82
	s_waitcnt lgkmcnt(0)
	v_add_f32_e32 v13, v13, v25
	ds_bpermute_b32 v25, v101, v13
	v_lshl_add_u64 v[82:83], v[82:83], 1, s[4:5]
	global_store_short v[82:83], v27, off
	global_store_short v[82:83], v31, off offset:64
	s_and_b64 vcc, exec, s[70:71]
	v_add_u32_e32 v108, s68, v175
	s_waitcnt lgkmcnt(0)
	v_add_f32_e32 v13, v13, v25
	ds_bpermute_b32 v25, v102, v13
	s_waitcnt lgkmcnt(0)
	v_add_f32_e32 v13, v13, v25
	ds_bpermute_b32 v25, v103, v13
	s_waitcnt lgkmcnt(0)
	v_add_f32_e32 v13, v13, v25
	ds_bpermute_b32 v25, v104, v13
	s_waitcnt lgkmcnt(0)
	v_add_f32_e32 v13, v13, v25
	v_fmamk_f32 v13, v13, 0x3c800000, v196
	v_rsq_f32_e32 v84, v13
	s_nop 0
	v_pk_mul_f32 v[82:83], v[10:11], v[84:85] op_sel_hi:[1,0]
	s_nop 0
	v_pk_mul_f32 v[84:85], v[66:67], v[82:83]
	s_cbranch_vccz .LBB0_881
	v_lshl_or_b32 v66, v108, 10, v134
	v_ashrrev_i32_e32 v67, 31, v66
	v_lshl_add_u64 v[66:67], v[66:67], 2, s[26:27]
	global_store_dword v[66:67], v85, off sc1
	global_store_dword v[66:67], v84, off offset:128 sc1

.LBB0_883:
	v_pk_mul_f32 v[66:67], v[64:65], v[64:65]
	v_cvt_pk_bf16_f32 v31, v84, s0
	v_add_f32_e32 v13, v67, v66
	ds_bpermute_b32 v25, v100, v13
	v_add_lshl_u32 v66, s8, v175, 10
	v_or_b32_e32 v84, v66, v134
	v_cvt_pk_bf16_f32 v27, v85, s0
	v_ashrrev_i32_e32 v85, 31, v84
	s_waitcnt lgkmcnt(0)
	v_add_f32_e32 v13, v13, v25
	ds_bpermute_b32 v25, v101, v13
	v_lshl_add_u64 v[84:85], v[84:85], 1, s[4:5]
	global_store_short v[84:85], v27, off
	global_store_short v[84:85], v31, off offset:64
	s_and_b64 vcc, exec, s[70:71]
	v_add_u32_e32 v109, s68, v176
	s_waitcnt lgkmcnt(0)
	v_add_f32_e32 v13, v13, v25
	ds_bpermute_b32 v25, v102, v13
	s_waitcnt lgkmcnt(0)
	v_add_f32_e32 v13, v13, v25
	ds_bpermute_b32 v25, v103, v13
	s_waitcnt lgkmcnt(0)
	v_add_f32_e32 v13, v13, v25
	ds_bpermute_b32 v25, v104, v13
	s_waitcnt lgkmcnt(0)
	v_add_f32_e32 v13, v13, v25
	v_fmamk_f32 v13, v13, 0x3c800000, v196
	v_rsq_f32_e32 v86, v13
	s_nop 0
	v_pk_mul_f32 v[84:85], v[10:11], v[86:87] op_sel_hi:[1,0]
	s_nop 0
	v_pk_mul_f32 v[86:87], v[64:65], v[84:85]
	s_cbranch_vccz .LBB0_885
	v_lshl_or_b32 v64, v109, 10, v134
	v_ashrrev_i32_e32 v65, 31, v64
	v_lshl_add_u64 v[64:65], v[64:65], 2, s[26:27]
	global_store_dword v[64:65], v87, off sc1
	global_store_dword v[64:65], v86, off offset:128 sc1

.LBB0_887:
	v_pk_mul_f32 v[64:65], v[56:57], v[56:57]
	v_cvt_pk_bf16_f32 v31, v86, s0
	v_add_f32_e32 v13, v65, v64
	ds_bpermute_b32 v25, v100, v13
	v_add_lshl_u32 v64, s8, v176, 10
	v_or_b32_e32 v86, v64, v134
	v_cvt_pk_bf16_f32 v27, v87, s0
	v_ashrrev_i32_e32 v87, 31, v86
	s_waitcnt lgkmcnt(0)
	v_add_f32_e32 v13, v13, v25
	ds_bpermute_b32 v25, v101, v13
	v_lshl_add_u64 v[86:87], v[86:87], 1, s[4:5]
	global_store_short v[86:87], v27, off
	global_store_short v[86:87], v31, off offset:64
	s_and_b64 vcc, exec, s[70:71]
	v_add_u32_e32 v110, s68, v177
	s_waitcnt lgkmcnt(0)
	v_add_f32_e32 v13, v13, v25
	ds_bpermute_b32 v25, v102, v13
	s_waitcnt lgkmcnt(0)
	v_add_f32_e32 v13, v13, v25
	ds_bpermute_b32 v25, v103, v13
	s_waitcnt lgkmcnt(0)
	v_add_f32_e32 v13, v13, v25
	ds_bpermute_b32 v25, v104, v13
	s_waitcnt lgkmcnt(0)
	v_add_f32_e32 v13, v13, v25
	v_fmamk_f32 v13, v13, 0x3c800000, v196
	v_rsq_f32_e32 v88, v13
	s_nop 0
	v_pk_mul_f32 v[86:87], v[10:11], v[88:89] op_sel_hi:[1,0]
	s_nop 0
	v_pk_mul_f32 v[88:89], v[56:57], v[86:87]
	s_cbranch_vccz .LBB0_889
	v_lshl_or_b32 v56, v110, 10, v134
	v_ashrrev_i32_e32 v57, 31, v56
	v_lshl_add_u64 v[56:57], v[56:57], 2, s[26:27]
	global_store_dword v[56:57], v89, off sc1
	global_store_dword v[56:57], v88, off offset:128 sc1

.LBB0_891:
	v_pk_mul_f32 v[56:57], v[54:55], v[54:55]
	v_cvt_pk_bf16_f32 v31, v88, s0
	v_add_f32_e32 v13, v57, v56
	ds_bpermute_b32 v25, v100, v13
	v_add_lshl_u32 v56, s8, v177, 10
	v_or_b32_e32 v88, v56, v134
	v_cvt_pk_bf16_f32 v27, v89, s0
	v_ashrrev_i32_e32 v89, 31, v88
	s_waitcnt lgkmcnt(0)
	v_add_f32_e32 v13, v13, v25
	ds_bpermute_b32 v25, v101, v13
	v_lshl_add_u64 v[88:89], v[88:89], 1, s[4:5]
	global_store_short v[88:89], v27, off
	global_store_short v[88:89], v31, off offset:64
	s_and_b64 vcc, exec, s[70:71]
	v_add_u32_e32 v111, s68, v178
	s_waitcnt lgkmcnt(0)
	v_add_f32_e32 v13, v13, v25
	ds_bpermute_b32 v25, v102, v13
	s_waitcnt lgkmcnt(0)
	v_add_f32_e32 v13, v13, v25
	ds_bpermute_b32 v25, v103, v13
	s_waitcnt lgkmcnt(0)
	v_add_f32_e32 v13, v13, v25
	ds_bpermute_b32 v25, v104, v13
	s_waitcnt lgkmcnt(0)
	v_add_f32_e32 v13, v13, v25
	v_fmamk_f32 v13, v13, 0x3c800000, v196
	v_rsq_f32_e32 v90, v13
	s_nop 0
	v_pk_mul_f32 v[88:89], v[10:11], v[90:91] op_sel_hi:[1,0]
	s_nop 0
	v_pk_mul_f32 v[90:91], v[54:55], v[88:89]
	s_cbranch_vccz .LBB0_893
	v_lshl_or_b32 v54, v111, 10, v134
	v_ashrrev_i32_e32 v55, 31, v54
	v_lshl_add_u64 v[54:55], v[54:55], 2, s[26:27]
	global_store_dword v[54:55], v91, off sc1
	global_store_dword v[54:55], v90, off offset:128 sc1

.LBB0_895:
	v_pk_mul_f32 v[54:55], v[52:53], v[52:53]
	v_cvt_pk_bf16_f32 v31, v90, s0
	v_add_f32_e32 v13, v55, v54
	ds_bpermute_b32 v25, v100, v13
	v_add_lshl_u32 v54, s8, v178, 10
	v_or_b32_e32 v90, v54, v134
	v_cvt_pk_bf16_f32 v27, v91, s0
	v_ashrrev_i32_e32 v91, 31, v90
	s_waitcnt lgkmcnt(0)
	v_add_f32_e32 v13, v13, v25
	ds_bpermute_b32 v25, v101, v13
	v_lshl_add_u64 v[90:91], v[90:91], 1, s[4:5]
	global_store_short v[90:91], v27, off
	global_store_short v[90:91], v31, off offset:64
	s_and_b64 vcc, exec, s[70:71]
	v_add_u32_e32 v112, s68, v179
	s_waitcnt lgkmcnt(0)
	v_add_f32_e32 v13, v13, v25
	ds_bpermute_b32 v25, v102, v13
	s_waitcnt lgkmcnt(0)
	v_add_f32_e32 v13, v13, v25
	ds_bpermute_b32 v25, v103, v13
	s_waitcnt lgkmcnt(0)
	v_add_f32_e32 v13, v13, v25
	ds_bpermute_b32 v25, v104, v13
	s_waitcnt lgkmcnt(0)
	v_add_f32_e32 v13, v13, v25
	v_fmamk_f32 v13, v13, 0x3c800000, v196
	v_rsq_f32_e32 v92, v13
	s_nop 0
	v_pk_mul_f32 v[90:91], v[10:11], v[92:93] op_sel_hi:[1,0]
	s_nop 0
	v_pk_mul_f32 v[92:93], v[52:53], v[90:91]
	s_cbranch_vccz .LBB0_897
	v_lshl_or_b32 v52, v112, 10, v134
	v_ashrrev_i32_e32 v53, 31, v52
	v_lshl_add_u64 v[52:53], v[52:53], 2, s[26:27]
	global_store_dword v[52:53], v93, off sc1
	global_store_dword v[52:53], v92, off offset:128 sc1

.LBB0_899:
	v_pk_mul_f32 v[52:53], v[50:51], v[50:51]
	v_cvt_pk_bf16_f32 v31, v92, s0
	v_add_f32_e32 v13, v53, v52
	ds_bpermute_b32 v25, v100, v13
	v_add_lshl_u32 v52, s8, v179, 10
	v_or_b32_e32 v92, v52, v134
	v_cvt_pk_bf16_f32 v27, v93, s0
	v_ashrrev_i32_e32 v93, 31, v92
	s_waitcnt lgkmcnt(0)
	v_add_f32_e32 v13, v13, v25
	ds_bpermute_b32 v25, v101, v13
	v_lshl_add_u64 v[92:93], v[92:93], 1, s[4:5]
	global_store_short v[92:93], v27, off
	global_store_short v[92:93], v31, off offset:64
	s_and_b64 vcc, exec, s[70:71]
	v_add_u32_e32 v113, s68, v180
	s_waitcnt lgkmcnt(0)
	v_add_f32_e32 v13, v13, v25
	ds_bpermute_b32 v25, v102, v13
	s_waitcnt lgkmcnt(0)
	v_add_f32_e32 v13, v13, v25
	ds_bpermute_b32 v25, v103, v13
	s_waitcnt lgkmcnt(0)
	v_add_f32_e32 v13, v13, v25
	ds_bpermute_b32 v25, v104, v13
	s_waitcnt lgkmcnt(0)
	v_add_f32_e32 v13, v13, v25
	v_fmamk_f32 v13, v13, 0x3c800000, v196
	v_rsq_f32_e32 v94, v13
	s_nop 0
	v_pk_mul_f32 v[92:93], v[10:11], v[94:95] op_sel_hi:[1,0]
	s_nop 0
	v_pk_mul_f32 v[94:95], v[50:51], v[92:93]
	s_cbranch_vccz .LBB0_901
	v_lshl_or_b32 v50, v113, 10, v134
	v_ashrrev_i32_e32 v51, 31, v50
	v_lshl_add_u64 v[50:51], v[50:51], 2, s[26:27]
	global_store_dword v[50:51], v95, off sc1
	global_store_dword v[50:51], v94, off offset:128 sc1

.LBB0_903:
	v_pk_mul_f32 v[50:51], v[48:49], v[48:49]
	v_cvt_pk_bf16_f32 v31, v94, s0
	v_add_f32_e32 v13, v51, v50
	ds_bpermute_b32 v25, v100, v13
	v_add_lshl_u32 v50, s8, v180, 10
	v_or_b32_e32 v94, v50, v134
	v_cvt_pk_bf16_f32 v27, v95, s0
	v_ashrrev_i32_e32 v95, 31, v94
	s_waitcnt lgkmcnt(0)
	v_add_f32_e32 v13, v13, v25
	ds_bpermute_b32 v25, v101, v13
	v_lshl_add_u64 v[94:95], v[94:95], 1, s[4:5]
	global_store_short v[94:95], v27, off
	global_store_short v[94:95], v31, off offset:64
	s_and_b64 vcc, exec, s[70:71]
	v_add_u32_e32 v114, s68, v181
	s_waitcnt lgkmcnt(0)
	v_add_f32_e32 v13, v13, v25
	ds_bpermute_b32 v25, v102, v13
	s_waitcnt lgkmcnt(0)
	v_add_f32_e32 v13, v13, v25
	ds_bpermute_b32 v25, v103, v13
	s_waitcnt lgkmcnt(0)
	v_add_f32_e32 v13, v13, v25
	ds_bpermute_b32 v25, v104, v13
	s_waitcnt lgkmcnt(0)
	v_add_f32_e32 v13, v13, v25
	v_fmamk_f32 v13, v13, 0x3c800000, v196
	v_rsq_f32_e32 v96, v13
	s_nop 0
	v_pk_mul_f32 v[94:95], v[10:11], v[96:97] op_sel_hi:[1,0]
	s_nop 0
	v_pk_mul_f32 v[96:97], v[48:49], v[94:95]
	s_cbranch_vccz .LBB0_905
	v_lshl_or_b32 v48, v114, 10, v134
	v_ashrrev_i32_e32 v49, 31, v48
	v_lshl_add_u64 v[48:49], v[48:49], 2, s[26:27]
	global_store_dword v[48:49], v97, off sc1
	global_store_dword v[48:49], v96, off offset:128 sc1

.LBB0_907:
	v_pk_mul_f32 v[48:49], v[46:47], v[46:47]
	v_cvt_pk_bf16_f32 v31, v96, s0
	v_add_f32_e32 v13, v49, v48
	ds_bpermute_b32 v25, v100, v13
	v_add_lshl_u32 v48, s8, v181, 10
	v_or_b32_e32 v98, v48, v134
	v_ashrrev_i32_e32 v99, 31, v98
	v_cvt_pk_bf16_f32 v27, v97, s0
	s_waitcnt lgkmcnt(0)
	v_add_f32_e32 v13, v13, v25
	ds_bpermute_b32 v25, v101, v13
	v_add_u32_e32 v97, s68, v182
	v_lshl_add_u64 v[98:99], v[98:99], 1, s[4:5]
	global_store_short v[98:99], v27, off
	global_store_short v[98:99], v31, off offset:64
	s_and_b64 vcc, exec, s[70:71]
	s_waitcnt lgkmcnt(0)
	v_add_f32_e32 v13, v13, v25
	ds_bpermute_b32 v25, v102, v13
	s_waitcnt lgkmcnt(0)
	v_add_f32_e32 v13, v13, v25
	ds_bpermute_b32 v25, v103, v13
	s_waitcnt lgkmcnt(0)
	v_add_f32_e32 v13, v13, v25
	ds_bpermute_b32 v25, v104, v13
	s_waitcnt lgkmcnt(0)
	v_add_f32_e32 v13, v13, v25
	v_fmamk_f32 v13, v13, 0x3c800000, v196
	v_rsq_f32_e32 v96, v13
	s_nop 0
	v_pk_mul_f32 v[98:99], v[10:11], v[96:97] op_sel_hi:[1,0]
	s_nop 0
	v_pk_mul_f32 v[98:99], v[46:47], v[98:99]
	s_cbranch_vccz .LBB0_909
	v_lshl_or_b32 v46, v97, 10, v134
	v_ashrrev_i32_e32 v47, 31, v46
	v_lshl_add_u64 v[46:47], v[46:47], 2, s[26:27]
	global_store_dword v[46:47], v99, off sc1
	global_store_dword v[46:47], v98, off offset:128 sc1

.LBB0_911:
	v_pk_mul_f32 v[116:117], v[44:45], v[44:45]
	v_add_lshl_u32 v96, s8, v182, 10
	v_add_f32_e32 v13, v117, v116
	ds_bpermute_b32 v25, v100, v13
	v_cvt_pk_bf16_f32 v31, v98, s0
	v_or_b32_e32 v98, v96, v134
	v_cvt_pk_bf16_f32 v27, v99, s0
	v_ashrrev_i32_e32 v99, 31, v98
	s_waitcnt lgkmcnt(0)
	v_add_f32_e32 v13, v13, v25
	ds_bpermute_b32 v25, v101, v13
	v_lshl_add_u64 v[98:99], v[98:99], 1, s[4:5]
	global_store_short v[98:99], v27, off
	global_store_short v[98:99], v31, off offset:64
	v_or_b32_e32 v47, 64, v134
	s_and_b64 vcc, exec, s[70:71]
	s_waitcnt lgkmcnt(0)
	v_add_f32_e32 v13, v13, v25
	ds_bpermute_b32 v25, v102, v13
	s_waitcnt lgkmcnt(0)
	v_add_f32_e32 v13, v13, v25
	ds_bpermute_b32 v25, v103, v13
	s_waitcnt lgkmcnt(0)
	v_add_f32_e32 v13, v13, v25
	ds_bpermute_b32 v25, v104, v13
	s_waitcnt lgkmcnt(0)
	v_add_f32_e32 v13, v13, v25
	v_fmamk_f32 v13, v13, 0x3c800000, v196
	v_rsq_f32_e32 v116, v13
	s_nop 0
	v_pk_mul_f32 v[98:99], v[10:11], v[116:117] op_sel_hi:[1,0]
	s_nop 0
	v_pk_mul_f32 v[44:45], v[44:45], v[98:99]
	s_cbranch_vccz .LBB0_913
	v_lshl_or_b32 v98, v148, 10, v47
	v_ashrrev_i32_e32 v99, 31, v98
	v_lshl_add_u64 v[98:99], v[98:99], 2, s[26:27]
	global_store_dword v[98:99], v45, off sc1
	global_store_dword v[98:99], v44, off offset:128 sc1

.LBB0_915:
	v_pk_mul_f32 v[12:13], v[42:43], v[42:43]
	v_cvt_pk_bf16_f32 v27, v45, s0
	v_add_f32_e32 v12, v13, v12
	ds_bpermute_b32 v13, v100, v12
	v_ashrrev_i32_e32 v25, 31, v24
	v_cvt_pk_bf16_f32 v44, v44, s0
	s_and_b64 vcc, exec, s[70:71]
	s_waitcnt lgkmcnt(0)
	v_add_f32_e32 v12, v12, v13
	ds_bpermute_b32 v13, v101, v12
	s_waitcnt lgkmcnt(0)
	v_add_f32_e32 v12, v12, v13
	ds_bpermute_b32 v13, v102, v12
	s_waitcnt lgkmcnt(0)
	v_add_f32_e32 v12, v12, v13
	ds_bpermute_b32 v13, v103, v12
	s_waitcnt lgkmcnt(0)
	v_add_f32_e32 v31, v12, v13
	ds_bpermute_b32 v45, v104, v31
	v_lshl_add_u64 v[12:13], v[24:25], 0, v[134:135]
	v_lshl_add_u64 v[12:13], v[12:13], 1, s[4:5]
	global_store_short v[12:13], v27, off offset:128
	global_store_short v[12:13], v44, off offset:192
	s_waitcnt lgkmcnt(0)
	v_add_f32_e32 v24, v31, v45
	v_fmamk_f32 v24, v24, 0x3c800000, v196
	v_rsq_f32_e32 v24, v24
	s_nop 0
	v_pk_mul_f32 v[12:13], v[10:11], v[24:25] op_sel_hi:[1,0]
	s_nop 0
	v_pk_mul_f32 v[12:13], v[42:43], v[12:13]
	s_cbranch_vccz .LBB0_917
	v_lshl_or_b32 v24, v15, 10, v47
	v_ashrrev_i32_e32 v25, 31, v24
	v_lshl_add_u64 v[24:25], v[24:25], 2, s[26:27]
	global_store_dword v[24:25], v13, off sc1
	global_store_dword v[24:25], v12, off offset:128 sc1

.LBB0_919:
	v_pk_mul_f32 v[24:25], v[40:41], v[40:41]
	v_cvt_pk_bf16_f32 v27, v12, s0
	v_add_f32_e32 v15, v25, v24
	ds_bpermute_b32 v24, v100, v15
	v_cvt_pk_bf16_f32 v25, v13, s0
	s_and_b64 vcc, exec, s[70:71]
	s_waitcnt lgkmcnt(0)
	v_add_f32_e32 v15, v15, v24
	ds_bpermute_b32 v24, v101, v15
	s_waitcnt lgkmcnt(0)
	v_add_f32_e32 v15, v15, v24
	ds_bpermute_b32 v24, v102, v15
	s_waitcnt lgkmcnt(0)
	v_add_f32_e32 v15, v15, v24
	ds_bpermute_b32 v24, v103, v15
	s_waitcnt lgkmcnt(0)
	v_add_f32_e32 v24, v15, v24
	ds_bpermute_b32 v26, v104, v24
	v_ashrrev_i32_e32 v15, 31, v14
	v_lshl_add_u64 v[12:13], v[14:15], 0, v[134:135]
	v_lshl_add_u64 v[12:13], v[12:13], 1, s[4:5]
	global_store_short v[12:13], v25, off offset:128
	global_store_short v[12:13], v27, off offset:192
	s_waitcnt lgkmcnt(0)
	v_add_f32_e32 v14, v24, v26
	v_fmamk_f32 v14, v14, 0x3c800000, v196
	v_rsq_f32_e32 v14, v14
	s_nop 0
	v_pk_mul_f32 v[12:13], v[10:11], v[14:15] op_sel_hi:[1,0]
	s_nop 0
	v_pk_mul_f32 v[12:13], v[40:41], v[12:13]
	s_cbranch_vccz .LBB0_921
	v_lshl_or_b32 v14, v29, 10, v47
	v_ashrrev_i32_e32 v15, 31, v14
	v_lshl_add_u64 v[14:15], v[14:15], 2, s[26:27]
	global_store_dword v[14:15], v13, off sc1
	global_store_dword v[14:15], v12, off offset:128 sc1

.LBB0_923:
	v_pk_mul_f32 v[14:15], v[38:39], v[38:39]
	v_ashrrev_i32_e32 v29, 31, v28
	v_add_f32_e32 v14, v15, v14
	ds_bpermute_b32 v15, v100, v14
	v_cvt_pk_bf16_f32 v24, v13, s0
	v_cvt_pk_bf16_f32 v25, v12, s0
	v_lshl_add_u64 v[12:13], v[28:29], 0, v[134:135]
	v_lshl_add_u64 v[12:13], v[12:13], 1, s[4:5]
	s_waitcnt lgkmcnt(0)
	v_add_f32_e32 v14, v14, v15
	ds_bpermute_b32 v15, v101, v14
	global_store_short v[12:13], v24, off offset:128
	global_store_short v[12:13], v25, off offset:192
	s_and_b64 vcc, exec, s[70:71]
	s_waitcnt lgkmcnt(0)
	v_add_f32_e32 v14, v14, v15
	ds_bpermute_b32 v15, v102, v14
	s_waitcnt lgkmcnt(0)
	v_add_f32_e32 v14, v14, v15
	ds_bpermute_b32 v15, v103, v14
	s_waitcnt lgkmcnt(0)
	v_add_f32_e32 v14, v14, v15
	ds_bpermute_b32 v15, v104, v14
	s_waitcnt lgkmcnt(0)
	v_add_f32_e32 v14, v14, v15
	v_fmamk_f32 v14, v14, 0x3c800000, v196
	v_rsq_f32_e32 v14, v14
	s_nop 0
	v_pk_mul_f32 v[12:13], v[10:11], v[14:15] op_sel_hi:[1,0]
	s_nop 0
	v_pk_mul_f32 v[12:13], v[38:39], v[12:13]
	s_cbranch_vccz .LBB0_925
	v_lshl_or_b32 v14, v59, 10, v47
	v_ashrrev_i32_e32 v15, 31, v14
	v_lshl_add_u64 v[14:15], v[14:15], 2, s[26:27]
	global_store_dword v[14:15], v13, off sc1
	global_store_dword v[14:15], v12, off offset:128 sc1

.LBB0_927:
	v_pk_mul_f32 v[14:15], v[36:37], v[36:37]
	v_ashrrev_i32_e32 v59, 31, v58
	v_add_f32_e32 v14, v15, v14
	ds_bpermute_b32 v15, v100, v14
	v_cvt_pk_bf16_f32 v24, v13, s0
	v_cvt_pk_bf16_f32 v25, v12, s0
	v_lshl_add_u64 v[12:13], v[58:59], 0, v[134:135]
	v_lshl_add_u64 v[12:13], v[12:13], 1, s[4:5]
	s_waitcnt lgkmcnt(0)
	v_add_f32_e32 v14, v14, v15
	ds_bpermute_b32 v15, v101, v14
	global_store_short v[12:13], v24, off offset:128
	global_store_short v[12:13], v25, off offset:192
	s_and_b64 vcc, exec, s[70:71]
	s_waitcnt lgkmcnt(0)
	v_add_f32_e32 v14, v14, v15
	ds_bpermute_b32 v15, v102, v14
	s_waitcnt lgkmcnt(0)
	v_add_f32_e32 v14, v14, v15
	ds_bpermute_b32 v15, v103, v14
	s_waitcnt lgkmcnt(0)
	v_add_f32_e32 v14, v14, v15
	ds_bpermute_b32 v15, v104, v14
	s_waitcnt lgkmcnt(0)
	v_add_f32_e32 v14, v14, v15
	v_fmamk_f32 v14, v14, 0x3c800000, v196
	v_rsq_f32_e32 v14, v14
	s_nop 0
	v_pk_mul_f32 v[12:13], v[10:11], v[14:15] op_sel_hi:[1,0]
	s_nop 0
	v_pk_mul_f32 v[12:13], v[36:37], v[12:13]
	s_cbranch_vccz .LBB0_929
	v_lshl_or_b32 v14, v63, 10, v47
	v_ashrrev_i32_e32 v15, 31, v14
	v_lshl_add_u64 v[14:15], v[14:15], 2, s[26:27]
	global_store_dword v[14:15], v13, off sc1
	global_store_dword v[14:15], v12, off offset:128 sc1

.LBB0_931:
	v_pk_mul_f32 v[14:15], v[34:35], v[34:35]
	v_ashrrev_i32_e32 v63, 31, v62
	v_add_f32_e32 v14, v15, v14
	ds_bpermute_b32 v15, v100, v14
	v_cvt_pk_bf16_f32 v24, v13, s0
	v_cvt_pk_bf16_f32 v25, v12, s0
	v_lshl_add_u64 v[12:13], v[62:63], 0, v[134:135]
	v_lshl_add_u64 v[12:13], v[12:13], 1, s[4:5]
	s_waitcnt lgkmcnt(0)
	v_add_f32_e32 v14, v14, v15
	ds_bpermute_b32 v15, v101, v14
	global_store_short v[12:13], v24, off offset:128
	global_store_short v[12:13], v25, off offset:192
	s_and_b64 vcc, exec, s[70:71]
	s_waitcnt lgkmcnt(0)
	v_add_f32_e32 v14, v14, v15
	ds_bpermute_b32 v15, v102, v14
	s_waitcnt lgkmcnt(0)
	v_add_f32_e32 v14, v14, v15
	ds_bpermute_b32 v15, v103, v14
	s_waitcnt lgkmcnt(0)
	v_add_f32_e32 v14, v14, v15
	ds_bpermute_b32 v15, v104, v14
	s_waitcnt lgkmcnt(0)
	v_add_f32_e32 v14, v14, v15
	v_fmamk_f32 v14, v14, 0x3c800000, v196
	v_rsq_f32_e32 v14, v14
	s_nop 0
	v_pk_mul_f32 v[12:13], v[10:11], v[14:15] op_sel_hi:[1,0]
	s_nop 0
	v_pk_mul_f32 v[12:13], v[34:35], v[12:13]
	s_cbranch_vccz .LBB0_933
	v_lshl_or_b32 v14, v105, 10, v47
	v_ashrrev_i32_e32 v15, 31, v14
	v_lshl_add_u64 v[14:15], v[14:15], 2, s[26:27]
	global_store_dword v[14:15], v13, off sc1
	global_store_dword v[14:15], v12, off offset:128 sc1

.LBB0_935:
	v_pk_mul_f32 v[14:15], v[32:33], v[32:33]
	v_ashrrev_i32_e32 v73, 31, v72
	v_add_f32_e32 v14, v15, v14
	ds_bpermute_b32 v15, v100, v14
	v_cvt_pk_bf16_f32 v24, v13, s0
	v_cvt_pk_bf16_f32 v25, v12, s0
	v_lshl_add_u64 v[12:13], v[72:73], 0, v[134:135]
	v_lshl_add_u64 v[12:13], v[12:13], 1, s[4:5]
	s_waitcnt lgkmcnt(0)
	v_add_f32_e32 v14, v14, v15
	ds_bpermute_b32 v15, v101, v14
	global_store_short v[12:13], v24, off offset:128
	global_store_short v[12:13], v25, off offset:192
	s_and_b64 vcc, exec, s[70:71]
	s_waitcnt lgkmcnt(0)
	v_add_f32_e32 v14, v14, v15
	ds_bpermute_b32 v15, v102, v14
	s_waitcnt lgkmcnt(0)
	v_add_f32_e32 v14, v14, v15
	ds_bpermute_b32 v15, v103, v14
	s_waitcnt lgkmcnt(0)
	v_add_f32_e32 v14, v14, v15
	ds_bpermute_b32 v15, v104, v14
	s_waitcnt lgkmcnt(0)
	v_add_f32_e32 v14, v14, v15
	v_fmamk_f32 v14, v14, 0x3c800000, v196
	v_rsq_f32_e32 v14, v14
	s_nop 0
	v_pk_mul_f32 v[12:13], v[10:11], v[14:15] op_sel_hi:[1,0]
	s_nop 0
	v_pk_mul_f32 v[12:13], v[32:33], v[12:13]
	s_cbranch_vccz .LBB0_937
	v_lshl_or_b32 v14, v106, 10, v47
	v_ashrrev_i32_e32 v15, 31, v14
	v_lshl_add_u64 v[14:15], v[14:15], 2, s[26:27]
	global_store_dword v[14:15], v13, off sc1
	global_store_dword v[14:15], v12, off offset:128 sc1

.LBB0_939:
	v_pk_mul_f32 v[14:15], v[22:23], v[22:23]
	v_ashrrev_i32_e32 v77, 31, v76
	v_add_f32_e32 v14, v15, v14
	ds_bpermute_b32 v15, v100, v14
	v_cvt_pk_bf16_f32 v24, v13, s0
	v_cvt_pk_bf16_f32 v25, v12, s0
	v_lshl_add_u64 v[12:13], v[76:77], 0, v[134:135]
	v_lshl_add_u64 v[12:13], v[12:13], 1, s[4:5]
	s_waitcnt lgkmcnt(0)
	v_add_f32_e32 v14, v14, v15
	ds_bpermute_b32 v15, v101, v14
	global_store_short v[12:13], v24, off offset:128
	global_store_short v[12:13], v25, off offset:192
	s_and_b64 vcc, exec, s[70:71]
	s_waitcnt lgkmcnt(0)
	v_add_f32_e32 v14, v14, v15
	ds_bpermute_b32 v15, v102, v14
	s_waitcnt lgkmcnt(0)
	v_add_f32_e32 v14, v14, v15
	ds_bpermute_b32 v15, v103, v14
	s_waitcnt lgkmcnt(0)
	v_add_f32_e32 v14, v14, v15
	ds_bpermute_b32 v15, v104, v14
	s_waitcnt lgkmcnt(0)
	v_add_f32_e32 v14, v14, v15
	v_fmamk_f32 v14, v14, 0x3c800000, v196
	v_rsq_f32_e32 v14, v14
	s_nop 0
	v_pk_mul_f32 v[12:13], v[10:11], v[14:15] op_sel_hi:[1,0]
	s_nop 0
	v_pk_mul_f32 v[12:13], v[22:23], v[12:13]
	s_cbranch_vccz .LBB0_941
	v_lshl_or_b32 v14, v107, 10, v47
	v_ashrrev_i32_e32 v15, 31, v14
	v_lshl_add_u64 v[14:15], v[14:15], 2, s[26:27]
	global_store_dword v[14:15], v13, off sc1
	global_store_dword v[14:15], v12, off offset:128 sc1

.LBB0_943:
	v_pk_mul_f32 v[14:15], v[20:21], v[20:21]
	v_ashrrev_i32_e32 v69, 31, v68
	v_add_f32_e32 v14, v15, v14
	ds_bpermute_b32 v15, v100, v14
	v_cvt_pk_bf16_f32 v22, v13, s0
	v_cvt_pk_bf16_f32 v23, v12, s0
	v_lshl_add_u64 v[12:13], v[68:69], 0, v[134:135]
	v_lshl_add_u64 v[12:13], v[12:13], 1, s[4:5]
	s_waitcnt lgkmcnt(0)
	v_add_f32_e32 v14, v14, v15
	ds_bpermute_b32 v15, v101, v14
	global_store_short v[12:13], v22, off offset:128
	global_store_short v[12:13], v23, off offset:192
	s_and_b64 vcc, exec, s[70:71]
	s_waitcnt lgkmcnt(0)
	v_add_f32_e32 v14, v14, v15
	ds_bpermute_b32 v15, v102, v14
	s_waitcnt lgkmcnt(0)
	v_add_f32_e32 v14, v14, v15
	ds_bpermute_b32 v15, v103, v14
	s_waitcnt lgkmcnt(0)
	v_add_f32_e32 v14, v14, v15
	ds_bpermute_b32 v15, v104, v14
	s_waitcnt lgkmcnt(0)
	v_add_f32_e32 v14, v14, v15
	v_fmamk_f32 v14, v14, 0x3c800000, v196
	v_rsq_f32_e32 v14, v14
	s_nop 0
	v_pk_mul_f32 v[12:13], v[10:11], v[14:15] op_sel_hi:[1,0]
	s_nop 0
	v_pk_mul_f32 v[12:13], v[20:21], v[12:13]
	s_cbranch_vccz .LBB0_945
	v_lshl_or_b32 v14, v108, 10, v47
	v_ashrrev_i32_e32 v15, 31, v14
	v_lshl_add_u64 v[14:15], v[14:15], 2, s[26:27]
	global_store_dword v[14:15], v13, off sc1
	global_store_dword v[14:15], v12, off offset:128 sc1

.LBB0_947:
	v_pk_mul_f32 v[14:15], v[18:19], v[18:19]
	v_ashrrev_i32_e32 v67, 31, v66
	v_add_f32_e32 v14, v15, v14
	ds_bpermute_b32 v15, v100, v14
	v_cvt_pk_bf16_f32 v20, v13, s0
	v_cvt_pk_bf16_f32 v21, v12, s0
	v_lshl_add_u64 v[12:13], v[66:67], 0, v[134:135]
	v_lshl_add_u64 v[12:13], v[12:13], 1, s[4:5]
	s_waitcnt lgkmcnt(0)
	v_add_f32_e32 v14, v14, v15
	ds_bpermute_b32 v15, v101, v14
	global_store_short v[12:13], v20, off offset:128
	global_store_short v[12:13], v21, off offset:192
	s_and_b64 vcc, exec, s[70:71]
	s_waitcnt lgkmcnt(0)
	v_add_f32_e32 v14, v14, v15
	ds_bpermute_b32 v15, v102, v14
	s_waitcnt lgkmcnt(0)
	v_add_f32_e32 v14, v14, v15
	ds_bpermute_b32 v15, v103, v14
	s_waitcnt lgkmcnt(0)
	v_add_f32_e32 v14, v14, v15
	ds_bpermute_b32 v15, v104, v14
	s_waitcnt lgkmcnt(0)
	v_add_f32_e32 v14, v14, v15
	v_fmamk_f32 v14, v14, 0x3c800000, v196
	v_rsq_f32_e32 v14, v14
	s_nop 0
	v_pk_mul_f32 v[12:13], v[10:11], v[14:15] op_sel_hi:[1,0]
	s_nop 0
	v_pk_mul_f32 v[12:13], v[18:19], v[12:13]
	s_cbranch_vccz .LBB0_949
	v_lshl_or_b32 v14, v109, 10, v47
	v_ashrrev_i32_e32 v15, 31, v14
	v_lshl_add_u64 v[14:15], v[14:15], 2, s[26:27]
	global_store_dword v[14:15], v13, off sc1
	global_store_dword v[14:15], v12, off offset:128 sc1

.LBB0_951:
	v_pk_mul_f32 v[14:15], v[16:17], v[16:17]
	v_ashrrev_i32_e32 v65, 31, v64
	v_add_f32_e32 v14, v15, v14
	ds_bpermute_b32 v15, v100, v14
	v_cvt_pk_bf16_f32 v18, v13, s0
	v_cvt_pk_bf16_f32 v19, v12, s0
	v_lshl_add_u64 v[12:13], v[64:65], 0, v[134:135]
	v_lshl_add_u64 v[12:13], v[12:13], 1, s[4:5]
	s_waitcnt lgkmcnt(0)
	v_add_f32_e32 v14, v14, v15
	ds_bpermute_b32 v15, v101, v14
	global_store_short v[12:13], v18, off offset:128
	global_store_short v[12:13], v19, off offset:192
	s_and_b64 vcc, exec, s[70:71]
	s_waitcnt lgkmcnt(0)
	v_add_f32_e32 v14, v14, v15
	ds_bpermute_b32 v15, v102, v14
	s_waitcnt lgkmcnt(0)
	v_add_f32_e32 v14, v14, v15
	ds_bpermute_b32 v15, v103, v14
	s_waitcnt lgkmcnt(0)
	v_add_f32_e32 v14, v14, v15
	ds_bpermute_b32 v15, v104, v14
	s_waitcnt lgkmcnt(0)
	v_add_f32_e32 v14, v14, v15
	v_fmamk_f32 v14, v14, 0x3c800000, v196
	v_rsq_f32_e32 v14, v14
	s_nop 0
	v_pk_mul_f32 v[12:13], v[10:11], v[14:15] op_sel_hi:[1,0]
	s_nop 0
	v_pk_mul_f32 v[12:13], v[16:17], v[12:13]
	s_cbranch_vccz .LBB0_953
	v_lshl_or_b32 v14, v110, 10, v47
	v_ashrrev_i32_e32 v15, 31, v14
	v_lshl_add_u64 v[14:15], v[14:15], 2, s[26:27]
	global_store_dword v[14:15], v13, off sc1
	global_store_dword v[14:15], v12, off offset:128 sc1

.LBB0_955:
	v_pk_mul_f32 v[14:15], v[8:9], v[8:9]
	v_ashrrev_i32_e32 v57, 31, v56
	v_add_f32_e32 v14, v15, v14
	ds_bpermute_b32 v15, v100, v14
	v_cvt_pk_bf16_f32 v16, v13, s0
	v_cvt_pk_bf16_f32 v17, v12, s0
	v_lshl_add_u64 v[12:13], v[56:57], 0, v[134:135]
	v_lshl_add_u64 v[12:13], v[12:13], 1, s[4:5]
	s_waitcnt lgkmcnt(0)
	v_add_f32_e32 v14, v14, v15
	ds_bpermute_b32 v15, v101, v14
	global_store_short v[12:13], v16, off offset:128
	global_store_short v[12:13], v17, off offset:192
	s_and_b64 vcc, exec, s[70:71]
	s_waitcnt lgkmcnt(0)
	v_add_f32_e32 v14, v14, v15
	ds_bpermute_b32 v15, v102, v14
	s_waitcnt lgkmcnt(0)
	v_add_f32_e32 v14, v14, v15
	ds_bpermute_b32 v15, v103, v14
	s_waitcnt lgkmcnt(0)
	v_add_f32_e32 v14, v14, v15
	ds_bpermute_b32 v15, v104, v14
	s_waitcnt lgkmcnt(0)
	v_add_f32_e32 v14, v14, v15
	v_fmamk_f32 v14, v14, 0x3c800000, v196
	v_rsq_f32_e32 v14, v14
	s_nop 0
	v_pk_mul_f32 v[12:13], v[10:11], v[14:15] op_sel_hi:[1,0]
	s_nop 0
	v_pk_mul_f32 v[8:9], v[8:9], v[12:13]
	s_cbranch_vccz .LBB0_957
	v_lshl_or_b32 v12, v111, 10, v47
	v_ashrrev_i32_e32 v13, 31, v12
	v_lshl_add_u64 v[12:13], v[12:13], 2, s[26:27]
	global_store_dword v[12:13], v9, off sc1
	global_store_dword v[12:13], v8, off offset:128 sc1

.LBB0_959:
	v_pk_mul_f32 v[12:13], v[6:7], v[6:7]
	v_ashrrev_i32_e32 v55, 31, v54
	v_add_f32_e32 v12, v13, v12
	ds_bpermute_b32 v13, v100, v12
	v_cvt_pk_bf16_f32 v14, v9, s0
	v_cvt_pk_bf16_f32 v15, v8, s0
	v_lshl_add_u64 v[8:9], v[54:55], 0, v[134:135]
	v_lshl_add_u64 v[8:9], v[8:9], 1, s[4:5]
	s_waitcnt lgkmcnt(0)
	v_add_f32_e32 v12, v12, v13
	ds_bpermute_b32 v13, v101, v12
	global_store_short v[8:9], v14, off offset:128
	global_store_short v[8:9], v15, off offset:192
	s_and_b64 vcc, exec, s[70:71]
	s_waitcnt lgkmcnt(0)
	v_add_f32_e32 v12, v12, v13
	ds_bpermute_b32 v13, v102, v12
	s_waitcnt lgkmcnt(0)
	v_add_f32_e32 v12, v12, v13
	ds_bpermute_b32 v13, v103, v12
	s_waitcnt lgkmcnt(0)
	v_add_f32_e32 v12, v12, v13
	ds_bpermute_b32 v13, v104, v12
	s_waitcnt lgkmcnt(0)
	v_add_f32_e32 v12, v12, v13
	v_fmamk_f32 v12, v12, 0x3c800000, v196
	v_rsq_f32_e32 v12, v12
	s_nop 0
	v_pk_mul_f32 v[8:9], v[10:11], v[12:13] op_sel_hi:[1,0]
	s_nop 0
	v_pk_mul_f32 v[6:7], v[6:7], v[8:9]
	s_cbranch_vccz .LBB0_961
	v_lshl_or_b32 v8, v112, 10, v47
	v_ashrrev_i32_e32 v9, 31, v8
	v_lshl_add_u64 v[8:9], v[8:9], 2, s[26:27]
	global_store_dword v[8:9], v7, off sc1
	global_store_dword v[8:9], v6, off offset:128 sc1

.LBB0_963:
	v_pk_mul_f32 v[8:9], v[4:5], v[4:5]
	v_ashrrev_i32_e32 v53, 31, v52
	v_add_f32_e32 v8, v9, v8
	ds_bpermute_b32 v9, v100, v8
	v_cvt_pk_bf16_f32 v12, v7, s0
	v_cvt_pk_bf16_f32 v13, v6, s0
	v_lshl_add_u64 v[6:7], v[52:53], 0, v[134:135]
	v_lshl_add_u64 v[6:7], v[6:7], 1, s[4:5]
	s_waitcnt lgkmcnt(0)
	v_add_f32_e32 v8, v8, v9
	ds_bpermute_b32 v9, v101, v8
	global_store_short v[6:7], v12, off offset:128
	global_store_short v[6:7], v13, off offset:192
	s_and_b64 vcc, exec, s[70:71]
	s_waitcnt lgkmcnt(0)
	v_add_f32_e32 v8, v8, v9
	ds_bpermute_b32 v9, v102, v8
	s_waitcnt lgkmcnt(0)
	v_add_f32_e32 v8, v8, v9
	ds_bpermute_b32 v9, v103, v8
	s_waitcnt lgkmcnt(0)
	v_add_f32_e32 v8, v8, v9
	ds_bpermute_b32 v9, v104, v8
	s_waitcnt lgkmcnt(0)
	v_add_f32_e32 v8, v8, v9
	v_fmamk_f32 v8, v8, 0x3c800000, v196
	v_rsq_f32_e32 v8, v8
	s_nop 0
	v_pk_mul_f32 v[6:7], v[10:11], v[8:9] op_sel_hi:[1,0]
	s_nop 0
	v_pk_mul_f32 v[4:5], v[4:5], v[6:7]
	s_cbranch_vccz .LBB0_965
	v_lshl_or_b32 v6, v113, 10, v47
	v_ashrrev_i32_e32 v7, 31, v6
	v_lshl_add_u64 v[6:7], v[6:7], 2, s[26:27]
	global_store_dword v[6:7], v5, off sc1
	global_store_dword v[6:7], v4, off offset:128 sc1

.LBB0_967:
	v_pk_mul_f32 v[6:7], v[2:3], v[2:3]
	v_ashrrev_i32_e32 v51, 31, v50
	v_add_f32_e32 v6, v7, v6
	ds_bpermute_b32 v7, v100, v6
	v_cvt_pk_bf16_f32 v8, v5, s0
	v_cvt_pk_bf16_f32 v9, v4, s0
	v_lshl_add_u64 v[4:5], v[50:51], 0, v[134:135]
	v_lshl_add_u64 v[4:5], v[4:5], 1, s[4:5]
	s_waitcnt lgkmcnt(0)
	v_add_f32_e32 v6, v6, v7
	ds_bpermute_b32 v7, v101, v6
	global_store_short v[4:5], v8, off offset:128
	global_store_short v[4:5], v9, off offset:192
	s_and_b64 vcc, exec, s[70:71]
	s_waitcnt lgkmcnt(0)
	v_add_f32_e32 v6, v6, v7
	ds_bpermute_b32 v7, v102, v6
	s_waitcnt lgkmcnt(0)
	v_add_f32_e32 v6, v6, v7
	ds_bpermute_b32 v7, v103, v6
	s_waitcnt lgkmcnt(0)
	v_add_f32_e32 v6, v6, v7
	ds_bpermute_b32 v7, v104, v6
	s_waitcnt lgkmcnt(0)
	v_add_f32_e32 v6, v6, v7
	v_fmamk_f32 v6, v6, 0x3c800000, v196
	v_rsq_f32_e32 v6, v6
	s_nop 0
	v_pk_mul_f32 v[4:5], v[10:11], v[6:7] op_sel_hi:[1,0]
	s_nop 0
	v_pk_mul_f32 v[2:3], v[2:3], v[4:5]
	s_cbranch_vccz .LBB0_969
	v_lshl_or_b32 v4, v114, 10, v47
	v_ashrrev_i32_e32 v5, 31, v4
	v_lshl_add_u64 v[4:5], v[4:5], 2, s[26:27]
	global_store_dword v[4:5], v3, off sc1
	global_store_dword v[4:5], v2, off offset:128 sc1

.LBB0_971:
	v_pk_mul_f32 v[4:5], v[0:1], v[0:1]
	v_ashrrev_i32_e32 v49, 31, v48
	v_add_f32_e32 v4, v5, v4
	ds_bpermute_b32 v5, v100, v4
	v_cvt_pk_bf16_f32 v6, v3, s0
	v_cvt_pk_bf16_f32 v7, v2, s0
	v_lshl_add_u64 v[2:3], v[48:49], 0, v[134:135]
	v_lshl_add_u64 v[2:3], v[2:3], 1, s[4:5]
	s_waitcnt lgkmcnt(0)
	v_add_f32_e32 v4, v4, v5
	ds_bpermute_b32 v5, v101, v4
	global_store_short v[2:3], v6, off offset:128
	global_store_short v[2:3], v7, off offset:192
	s_and_b64 vcc, exec, s[70:71]
	s_waitcnt lgkmcnt(0)
	v_add_f32_e32 v4, v4, v5
	ds_bpermute_b32 v5, v102, v4
	s_waitcnt lgkmcnt(0)
	v_add_f32_e32 v4, v4, v5
	ds_bpermute_b32 v5, v103, v4
	s_waitcnt lgkmcnt(0)
	v_add_f32_e32 v4, v4, v5
	ds_bpermute_b32 v5, v104, v4
	s_waitcnt lgkmcnt(0)
	v_add_f32_e32 v4, v4, v5
	v_fmamk_f32 v4, v4, 0x3c800000, v196
	v_rsq_f32_e32 v4, v4
	s_nop 0
	v_pk_mul_f32 v[2:3], v[10:11], v[4:5] op_sel_hi:[1,0]
	s_nop 0
	v_pk_mul_f32 v[0:1], v[0:1], v[2:3]
	s_cbranch_vccz .LBB0_973
	v_lshl_or_b32 v2, v97, 10, v47
	v_ashrrev_i32_e32 v3, 31, v2
	v_lshl_add_u64 v[2:3], v[2:3], 2, s[26:27]
	global_store_dword v[2:3], v1, off sc1
	global_store_dword v[2:3], v0, off offset:128 sc1

.LBB0_1179:
	v_add_u32_e32 v118, s66, v133
	v_ashrrev_i32_e32 v119, 31, v118
	v_lshl_add_u64 v[64:65], v[118:119], 2, s[18:19]
	v_add_co_u32_e32 v66, vcc, 0x10000, v64
	v_or_b32_e32 v120, 8, v118
	s_nop 0
	v_addc_co_u32_e32 v67, vcc, 0, v65, vcc
	global_load_dwordx4 v[92:95], v[64:65], off
	global_load_dwordx4 v[96:99], v[66:67], off
	v_add_co_u32_e32 v66, vcc, 0x20000, v64
	v_ashrrev_i32_e32 v121, 31, v120
	s_nop 0
	v_addc_co_u32_e32 v67, vcc, 0, v65, vcc
	v_add_co_u32_e32 v68, vcc, 0x30000, v64
	v_lshl_add_u64 v[88:89], v[120:121], 2, s[18:19]
	s_nop 0
	v_addc_co_u32_e32 v69, vcc, 0, v65, vcc
	global_load_dwordx4 v[100:103], v[66:67], off
	global_load_dwordx4 v[124:127], v[68:69], off
	v_add_co_u32_e32 v66, vcc, 0x40000, v64
	v_or_b32_e32 v122, 9, v118
	s_nop 0
	v_addc_co_u32_e32 v67, vcc, 0, v65, vcc
	v_add_co_u32_e32 v68, vcc, 0x50000, v64
	v_ashrrev_i32_e32 v123, 31, v122
	s_nop 0
	v_addc_co_u32_e32 v69, vcc, 0, v65, vcc
	global_load_dwordx4 v[172:175], v[66:67], off
	global_load_dwordx4 v[176:179], v[68:69], off
	v_add_co_u32_e32 v66, vcc, 0x60000, v64
	v_lshl_add_u64 v[104:105], v[122:123], 2, s[18:19]
	s_nop 0
	v_addc_co_u32_e32 v67, vcc, 0, v65, vcc
	v_add_co_u32_e32 v64, vcc, 0x70000, v64
	global_load_dwordx4 v[180:183], v[66:67], off
	s_nop 0
	v_addc_co_u32_e32 v65, vcc, 0, v65, vcc
	global_load_dwordx4 v[184:187], v[64:65], off
	v_add_co_u32_e32 v64, vcc, s75, v88
	s_lshl_b64 s[70:71], s[70:71], 2
	s_nop 0
	v_addc_co_u32_e32 v65, vcc, 0, v89, vcc
	v_add_co_u32_e32 v68, vcc, s76, v88
	global_load_dword v188, v[88:89], off
	s_nop 0
	global_load_dwordx4 v[64:67], v[64:65], off
	v_addc_co_u32_e32 v69, vcc, 0, v89, vcc
	v_add_co_u32_e32 v72, vcc, s77, v88
	s_add_u32 s70, s10, s70
	s_nop 0
	v_addc_co_u32_e32 v73, vcc, 0, v89, vcc
	v_add_co_u32_e32 v76, vcc, s78, v88
	global_load_dwordx4 v[68:71], v[68:69], off
	s_nop 0
	global_load_dwordx4 v[72:75], v[72:73], off
	v_addc_co_u32_e32 v77, vcc, 0, v89, vcc
	v_add_co_u32_e32 v80, vcc, s79, v88
	s_addc_u32 s71, s11, s71
	s_nop 0
	v_addc_co_u32_e32 v81, vcc, 0, v89, vcc
	v_add_co_u32_e32 v84, vcc, s80, v88
	global_load_dwordx4 v[76:79], v[76:77], off
	s_nop 0
	global_load_dwordx4 v[80:83], v[80:81], off
	v_addc_co_u32_e32 v85, vcc, 0, v89, vcc
	v_add_co_u32_e32 v88, vcc, s81, v88
	global_load_dwordx4 v[84:87], v[84:85], off
	s_nop 0
	v_addc_co_u32_e32 v89, vcc, 0, v89, vcc
	global_load_dwordx4 v[88:91], v[88:89], off
	s_cmpk_gt_i32 s85, 0x4f
	global_load_dwordx3 v[104:106], v[104:105], off
	s_waitcnt vmcnt(0)
	v_mov_b32_e32 v190, v92
	v_mov_b32_e32 v192, v96
	v_mov_b32_e32 v194, v124
	v_or_b32_e32 v124, 16, v118
	v_mov_b32_e32 v191, v172
	v_mov_b32_e32 v193, v176
	v_pk_add_f32 v[190:191], v[190:191], v[192:193]
	v_mov_b32_e32 v172, v93
	v_mov_b32_e32 v176, v97
	v_pk_add_f32 v[92:93], v[172:173], v[176:177]
	v_mov_b32_e32 v192, v100
	v_mov_b32_e32 v100, v126
	v_or_b32_e32 v126, 17, v118
	v_mov_b32_e32 v193, v180
	v_mov_b32_e32 v180, v101
	v_mov_b32_e32 v195, v184
	v_mov_b32_e32 v184, v125
	v_pk_add_f32 v[96:97], v[180:181], v[184:185]
	v_mov_b32_e32 v101, v186
	v_pk_add_f32 v[92:93], v[92:93], v[96:97]
	v_mov_b32_e32 v96, v98
	v_add_f32_e32 v121, v92, v93
	v_mov_b32_e32 v92, v94
	v_mov_b32_e32 v93, v174
	v_mov_b32_e32 v97, v178
	v_pk_add_f32 v[92:93], v[92:93], v[96:97]
	v_mov_b32_e32 v96, v102
	v_mov_b32_e32 v97, v182
	v_pk_add_f32 v[96:97], v[96:97], v[100:101]
	v_mov_b32_e32 v174, v95
	v_pk_add_f32 v[92:93], v[92:93], v[96:97]
	v_mov_b32_e32 v178, v99
	v_mov_b32_e32 v182, v103
	v_mov_b32_e32 v186, v127
	v_add_f32_e32 v123, v92, v93
	v_pk_add_f32 v[92:93], v[174:175], v[178:179]
	v_pk_add_f32 v[94:95], v[182:183], v[186:187]
	v_ashrrev_i32_e32 v125, 31, v124
	v_pk_add_f32 v[92:93], v[92:93], v[94:95]
	v_lshl_add_u64 v[100:101], v[124:125], 2, s[18:19]
	v_add_f32_e32 v171, v92, v93
	v_mov_b32_e32 v92, v64
	v_mov_b32_e32 v189, v76
	v_mov_b32_e32 v93, v80
	v_mov_b32_e32 v94, v68
	v_mov_b32_e32 v96, v72
	global_load_dword v64, v[100:101], off
	v_mov_b32_e32 v80, v65
	v_mov_b32_e32 v95, v84
	v_pk_add_f32 v[92:93], v[188:189], v[92:93]
	v_ashrrev_i32_e32 v127, 31, v126
	v_mov_b32_e32 v97, v88
	v_pk_add_f32 v[94:95], v[94:95], v[96:97]
	v_mov_b32_e32 v76, v104
	v_pk_add_f32 v[76:77], v[76:77], v[80:81]
	v_add_co_u32_e32 v80, vcc, s75, v100
	v_pk_add_f32 v[92:93], v[92:93], v[94:95]
	s_nop 0
	v_addc_co_u32_e32 v81, vcc, 0, v101, vcc
	v_add_f32_e32 v225, v92, v93
	v_add_co_u32_e32 v92, vcc, s76, v100
	v_mov_b32_e32 v84, v69
	s_nop 0
	v_addc_co_u32_e32 v93, vcc, 0, v101, vcc
	global_load_dwordx4 v[172:175], v[80:81], off
	global_load_dwordx4 v[176:179], v[92:93], off
	v_add_co_u32_e32 v80, vcc, s77, v100
	v_mov_b32_e32 v88, v73
	s_nop 0
	v_addc_co_u32_e32 v81, vcc, 0, v101, vcc
	v_add_co_u32_e32 v96, vcc, s78, v100
	v_pk_add_f32 v[68:69], v[84:85], v[88:89]
	s_nop 0
	v_addc_co_u32_e32 v97, vcc, 0, v101, vcc
	global_load_dwordx4 v[92:95], v[80:81], off
	global_load_dwordx4 v[180:183], v[96:97], off
	v_add_co_u32_e32 v80, vcc, s79, v100
	v_or_b32_e32 v84, 24, v118
	s_nop 0
	v_addc_co_u32_e32 v81, vcc, 0, v101, vcc
	v_add_co_u32_e32 v96, vcc, s80, v100
	v_ashrrev_i32_e32 v85, 31, v84
	s_nop 0
	v_addc_co_u32_e32 v97, vcc, 0, v101, vcc
	global_load_dwordx4 v[184:187], v[80:81], off
	s_nop 0
	global_load_dwordx4 v[96:99], v[96:97], off
	v_add_co_u32_e32 v80, vcc, s81, v100
	v_lshl_add_u64 v[72:73], v[84:85], 2, s[18:19]
	s_nop 0
	v_addc_co_u32_e32 v81, vcc, 0, v101, vcc
	global_load_dwordx4 v[100:103], v[80:81], off
	v_lshl_add_u64 v[80:81], v[126:127], 2, s[18:19]
	global_load_dwordx3 v[196:198], v[80:81], off
	v_pk_add_f32 v[192:193], v[192:193], v[194:195]
	v_pk_add_f32 v[68:69], v[76:77], v[68:69]
	v_add_co_u32_e32 v76, vcc, s75, v72
	v_pk_add_f32 v[190:191], v[190:191], v[192:193]
	s_nop 0
	v_addc_co_u32_e32 v77, vcc, 0, v73, vcc
	v_add_f32_e32 v119, v190, v191
	global_load_dword v80, v[72:73], off
	global_load_dwordx4 v[188:191], v[76:77], off
	v_add_co_u32_e32 v76, vcc, s76, v72
	v_or_b32_e32 v104, 25, v118
	s_nop 0
	v_addc_co_u32_e32 v77, vcc, 0, v73, vcc
	v_add_co_u32_e32 v88, vcc, s77, v72
	v_add_f32_e32 v125, v68, v69
	s_nop 0
	v_addc_co_u32_e32 v89, vcc, 0, v73, vcc
	global_load_dwordx4 v[192:195], v[76:77], off
	global_load_dwordx4 v[202:205], v[88:89], off
	v_add_co_u32_e32 v76, vcc, s78, v72
	v_mov_b32_e32 v68, v105
	s_nop 0
	v_addc_co_u32_e32 v77, vcc, 0, v73, vcc
	v_add_co_u32_e32 v88, vcc, s79, v72
	v_ashrrev_i32_e32 v105, 31, v104
	s_nop 0
	v_addc_co_u32_e32 v89, vcc, 0, v73, vcc
	global_load_dwordx4 v[206:209], v[76:77], off
	global_load_dwordx4 v[210:213], v[88:89], off
	v_add_co_u32_e32 v76, vcc, s80, v72
	v_mov_b32_e32 v69, v78
	s_nop 0
	v_addc_co_u32_e32 v77, vcc, 0, v73, vcc
	v_add_co_u32_e32 v72, vcc, s81, v72
	global_load_dwordx4 v[214:217], v[76:77], off
	s_nop 0
	v_addc_co_u32_e32 v73, vcc, 0, v73, vcc
	global_load_dwordx4 v[218:221], v[72:73], off
	v_lshl_add_u64 v[72:73], v[104:105], 2, s[18:19]
	global_load_dwordx3 v[222:224], v[72:73], off
	v_mov_b32_e32 v72, v66
	v_mov_b32_e32 v73, v82
	v_pk_add_f32 v[68:69], v[68:69], v[72:73]
	v_mov_b32_e32 v72, v70
	v_mov_b32_e32 v73, v86
	v_mov_b32_e32 v76, v74
	v_mov_b32_e32 v77, v90
	v_pk_add_f32 v[72:73], v[72:73], v[76:77]
	v_mov_b32_e32 v78, v106
	v_pk_add_f32 v[68:69], v[68:69], v[72:73]
	v_mov_b32_e32 v82, v67
	v_mov_b32_e32 v86, v71
	v_mov_b32_e32 v90, v75
	v_add_f32_e32 v72, v68, v69
	v_pk_add_f32 v[66:67], v[78:79], v[82:83]
	v_pk_add_f32 v[68:69], v[86:87], v[90:91]
	s_waitcnt vmcnt(13)
	v_mov_b32_e32 v65, v180
	v_pk_add_f32 v[66:67], v[66:67], v[68:69]
	v_mov_b32_e32 v68, v92
	v_add_f32_e32 v71, v66, v67
	v_mov_b32_e32 v66, v172
	s_waitcnt vmcnt(12)
	v_mov_b32_e32 v67, v184
	v_pk_add_f32 v[64:65], v[64:65], v[66:67]
	v_mov_b32_e32 v66, v176
	s_waitcnt vmcnt(11)
	v_mov_b32_e32 v67, v96
	v_mov_b32_e32 v184, v173
	v_mov_b32_e32 v96, v177
	s_waitcnt vmcnt(10)
	v_mov_b32_e32 v69, v100
	v_pk_add_f32 v[66:67], v[66:67], v[68:69]
	s_waitcnt vmcnt(9)
	v_mov_b32_e32 v180, v196
	v_pk_add_f32 v[64:65], v[64:65], v[66:67]
	v_mov_b32_e32 v100, v93
	v_add_f32_e32 v73, v64, v65
	v_pk_add_f32 v[64:65], v[180:181], v[184:185]
	v_pk_add_f32 v[66:67], v[96:97], v[100:101]
	v_mov_b32_e32 v68, v94
	v_pk_add_f32 v[64:65], v[64:65], v[66:67]
	v_mov_b32_e32 v66, v174
	v_add_f32_e32 v75, v64, v65
	v_mov_b32_e32 v64, v197
	v_mov_b32_e32 v65, v182
	v_mov_b32_e32 v67, v186
	v_pk_add_f32 v[64:65], v[64:65], v[66:67]
	v_mov_b32_e32 v66, v178
	v_mov_b32_e32 v67, v98
	v_mov_b32_e32 v69, v102
	v_pk_add_f32 v[66:67], v[66:67], v[68:69]
	v_mov_b32_e32 v102, v95
	v_pk_add_f32 v[64:65], v[64:65], v[66:67]
	v_or_b32_e32 v66, s4, v108
	v_ashrrev_i32_e32 v67, 31, v66
	v_lshl_add_u64 v[66:67], v[66:67], 2, s[70:71]
	global_load_dword v97, v[66:67], off
	global_load_dword v96, v[66:67], off offset:128
	global_load_dword v95, v[66:67], off offset:256
	global_load_dword v94, v[66:67], off offset:384
	v_mov_b32_e32 v182, v198
	v_mov_b32_e32 v186, v175
	v_mov_b32_e32 v98, v179
	v_add_f32_e32 v76, v64, v65
	v_pk_add_f32 v[64:65], v[182:183], v[186:187]
	v_pk_add_f32 v[66:67], v[98:99], v[102:103]
	s_waitcnt vmcnt(8)
	v_mov_b32_e32 v81, v206
	v_pk_add_f32 v[64:65], v[64:65], v[66:67]
	v_mov_b32_e32 v66, v192
	v_add_f32_e32 v77, v64, v65
	v_mov_b32_e32 v64, v188
	s_waitcnt vmcnt(7)
	v_mov_b32_e32 v65, v210
	v_mov_b32_e32 v68, v202
	v_pk_add_f32 v[64:65], v[80:81], v[64:65]
	s_waitcnt vmcnt(6)
	v_mov_b32_e32 v67, v214
	v_mov_b32_e32 v210, v189
	v_mov_b32_e32 v214, v193
	s_waitcnt vmcnt(5)
	v_mov_b32_e32 v69, v218
	v_pk_add_f32 v[66:67], v[66:67], v[68:69]
	s_waitcnt vmcnt(4)
	v_mov_b32_e32 v206, v222
	v_pk_add_f32 v[64:65], v[64:65], v[66:67]
	v_mov_b32_e32 v218, v203
	v_add_f32_e32 v78, v64, v65
	v_pk_add_f32 v[64:65], v[206:207], v[210:211]
	v_pk_add_f32 v[66:67], v[214:215], v[218:219]
	v_mov_b32_e32 v68, v204
	v_pk_add_f32 v[64:65], v[64:65], v[66:67]
	v_mov_b32_e32 v66, v190
	v_add_f32_e32 v79, v64, v65
	v_mov_b32_e32 v64, v223
	v_mov_b32_e32 v65, v208
	v_mov_b32_e32 v67, v212
	v_pk_add_f32 v[64:65], v[64:65], v[66:67]
	v_mov_b32_e32 v66, v194
	v_mov_b32_e32 v67, v216
	v_mov_b32_e32 v69, v220
	v_pk_add_f32 v[66:67], v[66:67], v[68:69]
	v_mov_b32_e32 v208, v224
	v_pk_add_f32 v[64:65], v[64:65], v[66:67]
	v_mov_b32_e32 v212, v191
	v_mov_b32_e32 v216, v195
	v_mov_b32_e32 v220, v205
	v_add_f32_e32 v69, v64, v65
	v_pk_add_f32 v[64:65], v[208:209], v[212:213]
	v_pk_add_f32 v[66:67], v[216:217], v[220:221]
	s_mov_b64 s[4:5], -1
	v_pk_add_f32 v[64:65], v[64:65], v[66:67]
	v_fmamk_f32 v67, v123, 0x3a800000, v166
	v_rsq_f32_e32 v68, v67
	v_fmamk_f32 v67, v171, 0x3a800000, v166
	v_add_f32_e32 v65, v64, v65
	v_fmamk_f32 v64, v119, 0x3a800000, v166
	v_rsq_f32_e32 v70, v67
	v_fmamk_f32 v67, v225, 0x3a800000, v166
	v_rsq_f32_e32 v64, v64
	v_rsq_f32_e32 v74, v67
	v_fmamk_f32 v67, v125, 0x3a800000, v166
	v_rsq_f32_e32 v98, v67
	v_fmamk_f32 v67, v72, 0x3a800000, v166
	v_rsq_f32_e32 v100, v67
	v_fmamk_f32 v67, v71, 0x3a800000, v166
	v_rsq_f32_e32 v102, v67
	v_fmamk_f32 v67, v73, 0x3a800000, v166
	v_fmamk_f32 v65, v65, 0x3a800000, v166
	v_mov_b32_e32 v72, v32
	v_mov_b32_e32 v73, v48
	v_rsq_f32_e32 v106, v67
	v_fmamk_f32 v67, v75, 0x3a800000, v166
	v_fmamk_f32 v66, v121, 0x3a800000, v166
	v_rsq_f32_e32 v172, v67
	v_fmamk_f32 v67, v76, 0x3a800000, v166
	v_rsq_f32_e32 v66, v66
	v_rsq_f32_e32 v174, v67
	v_fmamk_f32 v67, v77, 0x3a800000, v166
	v_rsq_f32_e32 v176, v67
	v_fmamk_f32 v67, v78, 0x3a800000, v166
	v_rsq_f32_e32 v178, v67
	v_fmamk_f32 v67, v79, 0x3a800000, v166
	s_waitcnt vmcnt(2)
	v_pk_fma_f32 v[90:91], v[72:73], v[64:65], v[96:97] op_sel_hi:[1,0,1]
	v_mov_b32_e32 v72, v0
	v_mov_b32_e32 v73, v16
	v_mov_b32_e32 v16, v1
	v_mov_b32_e32 v0, v34
	v_mov_b32_e32 v1, v50
	v_pk_fma_f32 v[80:81], v[0:1], v[68:69], v[96:97] op_sel_hi:[1,0,1]
	v_mov_b32_e32 v0, v2
	v_mov_b32_e32 v1, v18
	s_waitcnt vmcnt(0)
	v_pk_fma_f32 v[82:83], v[0:1], v[68:69], v[94:95] op_sel_hi:[1,0,1]
	v_mov_b32_e32 v0, v36
	v_mov_b32_e32 v1, v52
	v_pk_fma_f32 v[92:93], v[72:73], v[64:65], v[94:95] op_sel_hi:[1,0,1]
	v_pk_fma_f32 v[72:73], v[0:1], v[74:75], v[96:97] op_sel_hi:[1,0,1]
	v_mov_b32_e32 v0, v4
	v_mov_b32_e32 v1, v20
	v_pk_fma_f32 v[74:75], v[0:1], v[74:75], v[94:95] op_sel_hi:[1,0,1]
	v_mov_b32_e32 v0, v38
	v_mov_b32_e32 v1, v54
	v_rsq_f32_e32 v180, v67
	v_fmamk_f32 v67, v69, 0x3a800000, v166
	v_rsq_f32_e32 v184, v65
	v_mov_b32_e32 v48, v33
	v_pk_fma_f32 v[64:65], v[0:1], v[100:101], v[96:97] op_sel_hi:[1,0,1]
	v_mov_b32_e32 v0, v6
	v_mov_b32_e32 v1, v22
	v_rsq_f32_e32 v182, v67
	v_pk_fma_f32 v[88:89], v[48:49], v[66:67], v[96:97] op_sel_hi:[1,0,1]
	v_pk_fma_f32 v[86:87], v[16:17], v[66:67], v[94:95] op_sel_hi:[1,0,1]
	v_pk_fma_f32 v[66:67], v[0:1], v[100:101], v[94:95] op_sel_hi:[1,0,1]
	v_mov_b32_e32 v0, v40
	v_mov_b32_e32 v1, v56
	v_mov_b32_e32 v54, v39
	v_pk_fma_f32 v[38:39], v[0:1], v[106:107], v[96:97] op_sel_hi:[1,0,1]
	v_mov_b32_e32 v0, v8
	v_mov_b32_e32 v1, v24
	v_pk_fma_f32 v[48:49], v[0:1], v[106:107], v[94:95] op_sel_hi:[1,0,1]
	v_mov_b32_e32 v24, v9
	v_mov_b32_e32 v0, v42
	v_mov_b32_e32 v1, v58
	v_mov_b32_e32 v52, v37
	v_pk_fma_f32 v[36:37], v[24:25], v[172:173], v[94:95] op_sel_hi:[1,0,1]
	v_pk_fma_f32 v[24:25], v[0:1], v[174:175], v[96:97] op_sel_hi:[1,0,1]
	v_mov_b32_e32 v0, v10
	v_mov_b32_e32 v1, v26
	v_pk_fma_f32 v[32:33], v[0:1], v[174:175], v[94:95] op_sel_hi:[1,0,1]
	v_mov_b32_e32 v0, v44
	v_mov_b32_e32 v1, v60
	v_mov_b32_e32 v18, v3
	v_pk_fma_f32 v[16:17], v[0:1], v[178:179], v[96:97] op_sel_hi:[1,0,1]
	v_mov_b32_e32 v0, v12
	v_mov_b32_e32 v1, v28
	v_pk_fma_f32 v[78:79], v[18:19], v[70:71], v[94:95] op_sel_hi:[1,0,1]
	v_pk_fma_f32 v[18:19], v[0:1], v[178:179], v[94:95] op_sel_hi:[1,0,1]
	v_mov_b32_e32 v0, v46
	v_mov_b32_e32 v1, v62
	v_mov_b32_e32 v50, v35
	v_mov_b32_e32 v20, v5
	v_mov_b32_e32 v22, v7
	v_mov_b32_e32 v56, v41
	v_mov_b32_e32 v58, v43
	v_mov_b32_e32 v26, v11
	v_mov_b32_e32 v60, v45
	v_mov_b32_e32 v28, v13
	v_pk_fma_f32 v[4:5], v[0:1], v[182:183], v[96:97] op_sel_hi:[1,0,1]
	v_mov_b32_e32 v0, v14
	v_mov_b32_e32 v1, v30
	v_mov_b32_e32 v62, v47
	v_mov_b32_e32 v30, v15
	v_pk_fma_f32 v[76:77], v[50:51], v[70:71], v[96:97] op_sel_hi:[1,0,1]
	v_pk_fma_f32 v[68:69], v[52:53], v[98:99], v[96:97] op_sel_hi:[1,0,1]
	v_pk_fma_f32 v[70:71], v[20:21], v[98:99], v[94:95] op_sel_hi:[1,0,1]
	v_pk_fma_f32 v[50:51], v[54:55], v[102:103], v[96:97] op_sel_hi:[1,0,1]
	v_pk_fma_f32 v[52:53], v[22:23], v[102:103], v[94:95] op_sel_hi:[1,0,1]
	v_pk_fma_f32 v[34:35], v[56:57], v[172:173], v[96:97] op_sel_hi:[1,0,1]
	v_pk_fma_f32 v[20:21], v[58:59], v[176:177], v[96:97] op_sel_hi:[1,0,1]
	v_pk_fma_f32 v[22:23], v[26:27], v[176:177], v[94:95] op_sel_hi:[1,0,1]
	v_pk_fma_f32 v[8:9], v[60:61], v[180:181], v[96:97] op_sel_hi:[1,0,1]
	v_pk_fma_f32 v[10:11], v[28:29], v[180:181], v[94:95] op_sel_hi:[1,0,1]
	v_pk_fma_f32 v[6:7], v[0:1], v[182:183], v[94:95] op_sel_hi:[1,0,1]
	v_pk_fma_f32 v[0:1], v[62:63], v[184:185], v[96:97] op_sel_hi:[1,0,1]
	v_pk_fma_f32 v[2:3], v[30:31], v[184:185], v[94:95] op_sel_hi:[1,0,1]
	s_cbranch_scc0 .LBB0_1189
	s_add_i32 s8, s84, -10
	s_and_b64 s[4:5], s[0:1], exec
	s_cselect_b32 s4, 0x100, 0
	s_add_i32 s4, s67, s4
	v_add_u32_e32 v31, s4, v133
	s_lshl_b32 s4, s8, 15
	s_lshl_b32 s71, s86, 8
	s_lshl_b32 s8, s8, 7
	s_add_i32 s71, s71, s8
	s_lshl_b32 s70, s86, 16
	v_or_b32_e32 v41, s71, v108
	s_add_i32 s70, s70, s4
	v_mul_lo_u32 v41, v41, s74
	v_or_b32_e32 v40, s70, v134
	v_add_u32_e32 v41, 0x200000, v41
	v_cndmask_b32_e64 v46, v40, v41, s[0:1]
	v_add_u32_e32 v40, v46, v31
	v_ashrrev_i32_e32 v41, 31, v40
	v_cvt_pk_bf16_f32 v42, v91, v89
	v_cvt_pk_bf16_f32 v43, v81, v77
	v_lshl_add_u64 v[40:41], v[40:41], 1, s[20:21]
	global_store_dwordx2 v[40:41], v[42:43], off
	v_or_b32_e32 v40, 8, v31
	v_add_u32_e32 v42, v46, v40
	v_ashrrev_i32_e32 v43, 31, v42
	v_cvt_pk_bf16_f32 v44, v73, v69
	v_cvt_pk_bf16_f32 v45, v65, v51
	v_lshl_add_u64 v[42:43], v[42:43], 1, s[20:21]
	v_or_b32_e32 v41, 16, v31
	global_store_dwordx2 v[42:43], v[44:45], off
	v_add_u32_e32 v42, v46, v41
	v_ashrrev_i32_e32 v43, 31, v42
	v_cvt_pk_bf16_f32 v44, v39, v35
	v_cvt_pk_bf16_f32 v45, v25, v21
	v_lshl_add_u64 v[42:43], v[42:43], 1, s[20:21]
	global_store_dwordx2 v[42:43], v[44:45], off
	v_or_b32_e32 v42, 24, v31
	v_add_u32_e32 v44, v46, v42
	v_ashrrev_i32_e32 v45, 31, v44
	v_cndmask_b32_e64 v43, 0, 1, s[68:69]
	v_or_b32_e32 v30, 1, v118
	v_or_b32_e32 v29, 2, v118
	v_or_b32_e32 v28, 3, v118
	v_or_b32_e32 v27, 10, v118
	v_or_b32_e32 v26, 11, v118
	v_or_b32_e32 v15, 18, v118
	v_or_b32_e32 v14, 19, v118
	v_or_b32_e32 v13, 26, v118
	v_or_b32_e32 v12, 27, v118
	v_cvt_pk_bf16_f32 v46, v17, v9
	v_cvt_pk_bf16_f32 v47, v5, v1
	v_lshl_add_u64 v[44:45], v[44:45], 1, s[20:21]
	v_cmp_ne_u32_e64 s[4:5], 1, v43
	s_andn2_b64 vcc, exec, s[68:69]
	global_store_dwordx2 v[44:45], v[46:47], off
	s_cbranch_vccnz .LBB0_1182
	v_or_b32_e32 v43, s8, v108
	v_lshl_add_u32 v44, v118, 8, v43
	v_ashrrev_i32_e32 v45, 31, v44
	v_lshl_add_u64 v[44:45], v[44:45], 2, s[22:23]
	global_store_dword v[44:45], v91, off sc1
	v_lshl_add_u32 v44, v30, 8, v43
	v_ashrrev_i32_e32 v45, 31, v44
	v_lshl_add_u64 v[44:45], v[44:45], 2, s[22:23]
	global_store_dword v[44:45], v89, off sc1
	v_lshl_add_u32 v44, v29, 8, v43
	v_ashrrev_i32_e32 v45, 31, v44
	v_lshl_add_u64 v[44:45], v[44:45], 2, s[22:23]
	global_store_dword v[44:45], v81, off sc1
	v_lshl_add_u32 v44, v28, 8, v43
	v_ashrrev_i32_e32 v45, 31, v44
	v_lshl_add_u64 v[44:45], v[44:45], 2, s[22:23]
	global_store_dword v[44:45], v77, off sc1
	v_lshl_add_u32 v44, v120, 8, v43
	v_ashrrev_i32_e32 v45, 31, v44
	v_lshl_add_u64 v[44:45], v[44:45], 2, s[22:23]
	global_store_dword v[44:45], v73, off sc1
	v_lshl_add_u32 v44, v122, 8, v43
	v_ashrrev_i32_e32 v45, 31, v44
	v_lshl_add_u64 v[44:45], v[44:45], 2, s[22:23]
	global_store_dword v[44:45], v69, off sc1
	v_lshl_add_u32 v44, v27, 8, v43
	v_ashrrev_i32_e32 v45, 31, v44
	v_lshl_add_u64 v[44:45], v[44:45], 2, s[22:23]
	global_store_dword v[44:45], v65, off sc1
	v_lshl_add_u32 v44, v26, 8, v43
	v_ashrrev_i32_e32 v45, 31, v44
	v_lshl_add_u64 v[44:45], v[44:45], 2, s[22:23]
	global_store_dword v[44:45], v51, off sc1
	v_lshl_add_u32 v44, v124, 8, v43
	v_ashrrev_i32_e32 v45, 31, v44
	v_lshl_add_u64 v[44:45], v[44:45], 2, s[22:23]
	global_store_dword v[44:45], v39, off sc1
	v_lshl_add_u32 v44, v126, 8, v43
	v_ashrrev_i32_e32 v45, 31, v44
	v_lshl_add_u64 v[44:45], v[44:45], 2, s[22:23]
	global_store_dword v[44:45], v35, off sc1
	v_lshl_add_u32 v44, v15, 8, v43
	v_ashrrev_i32_e32 v45, 31, v44
	v_lshl_add_u64 v[44:45], v[44:45], 2, s[22:23]
	global_store_dword v[44:45], v25, off sc1
	v_lshl_add_u32 v44, v14, 8, v43
	v_ashrrev_i32_e32 v45, 31, v44
	v_lshl_add_u64 v[44:45], v[44:45], 2, s[22:23]
	global_store_dword v[44:45], v21, off sc1
	v_lshl_add_u32 v44, v84, 8, v43
	v_ashrrev_i32_e32 v45, 31, v44
	v_lshl_add_u64 v[44:45], v[44:45], 2, s[22:23]
	global_store_dword v[44:45], v17, off sc1
	v_lshl_add_u32 v44, v104, 8, v43
	v_ashrrev_i32_e32 v45, 31, v44
	v_lshl_add_u64 v[44:45], v[44:45], 2, s[22:23]
	global_store_dword v[44:45], v9, off sc1
	v_lshl_add_u32 v44, v13, 8, v43
	v_ashrrev_i32_e32 v45, 31, v44
	v_lshl_add_u64 v[44:45], v[44:45], 2, s[22:23]
	global_store_dword v[44:45], v5, off sc1
	v_lshl_add_u32 v44, v12, 8, v43
	v_ashrrev_i32_e32 v45, 31, v44
	v_lshl_add_u64 v[44:45], v[44:45], 2, s[22:23]
	global_store_dword v[44:45], v1, off sc1
.LBB0_1182:
	v_or_b32_e32 v44, s71, v135
	v_mul_lo_u32 v44, v44, s74
	v_or_b32_e32 v43, s70, v136
	v_add_u32_e32 v44, 0x200000, v44
	v_cndmask_b32_e64 v43, v43, v44, s[0:1]
	v_add_u32_e32 v44, v43, v31
	v_ashrrev_i32_e32 v45, 31, v44
	v_cvt_pk_bf16_f32 v46, v90, v88
	v_cvt_pk_bf16_f32 v47, v80, v76
	v_lshl_add_u64 v[44:45], v[44:45], 1, s[20:21]
	global_store_dwordx2 v[44:45], v[46:47], off
	v_add_u32_e32 v44, v43, v40
	v_ashrrev_i32_e32 v45, 31, v44
	v_cvt_pk_bf16_f32 v46, v72, v68
	v_cvt_pk_bf16_f32 v47, v64, v50
	v_lshl_add_u64 v[44:45], v[44:45], 1, s[20:21]
	global_store_dwordx2 v[44:45], v[46:47], off
	v_add_u32_e32 v44, v43, v41
	v_ashrrev_i32_e32 v45, 31, v44
	v_cvt_pk_bf16_f32 v46, v38, v34
	v_cvt_pk_bf16_f32 v47, v24, v20
	v_lshl_add_u64 v[44:45], v[44:45], 1, s[20:21]
	global_store_dwordx2 v[44:45], v[46:47], off
	v_add_u32_e32 v44, v43, v42
	v_ashrrev_i32_e32 v45, 31, v44
	v_cvt_pk_bf16_f32 v46, v16, v8
	v_cvt_pk_bf16_f32 v47, v4, v0
	v_lshl_add_u64 v[44:45], v[44:45], 1, s[20:21]
	s_and_b64 vcc, exec, s[4:5]
	global_store_dwordx2 v[44:45], v[46:47], off
	s_cbranch_vccnz .LBB0_1184
	v_or_b32_e32 v43, s8, v135
	v_lshl_add_u32 v44, v118, 8, v43
	v_ashrrev_i32_e32 v45, 31, v44
	v_lshl_add_u64 v[44:45], v[44:45], 2, s[22:23]
	global_store_dword v[44:45], v90, off sc1
	v_lshl_add_u32 v44, v30, 8, v43
	v_ashrrev_i32_e32 v45, 31, v44
	v_lshl_add_u64 v[44:45], v[44:45], 2, s[22:23]
	global_store_dword v[44:45], v88, off sc1
	v_lshl_add_u32 v44, v29, 8, v43
	v_ashrrev_i32_e32 v45, 31, v44
	v_lshl_add_u64 v[44:45], v[44:45], 2, s[22:23]
	global_store_dword v[44:45], v80, off sc1
	v_lshl_add_u32 v44, v28, 8, v43
	v_ashrrev_i32_e32 v45, 31, v44
	v_lshl_add_u64 v[44:45], v[44:45], 2, s[22:23]
	global_store_dword v[44:45], v76, off sc1
	v_lshl_add_u32 v44, v120, 8, v43
	v_ashrrev_i32_e32 v45, 31, v44
	v_lshl_add_u64 v[44:45], v[44:45], 2, s[22:23]
	global_store_dword v[44:45], v72, off sc1
	v_lshl_add_u32 v44, v122, 8, v43
	v_ashrrev_i32_e32 v45, 31, v44
	v_lshl_add_u64 v[44:45], v[44:45], 2, s[22:23]
	global_store_dword v[44:45], v68, off sc1
	v_lshl_add_u32 v44, v27, 8, v43
	v_ashrrev_i32_e32 v45, 31, v44
	v_lshl_add_u64 v[44:45], v[44:45], 2, s[22:23]
	global_store_dword v[44:45], v64, off sc1
	v_lshl_add_u32 v44, v26, 8, v43
	v_ashrrev_i32_e32 v45, 31, v44
	v_lshl_add_u64 v[44:45], v[44:45], 2, s[22:23]
	global_store_dword v[44:45], v50, off sc1
	v_lshl_add_u32 v44, v124, 8, v43
	v_ashrrev_i32_e32 v45, 31, v44
	v_lshl_add_u64 v[44:45], v[44:45], 2, s[22:23]
	global_store_dword v[44:45], v38, off sc1
	v_lshl_add_u32 v44, v126, 8, v43
	v_ashrrev_i32_e32 v45, 31, v44
	v_lshl_add_u64 v[44:45], v[44:45], 2, s[22:23]
	global_store_dword v[44:45], v34, off sc1
	v_lshl_add_u32 v44, v15, 8, v43
	v_ashrrev_i32_e32 v45, 31, v44
	v_lshl_add_u64 v[44:45], v[44:45], 2, s[22:23]
	global_store_dword v[44:45], v24, off sc1
	v_lshl_add_u32 v44, v14, 8, v43
	v_ashrrev_i32_e32 v45, 31, v44
	v_lshl_add_u64 v[44:45], v[44:45], 2, s[22:23]
	global_store_dword v[44:45], v20, off sc1
	v_lshl_add_u32 v44, v84, 8, v43
	v_ashrrev_i32_e32 v45, 31, v44
	v_lshl_add_u64 v[44:45], v[44:45], 2, s[22:23]
	global_store_dword v[44:45], v16, off sc1
	v_lshl_add_u32 v44, v104, 8, v43
	v_ashrrev_i32_e32 v45, 31, v44
	v_lshl_add_u64 v[44:45], v[44:45], 2, s[22:23]
	global_store_dword v[44:45], v8, off sc1
	v_lshl_add_u32 v44, v13, 8, v43
	v_ashrrev_i32_e32 v45, 31, v44
	v_lshl_add_u64 v[44:45], v[44:45], 2, s[22:23]
	global_store_dword v[44:45], v4, off sc1
	v_lshl_add_u32 v44, v12, 8, v43
	v_ashrrev_i32_e32 v45, 31, v44
	v_lshl_add_u64 v[44:45], v[44:45], 2, s[22:23]
	global_store_dword v[44:45], v0, off sc1
.LBB0_1184:
	v_or_b32_e32 v44, s71, v137
	v_mul_lo_u32 v44, v44, s74
	v_or_b32_e32 v43, s70, v138
	v_add_u32_e32 v44, 0x200000, v44
	v_cndmask_b32_e64 v43, v43, v44, s[0:1]
	v_add_u32_e32 v44, v43, v31
	v_ashrrev_i32_e32 v45, 31, v44
	v_cvt_pk_bf16_f32 v46, v93, v87
	v_cvt_pk_bf16_f32 v47, v83, v79
	v_lshl_add_u64 v[44:45], v[44:45], 1, s[20:21]
	global_store_dwordx2 v[44:45], v[46:47], off
	v_add_u32_e32 v44, v43, v40
	v_ashrrev_i32_e32 v45, 31, v44
	v_cvt_pk_bf16_f32 v46, v75, v71
	v_cvt_pk_bf16_f32 v47, v67, v53
	v_lshl_add_u64 v[44:45], v[44:45], 1, s[20:21]
	global_store_dwordx2 v[44:45], v[46:47], off
	v_add_u32_e32 v44, v43, v41
	v_ashrrev_i32_e32 v45, 31, v44
	v_cvt_pk_bf16_f32 v46, v49, v37
	v_cvt_pk_bf16_f32 v47, v33, v23
	v_lshl_add_u64 v[44:45], v[44:45], 1, s[20:21]
	global_store_dwordx2 v[44:45], v[46:47], off
	v_add_u32_e32 v44, v43, v42
	v_ashrrev_i32_e32 v45, 31, v44
	v_cvt_pk_bf16_f32 v46, v19, v11
	v_cvt_pk_bf16_f32 v47, v7, v3
	v_lshl_add_u64 v[44:45], v[44:45], 1, s[20:21]
	s_and_b64 vcc, exec, s[4:5]
	global_store_dwordx2 v[44:45], v[46:47], off
	s_cbranch_vccnz .LBB0_1186
	v_or_b32_e32 v43, s8, v137
	v_lshl_add_u32 v44, v118, 8, v43
	v_ashrrev_i32_e32 v45, 31, v44
	v_lshl_add_u64 v[44:45], v[44:45], 2, s[22:23]
	global_store_dword v[44:45], v93, off sc1
	v_lshl_add_u32 v44, v30, 8, v43
	v_ashrrev_i32_e32 v45, 31, v44
	v_lshl_add_u64 v[44:45], v[44:45], 2, s[22:23]
	global_store_dword v[44:45], v87, off sc1
	v_lshl_add_u32 v44, v29, 8, v43
	v_ashrrev_i32_e32 v45, 31, v44
	v_lshl_add_u64 v[44:45], v[44:45], 2, s[22:23]
	global_store_dword v[44:45], v83, off sc1
	v_lshl_add_u32 v44, v28, 8, v43
	v_ashrrev_i32_e32 v45, 31, v44
	v_lshl_add_u64 v[44:45], v[44:45], 2, s[22:23]
	global_store_dword v[44:45], v79, off sc1
	v_lshl_add_u32 v44, v120, 8, v43
	v_ashrrev_i32_e32 v45, 31, v44
	v_lshl_add_u64 v[44:45], v[44:45], 2, s[22:23]
	global_store_dword v[44:45], v75, off sc1
	v_lshl_add_u32 v44, v122, 8, v43
	v_ashrrev_i32_e32 v45, 31, v44
	v_lshl_add_u64 v[44:45], v[44:45], 2, s[22:23]
	global_store_dword v[44:45], v71, off sc1
	v_lshl_add_u32 v44, v27, 8, v43
	v_ashrrev_i32_e32 v45, 31, v44
	v_lshl_add_u64 v[44:45], v[44:45], 2, s[22:23]
	global_store_dword v[44:45], v67, off sc1
	v_lshl_add_u32 v44, v26, 8, v43
	v_ashrrev_i32_e32 v45, 31, v44
	v_lshl_add_u64 v[44:45], v[44:45], 2, s[22:23]
	global_store_dword v[44:45], v53, off sc1
	v_lshl_add_u32 v44, v124, 8, v43
	v_ashrrev_i32_e32 v45, 31, v44
	v_lshl_add_u64 v[44:45], v[44:45], 2, s[22:23]
	global_store_dword v[44:45], v49, off sc1
	v_lshl_add_u32 v44, v126, 8, v43
	v_ashrrev_i32_e32 v45, 31, v44
	v_lshl_add_u64 v[44:45], v[44:45], 2, s[22:23]
	global_store_dword v[44:45], v37, off sc1
	v_lshl_add_u32 v44, v15, 8, v43
	v_ashrrev_i32_e32 v45, 31, v44
	v_lshl_add_u64 v[44:45], v[44:45], 2, s[22:23]
	global_store_dword v[44:45], v33, off sc1
	v_lshl_add_u32 v44, v14, 8, v43
	v_ashrrev_i32_e32 v45, 31, v44
	v_lshl_add_u64 v[44:45], v[44:45], 2, s[22:23]
	global_store_dword v[44:45], v23, off sc1
	v_lshl_add_u32 v44, v84, 8, v43
	v_ashrrev_i32_e32 v45, 31, v44
	v_lshl_add_u64 v[44:45], v[44:45], 2, s[22:23]
	global_store_dword v[44:45], v19, off sc1
	v_lshl_add_u32 v44, v104, 8, v43
	v_ashrrev_i32_e32 v45, 31, v44
	v_lshl_add_u64 v[44:45], v[44:45], 2, s[22:23]
	global_store_dword v[44:45], v11, off sc1
	v_lshl_add_u32 v44, v13, 8, v43
	v_ashrrev_i32_e32 v45, 31, v44
	v_lshl_add_u64 v[44:45], v[44:45], 2, s[22:23]
	global_store_dword v[44:45], v7, off sc1
	v_lshl_add_u32 v44, v12, 8, v43
	v_ashrrev_i32_e32 v45, 31, v44
	v_lshl_add_u64 v[44:45], v[44:45], 2, s[22:23]
	global_store_dword v[44:45], v3, off sc1
.LBB0_1186:
	v_or_b32_e32 v44, s71, v139
	v_mul_lo_u32 v44, v44, s74
	v_or_b32_e32 v43, s70, v140
	v_add_u32_e32 v44, 0x200000, v44
	v_cndmask_b32_e64 v43, v43, v44, s[0:1]
	v_add_u32_e32 v44, v43, v31
	v_ashrrev_i32_e32 v45, 31, v44
	v_cvt_pk_bf16_f32 v46, v92, v86
	v_cvt_pk_bf16_f32 v47, v82, v78
	v_lshl_add_u64 v[44:45], v[44:45], 1, s[20:21]
	global_store_dwordx2 v[44:45], v[46:47], off
	v_add_u32_e32 v44, v43, v40
	v_ashrrev_i32_e32 v45, 31, v44
	v_add_u32_e32 v40, v43, v41
	v_cvt_pk_bf16_f32 v46, v74, v70
	v_cvt_pk_bf16_f32 v47, v66, v52
	v_lshl_add_u64 v[44:45], v[44:45], 1, s[20:21]
	v_ashrrev_i32_e32 v41, 31, v40
	global_store_dwordx2 v[44:45], v[46:47], off
	v_cvt_pk_bf16_f32 v44, v48, v36
	v_cvt_pk_bf16_f32 v45, v32, v22
	v_lshl_add_u64 v[40:41], v[40:41], 1, s[20:21]
	global_store_dwordx2 v[40:41], v[44:45], off
	v_add_u32_e32 v40, v43, v42
	v_ashrrev_i32_e32 v41, 31, v40
	v_cvt_pk_bf16_f32 v42, v18, v10
	v_cvt_pk_bf16_f32 v43, v6, v2
	v_lshl_add_u64 v[40:41], v[40:41], 1, s[20:21]
	s_and_b64 vcc, exec, s[4:5]
	global_store_dwordx2 v[40:41], v[42:43], off
	s_cbranch_vccnz .LBB0_1188
	v_or_b32_e32 v42, s8, v139
	v_lshl_add_u32 v30, v30, 8, v42
	v_ashrrev_i32_e32 v31, 31, v30
	v_lshl_add_u64 v[30:31], v[30:31], 2, s[22:23]
	v_lshl_add_u32 v28, v28, 8, v42
	global_store_dword v[30:31], v86, off sc1
	v_lshl_add_u32 v30, v29, 8, v42
	v_ashrrev_i32_e32 v29, 31, v28
	v_lshl_add_u64 v[28:29], v[28:29], 2, s[22:23]
	global_store_dword v[28:29], v78, off sc1
	v_lshl_add_u32 v28, v120, 8, v42
	v_ashrrev_i32_e32 v29, 31, v28
	v_lshl_add_u64 v[28:29], v[28:29], 2, s[22:23]
	global_store_dword v[28:29], v74, off sc1
	v_lshl_add_u32 v28, v122, 8, v42
	v_ashrrev_i32_e32 v29, 31, v28
	v_lshl_add_u64 v[28:29], v[28:29], 2, s[22:23]
	v_lshl_add_u32 v26, v26, 8, v42
	global_store_dword v[28:29], v70, off sc1
	v_lshl_add_u32 v28, v27, 8, v42
	v_ashrrev_i32_e32 v27, 31, v26
	v_lshl_add_u64 v[26:27], v[26:27], 2, s[22:23]
	global_store_dword v[26:27], v52, off sc1
	v_lshl_add_u32 v26, v124, 8, v42
	v_ashrrev_i32_e32 v27, 31, v26
	v_lshl_add_u64 v[26:27], v[26:27], 2, s[22:23]
	global_store_dword v[26:27], v48, off sc1
	v_lshl_add_u32 v26, v126, 8, v42
	v_ashrrev_i32_e32 v27, 31, v26
	v_lshl_add_u64 v[26:27], v[26:27], 2, s[22:23]
	v_lshl_add_u32 v14, v14, 8, v42
	global_store_dword v[26:27], v36, off sc1
	v_lshl_add_u32 v26, v15, 8, v42
	v_ashrrev_i32_e32 v15, 31, v14
	v_lshl_add_u64 v[14:15], v[14:15], 2, s[22:23]
	global_store_dword v[14:15], v22, off sc1
	v_lshl_add_u32 v14, v84, 8, v42
	v_ashrrev_i32_e32 v15, 31, v14
	v_lshl_add_u64 v[14:15], v[14:15], 2, s[22:23]
	global_store_dword v[14:15], v18, off sc1
	v_lshl_add_u32 v14, v104, 8, v42
	v_ashrrev_i32_e32 v15, 31, v14
	v_lshl_add_u64 v[14:15], v[14:15], 2, s[22:23]
	v_lshl_add_u32 v40, v118, 8, v42
	global_store_dword v[14:15], v10, off sc1
	v_lshl_add_u32 v14, v13, 8, v42
	v_lshl_add_u32 v12, v12, 8, v42
	v_ashrrev_i32_e32 v41, 31, v40
	v_ashrrev_i32_e32 v31, 31, v30
	v_ashrrev_i32_e32 v29, 31, v28
	v_ashrrev_i32_e32 v27, 31, v26
	v_ashrrev_i32_e32 v15, 31, v14
	v_ashrrev_i32_e32 v13, 31, v12
	v_lshl_add_u64 v[40:41], v[40:41], 2, s[22:23]
	v_lshl_add_u64 v[30:31], v[30:31], 2, s[22:23]
	v_lshl_add_u64 v[28:29], v[28:29], 2, s[22:23]
	v_lshl_add_u64 v[26:27], v[26:27], 2, s[22:23]
	v_lshl_add_u64 v[14:15], v[14:15], 2, s[22:23]
	v_lshl_add_u64 v[12:13], v[12:13], 2, s[22:23]
	global_store_dword v[40:41], v92, off sc1
	global_store_dword v[30:31], v82, off sc1
	global_store_dword v[28:29], v66, off sc1
	global_store_dword v[26:27], v32, off sc1
	global_store_dword v[14:15], v6, off sc1
	global_store_dword v[12:13], v2, off sc1

.LBB0_1194:
	v_pk_mul_f32 v[28:29], v[88:89], v[88:89]
	v_pk_mul_f32 v[54:55], v[86:87], v[86:87]
	v_add_f32_e32 v28, v29, v28
	v_add_f32_e32 v28, v28, v55
	v_add_f32_e32 v28, v28, v54
	ds_bpermute_b32 v29, v42, v28
	s_xor_b64 s[70:71], s[70:71], -1
	s_and_b64 s[0:1], s[68:69], exec
	s_cselect_b32 s0, s83, 0xdf9f000
	s_cselect_b32 s8, s66, s72
	s_waitcnt lgkmcnt(0)
	v_add_f32_e32 v28, v28, v29
	ds_bpermute_b32 v29, v44, v28
	s_cselect_b32 s72, s84, s73
	s_add_u32 s73, s14, s0
	s_addc_u32 s84, s15, 0
	s_and_b64 s[0:1], s[68:69], exec
	s_waitcnt lgkmcnt(0)
	v_add_f32_e32 v47, v28, v29
	ds_bpermute_b32 v54, v45, v47
	s_cselect_b32 s68, 10, 8
	s_lshl_b32 s0, s72, 7
	s_ashr_i32 s1, s0, 31
	s_lshl_b64 s[0:1], s[0:1], 1
	s_waitcnt lgkmcnt(0)
	v_add_f32_e32 v47, v47, v54
	ds_bpermute_b32 v56, v46, v47
	s_add_u32 s0, s73, s0
	v_add_u32_e32 v55, s8, v133
	s_addc_u32 s1, s84, s1
	v_lshlrev_b32_e32 v106, 1, v108
	s_waitcnt lgkmcnt(0)
	v_add_f32_e32 v47, v47, v56
	ds_bpermute_b32 v56, v43, v47
	v_lshlrev_b32_e32 v54, s68, v55
	v_lshl_add_u64 v[28:29], s[0:1], 0, v[106:107]
	v_ashrrev_i32_e32 v55, 31, v54
	v_lshl_add_u64 v[54:55], v[54:55], 1, v[28:29]
	v_cvt_pk_bf16_f32 v40, v40, s0
	global_store_short v[54:55], v40, off offset:64
	s_waitcnt lgkmcnt(0)
	v_add_f32_e32 v40, v47, v56
	v_fmamk_f32 v40, v40, 0x3c000000, v166
	v_rsq_f32_e32 v40, v40
	v_cvt_pk_bf16_f32 v41, v41, s0
	v_cvt_pk_bf16_f32 v31, v31, s0
	v_cvt_pk_bf16_f32 v30, v30, s0
	global_store_short v[54:55], v41, off
	global_store_short v[54:55], v31, off offset:128
	global_store_short v[54:55], v30, off offset:192
	v_pk_mul_f32 v[30:31], v[12:13], v[40:41] op_sel_hi:[1,0]
	v_pk_mul_f32 v[40:41], v[14:15], v[40:41] op_sel_hi:[1,0]
	v_cndmask_b32_e64 v47, 0, 1, s[70:71]
	v_pk_mul_f32 v[30:31], v[88:89], v[30:31]
	v_cmp_ne_u32_e64 s[0:1], 1, v47
	s_andn2_b64 vcc, exec, s[70:71]
	v_pk_mul_f32 v[40:41], v[86:87], v[40:41]
	s_cbranch_vccnz .LBB0_1196
	v_add_lshl_u32 v54, s66, v141, 8
	v_ashrrev_i32_e32 v55, 31, v54
	v_lshl_add_u64 v[54:55], v[54:55], 2, v[26:27]
	global_store_dword v[54:55], v31, off sc1
	global_store_dword v[54:55], v30, off offset:128 sc1
	global_store_dword v[54:55], v41, off offset:256 sc1
	global_store_dword v[54:55], v40, off offset:384 sc1

.LBB0_1198:
	v_pk_mul_f32 v[54:55], v[80:81], v[80:81]
	v_pk_mul_f32 v[56:57], v[82:83], v[82:83]
	v_add_f32_e32 v47, v55, v54
	v_add_f32_e32 v47, v47, v57
	v_add_f32_e32 v47, v47, v56
	ds_bpermute_b32 v54, v42, v47
	v_cvt_pk_bf16_f32 v56, v31, s0
	v_cvt_pk_bf16_f32 v57, v40, s0
	v_add_u32_e32 v55, s8, v141
	v_cvt_pk_bf16_f32 v41, v41, s0
	s_waitcnt lgkmcnt(0)
	v_add_f32_e32 v47, v47, v54
	ds_bpermute_b32 v54, v44, v47
	s_and_b64 vcc, exec, s[0:1]
	s_waitcnt lgkmcnt(0)
	v_add_f32_e32 v47, v47, v54
	ds_bpermute_b32 v54, v45, v47
	s_waitcnt lgkmcnt(0)
	v_add_f32_e32 v31, v47, v54
	ds_bpermute_b32 v47, v46, v31
	v_cvt_pk_bf16_f32 v54, v30, s0
	v_lshlrev_b32_e32 v30, s68, v55
	s_waitcnt lgkmcnt(0)
	v_add_f32_e32 v40, v31, v47
	ds_bpermute_b32 v47, v43, v40
	v_ashrrev_i32_e32 v31, 31, v30
	v_lshl_add_u64 v[30:31], v[30:31], 1, v[28:29]
	global_store_short v[30:31], v56, off
	global_store_short v[30:31], v54, off offset:64
	global_store_short v[30:31], v41, off offset:128
	global_store_short v[30:31], v57, off offset:192
	s_waitcnt lgkmcnt(0)
	v_add_f32_e32 v40, v40, v47
	v_fmamk_f32 v40, v40, 0x3c000000, v166
	v_rsq_f32_e32 v40, v40
	s_nop 0
	v_pk_mul_f32 v[30:31], v[12:13], v[40:41] op_sel_hi:[1,0]
	v_pk_mul_f32 v[54:55], v[14:15], v[40:41] op_sel_hi:[1,0]
	v_pk_mul_f32 v[40:41], v[80:81], v[30:31]
	v_pk_mul_f32 v[30:31], v[82:83], v[54:55]
	s_cbranch_vccnz .LBB0_1200
	v_add_lshl_u32 v54, s66, v142, 8
	v_ashrrev_i32_e32 v55, 31, v54
	v_lshl_add_u64 v[54:55], v[54:55], 2, v[26:27]
	global_store_dword v[54:55], v41, off sc1
	global_store_dword v[54:55], v40, off offset:128 sc1
	global_store_dword v[54:55], v31, off offset:256 sc1
	global_store_dword v[54:55], v30, off offset:384 sc1

.LBB0_1202:
	v_pk_mul_f32 v[54:55], v[76:77], v[76:77]
	v_pk_mul_f32 v[56:57], v[78:79], v[78:79]
	v_add_f32_e32 v47, v55, v54
	v_add_f32_e32 v47, v47, v57
	v_add_f32_e32 v47, v47, v56
	ds_bpermute_b32 v54, v42, v47
	v_cvt_pk_bf16_f32 v56, v40, s0
	v_add_u32_e32 v55, s8, v142
	v_cvt_pk_bf16_f32 v58, v30, s0
	v_lshlrev_b32_e32 v30, s68, v55
	s_waitcnt lgkmcnt(0)
	v_add_f32_e32 v47, v47, v54
	ds_bpermute_b32 v54, v44, v47
	v_cvt_pk_bf16_f32 v57, v31, s0
	v_ashrrev_i32_e32 v31, 31, v30
	v_cvt_pk_bf16_f32 v41, v41, s0
	v_lshl_add_u64 v[30:31], v[30:31], 1, v[28:29]
	s_waitcnt lgkmcnt(0)
	v_add_f32_e32 v47, v47, v54
	ds_bpermute_b32 v54, v45, v47
	global_store_short v[30:31], v41, off
	global_store_short v[30:31], v56, off offset:64
	global_store_short v[30:31], v57, off offset:128
	global_store_short v[30:31], v58, off offset:192
	s_and_b64 vcc, exec, s[0:1]
	s_waitcnt lgkmcnt(0)
	v_add_f32_e32 v47, v47, v54
	ds_bpermute_b32 v54, v46, v47
	s_waitcnt lgkmcnt(0)
	v_add_f32_e32 v40, v47, v54
	ds_bpermute_b32 v47, v43, v40
	s_waitcnt lgkmcnt(0)
	v_add_f32_e32 v40, v40, v47
	v_fmamk_f32 v40, v40, 0x3c000000, v166
	v_rsq_f32_e32 v40, v40
	s_nop 0
	v_pk_mul_f32 v[30:31], v[12:13], v[40:41] op_sel_hi:[1,0]
	v_pk_mul_f32 v[54:55], v[14:15], v[40:41] op_sel_hi:[1,0]
	v_pk_mul_f32 v[40:41], v[76:77], v[30:31]
	v_pk_mul_f32 v[30:31], v[78:79], v[54:55]
	s_cbranch_vccnz .LBB0_1204
	v_add_lshl_u32 v54, s66, v143, 8
	v_ashrrev_i32_e32 v55, 31, v54
	v_lshl_add_u64 v[54:55], v[54:55], 2, v[26:27]
	global_store_dword v[54:55], v41, off sc1
	global_store_dword v[54:55], v40, off offset:128 sc1
	global_store_dword v[54:55], v31, off offset:256 sc1
	global_store_dword v[54:55], v30, off offset:384 sc1

.LBB0_1206:
	v_pk_mul_f32 v[54:55], v[72:73], v[72:73]
	v_pk_mul_f32 v[56:57], v[74:75], v[74:75]
	v_add_f32_e32 v47, v55, v54
	v_add_f32_e32 v47, v47, v57
	v_add_f32_e32 v47, v47, v56
	ds_bpermute_b32 v54, v42, v47
	v_cvt_pk_bf16_f32 v56, v40, s0
	v_add_u32_e32 v55, s8, v143
	v_cvt_pk_bf16_f32 v58, v30, s0
	v_lshlrev_b32_e32 v30, s68, v55
	s_waitcnt lgkmcnt(0)
	v_add_f32_e32 v47, v47, v54
	ds_bpermute_b32 v54, v44, v47
	v_cvt_pk_bf16_f32 v57, v31, s0
	v_ashrrev_i32_e32 v31, 31, v30
	v_cvt_pk_bf16_f32 v41, v41, s0
	v_lshl_add_u64 v[30:31], v[30:31], 1, v[28:29]
	s_waitcnt lgkmcnt(0)
	v_add_f32_e32 v47, v47, v54
	ds_bpermute_b32 v54, v45, v47
	global_store_short v[30:31], v41, off
	global_store_short v[30:31], v56, off offset:64
	global_store_short v[30:31], v57, off offset:128
	global_store_short v[30:31], v58, off offset:192
	s_and_b64 vcc, exec, s[0:1]
	s_waitcnt lgkmcnt(0)
	v_add_f32_e32 v47, v47, v54
	ds_bpermute_b32 v54, v46, v47
	s_waitcnt lgkmcnt(0)
	v_add_f32_e32 v40, v47, v54
	ds_bpermute_b32 v47, v43, v40
	s_waitcnt lgkmcnt(0)
	v_add_f32_e32 v40, v40, v47
	v_fmamk_f32 v40, v40, 0x3c000000, v166
	v_rsq_f32_e32 v40, v40
	s_nop 0
	v_pk_mul_f32 v[30:31], v[12:13], v[40:41] op_sel_hi:[1,0]
	v_pk_mul_f32 v[54:55], v[14:15], v[40:41] op_sel_hi:[1,0]
	v_pk_mul_f32 v[40:41], v[72:73], v[30:31]
	v_pk_mul_f32 v[30:31], v[74:75], v[54:55]
	s_cbranch_vccnz .LBB0_1208
	v_add_lshl_u32 v54, s66, v144, 8
	v_ashrrev_i32_e32 v55, 31, v54
	v_lshl_add_u64 v[54:55], v[54:55], 2, v[26:27]
	global_store_dword v[54:55], v41, off sc1
	global_store_dword v[54:55], v40, off offset:128 sc1
	global_store_dword v[54:55], v31, off offset:256 sc1
	global_store_dword v[54:55], v30, off offset:384 sc1

.LBB0_1210:
	v_pk_mul_f32 v[54:55], v[68:69], v[68:69]
	v_pk_mul_f32 v[56:57], v[70:71], v[70:71]
	v_add_f32_e32 v47, v55, v54
	v_add_f32_e32 v47, v47, v57
	v_add_f32_e32 v47, v47, v56
	ds_bpermute_b32 v54, v42, v47
	v_cvt_pk_bf16_f32 v56, v40, s0
	v_add_u32_e32 v55, s8, v144
	v_cvt_pk_bf16_f32 v58, v30, s0
	v_lshlrev_b32_e32 v30, s68, v55
	s_waitcnt lgkmcnt(0)
	v_add_f32_e32 v47, v47, v54
	ds_bpermute_b32 v54, v44, v47
	v_cvt_pk_bf16_f32 v57, v31, s0
	v_ashrrev_i32_e32 v31, 31, v30
	v_cvt_pk_bf16_f32 v41, v41, s0
	v_lshl_add_u64 v[30:31], v[30:31], 1, v[28:29]
	s_waitcnt lgkmcnt(0)
	v_add_f32_e32 v47, v47, v54
	ds_bpermute_b32 v54, v45, v47
	global_store_short v[30:31], v41, off
	global_store_short v[30:31], v56, off offset:64
	global_store_short v[30:31], v57, off offset:128
	global_store_short v[30:31], v58, off offset:192
	s_and_b64 vcc, exec, s[0:1]
	s_waitcnt lgkmcnt(0)
	v_add_f32_e32 v47, v47, v54
	ds_bpermute_b32 v54, v46, v47
	s_waitcnt lgkmcnt(0)
	v_add_f32_e32 v40, v47, v54
	ds_bpermute_b32 v47, v43, v40
	s_waitcnt lgkmcnt(0)
	v_add_f32_e32 v40, v40, v47
	v_fmamk_f32 v40, v40, 0x3c000000, v166
	v_rsq_f32_e32 v40, v40
	s_nop 0
	v_pk_mul_f32 v[30:31], v[12:13], v[40:41] op_sel_hi:[1,0]
	v_pk_mul_f32 v[54:55], v[14:15], v[40:41] op_sel_hi:[1,0]
	v_pk_mul_f32 v[40:41], v[68:69], v[30:31]
	v_pk_mul_f32 v[30:31], v[70:71], v[54:55]
	s_cbranch_vccnz .LBB0_1212
	v_add_lshl_u32 v54, s66, v145, 8
	v_ashrrev_i32_e32 v55, 31, v54
	v_lshl_add_u64 v[54:55], v[54:55], 2, v[26:27]
	global_store_dword v[54:55], v41, off sc1
	global_store_dword v[54:55], v40, off offset:128 sc1
	global_store_dword v[54:55], v31, off offset:256 sc1
	global_store_dword v[54:55], v30, off offset:384 sc1

.LBB0_1214:
	v_pk_mul_f32 v[54:55], v[64:65], v[64:65]
	v_pk_mul_f32 v[56:57], v[66:67], v[66:67]
	v_add_f32_e32 v47, v55, v54
	v_add_f32_e32 v47, v47, v57
	v_add_f32_e32 v47, v47, v56
	ds_bpermute_b32 v54, v42, v47
	v_cvt_pk_bf16_f32 v56, v40, s0
	v_add_u32_e32 v55, s8, v145
	v_cvt_pk_bf16_f32 v58, v30, s0
	v_lshlrev_b32_e32 v30, s68, v55
	s_waitcnt lgkmcnt(0)
	v_add_f32_e32 v47, v47, v54
	ds_bpermute_b32 v54, v44, v47
	v_cvt_pk_bf16_f32 v57, v31, s0
	v_ashrrev_i32_e32 v31, 31, v30
	v_cvt_pk_bf16_f32 v41, v41, s0
	v_lshl_add_u64 v[30:31], v[30:31], 1, v[28:29]
	s_waitcnt lgkmcnt(0)
	v_add_f32_e32 v47, v47, v54
	ds_bpermute_b32 v54, v45, v47
	global_store_short v[30:31], v41, off
	global_store_short v[30:31], v56, off offset:64
	global_store_short v[30:31], v57, off offset:128
	global_store_short v[30:31], v58, off offset:192
	s_and_b64 vcc, exec, s[0:1]
	s_waitcnt lgkmcnt(0)
	v_add_f32_e32 v47, v47, v54
	ds_bpermute_b32 v54, v46, v47
	s_waitcnt lgkmcnt(0)
	v_add_f32_e32 v40, v47, v54
	ds_bpermute_b32 v47, v43, v40
	s_waitcnt lgkmcnt(0)
	v_add_f32_e32 v40, v40, v47
	v_fmamk_f32 v40, v40, 0x3c000000, v166
	v_rsq_f32_e32 v40, v40
	s_nop 0
	v_pk_mul_f32 v[30:31], v[12:13], v[40:41] op_sel_hi:[1,0]
	v_pk_mul_f32 v[54:55], v[14:15], v[40:41] op_sel_hi:[1,0]
	v_pk_mul_f32 v[40:41], v[64:65], v[30:31]
	v_pk_mul_f32 v[30:31], v[66:67], v[54:55]
	s_cbranch_vccnz .LBB0_1216
	v_add_lshl_u32 v54, s66, v146, 8
	v_ashrrev_i32_e32 v55, 31, v54
	v_lshl_add_u64 v[54:55], v[54:55], 2, v[26:27]
	global_store_dword v[54:55], v41, off sc1
	global_store_dword v[54:55], v40, off offset:128 sc1
	global_store_dword v[54:55], v31, off offset:256 sc1
	global_store_dword v[54:55], v30, off offset:384 sc1

.LBB0_1218:
	v_pk_mul_f32 v[54:55], v[50:51], v[50:51]
	v_pk_mul_f32 v[56:57], v[52:53], v[52:53]
	v_add_f32_e32 v47, v55, v54
	v_add_f32_e32 v47, v47, v57
	v_add_f32_e32 v47, v47, v56
	ds_bpermute_b32 v54, v42, v47
	v_cvt_pk_bf16_f32 v56, v40, s0
	v_add_u32_e32 v55, s8, v146
	v_cvt_pk_bf16_f32 v58, v30, s0
	v_lshlrev_b32_e32 v30, s68, v55
	s_waitcnt lgkmcnt(0)
	v_add_f32_e32 v47, v47, v54
	ds_bpermute_b32 v54, v44, v47
	v_cvt_pk_bf16_f32 v57, v31, s0
	v_ashrrev_i32_e32 v31, 31, v30
	v_cvt_pk_bf16_f32 v41, v41, s0
	v_lshl_add_u64 v[30:31], v[30:31], 1, v[28:29]
	s_waitcnt lgkmcnt(0)
	v_add_f32_e32 v47, v47, v54
	ds_bpermute_b32 v54, v45, v47
	global_store_short v[30:31], v41, off
	global_store_short v[30:31], v56, off offset:64
	global_store_short v[30:31], v57, off offset:128
	global_store_short v[30:31], v58, off offset:192
	s_and_b64 vcc, exec, s[0:1]
	s_waitcnt lgkmcnt(0)
	v_add_f32_e32 v47, v47, v54
	ds_bpermute_b32 v54, v46, v47
	s_waitcnt lgkmcnt(0)
	v_add_f32_e32 v40, v47, v54
	ds_bpermute_b32 v47, v43, v40
	s_waitcnt lgkmcnt(0)
	v_add_f32_e32 v40, v40, v47
	v_fmamk_f32 v40, v40, 0x3c000000, v166
	v_rsq_f32_e32 v40, v40
	s_nop 0
	v_pk_mul_f32 v[30:31], v[12:13], v[40:41] op_sel_hi:[1,0]
	v_pk_mul_f32 v[54:55], v[14:15], v[40:41] op_sel_hi:[1,0]
	v_pk_mul_f32 v[40:41], v[50:51], v[30:31]
	v_pk_mul_f32 v[30:31], v[52:53], v[54:55]
	s_cbranch_vccnz .LBB0_1220
	v_add_lshl_u32 v50, s66, v147, 8
	v_ashrrev_i32_e32 v51, 31, v50
	v_lshl_add_u64 v[50:51], v[50:51], 2, v[26:27]
	global_store_dword v[50:51], v41, off sc1
	global_store_dword v[50:51], v40, off offset:128 sc1
	global_store_dword v[50:51], v31, off offset:256 sc1
	global_store_dword v[50:51], v30, off offset:384 sc1

.LBB0_1222:
	v_pk_mul_f32 v[50:51], v[38:39], v[38:39]
	v_pk_mul_f32 v[52:53], v[48:49], v[48:49]
	v_add_f32_e32 v47, v51, v50
	v_add_f32_e32 v47, v47, v53
	v_add_f32_e32 v47, v47, v52
	ds_bpermute_b32 v50, v42, v47
	v_cvt_pk_bf16_f32 v52, v40, s0
	v_add_u32_e32 v51, s8, v147
	v_cvt_pk_bf16_f32 v54, v30, s0
	v_lshlrev_b32_e32 v30, s68, v51
	s_waitcnt lgkmcnt(0)
	v_add_f32_e32 v47, v47, v50
	ds_bpermute_b32 v50, v44, v47
	v_cvt_pk_bf16_f32 v53, v31, s0
	v_ashrrev_i32_e32 v31, 31, v30
	v_cvt_pk_bf16_f32 v41, v41, s0
	v_lshl_add_u64 v[30:31], v[30:31], 1, v[28:29]
	s_waitcnt lgkmcnt(0)
	v_add_f32_e32 v47, v47, v50
	ds_bpermute_b32 v50, v45, v47
	global_store_short v[30:31], v41, off
	global_store_short v[30:31], v52, off offset:64
	global_store_short v[30:31], v53, off offset:128
	global_store_short v[30:31], v54, off offset:192
	s_and_b64 vcc, exec, s[0:1]
	s_waitcnt lgkmcnt(0)
	v_add_f32_e32 v47, v47, v50
	ds_bpermute_b32 v50, v46, v47
	s_waitcnt lgkmcnt(0)
	v_add_f32_e32 v40, v47, v50
	ds_bpermute_b32 v47, v43, v40
	s_waitcnt lgkmcnt(0)
	v_add_f32_e32 v40, v40, v47
	v_fmamk_f32 v40, v40, 0x3c000000, v166
	v_rsq_f32_e32 v40, v40
	s_nop 0
	v_pk_mul_f32 v[30:31], v[12:13], v[40:41] op_sel_hi:[1,0]
	v_pk_mul_f32 v[40:41], v[14:15], v[40:41] op_sel_hi:[1,0]
	v_pk_mul_f32 v[38:39], v[38:39], v[30:31]
	v_pk_mul_f32 v[30:31], v[48:49], v[40:41]
	s_cbranch_vccnz .LBB0_1224
	v_add_lshl_u32 v40, s66, v148, 8
	v_ashrrev_i32_e32 v41, 31, v40
	v_lshl_add_u64 v[40:41], v[40:41], 2, v[26:27]
	global_store_dword v[40:41], v39, off sc1
	global_store_dword v[40:41], v38, off offset:128 sc1
	global_store_dword v[40:41], v31, off offset:256 sc1
	global_store_dword v[40:41], v30, off offset:384 sc1

.LBB0_1226:
	v_pk_mul_f32 v[40:41], v[34:35], v[34:35]
	v_pk_mul_f32 v[48:49], v[36:37], v[36:37]
	v_add_f32_e32 v40, v41, v40
	v_add_f32_e32 v40, v40, v49
	v_add_f32_e32 v40, v40, v48
	ds_bpermute_b32 v41, v42, v40
	v_cvt_pk_bf16_f32 v48, v38, s0
	v_add_u32_e32 v47, s8, v148
	v_cvt_pk_bf16_f32 v50, v30, s0
	v_lshlrev_b32_e32 v30, s68, v47
	s_waitcnt lgkmcnt(0)
	v_add_f32_e32 v40, v40, v41
	ds_bpermute_b32 v41, v44, v40
	v_cvt_pk_bf16_f32 v49, v31, s0
	v_ashrrev_i32_e32 v31, 31, v30
	v_cvt_pk_bf16_f32 v39, v39, s0
	v_lshl_add_u64 v[30:31], v[30:31], 1, v[28:29]
	s_waitcnt lgkmcnt(0)
	v_add_f32_e32 v40, v40, v41
	ds_bpermute_b32 v41, v45, v40
	global_store_short v[30:31], v39, off
	global_store_short v[30:31], v48, off offset:64
	global_store_short v[30:31], v49, off offset:128
	global_store_short v[30:31], v50, off offset:192
	s_and_b64 vcc, exec, s[0:1]
	s_waitcnt lgkmcnt(0)
	v_add_f32_e32 v40, v40, v41
	ds_bpermute_b32 v41, v46, v40
	s_waitcnt lgkmcnt(0)
	v_add_f32_e32 v38, v40, v41
	ds_bpermute_b32 v40, v43, v38
	s_waitcnt lgkmcnt(0)
	v_add_f32_e32 v38, v38, v40
	v_fmamk_f32 v38, v38, 0x3c000000, v166
	v_rsq_f32_e32 v38, v38
	s_nop 0
	v_pk_mul_f32 v[30:31], v[12:13], v[38:39] op_sel_hi:[1,0]
	v_pk_mul_f32 v[38:39], v[14:15], v[38:39] op_sel_hi:[1,0]
	v_pk_mul_f32 v[34:35], v[34:35], v[30:31]
	v_pk_mul_f32 v[30:31], v[36:37], v[38:39]
	s_cbranch_vccnz .LBB0_1228
	v_add_lshl_u32 v36, s66, v149, 8
	v_ashrrev_i32_e32 v37, 31, v36
	v_lshl_add_u64 v[36:37], v[36:37], 2, v[26:27]
	global_store_dword v[36:37], v35, off sc1
	global_store_dword v[36:37], v34, off offset:128 sc1
	global_store_dword v[36:37], v31, off offset:256 sc1
	global_store_dword v[36:37], v30, off offset:384 sc1

.LBB0_1230:
	v_pk_mul_f32 v[36:37], v[24:25], v[24:25]
	v_pk_mul_f32 v[38:39], v[32:33], v[32:33]
	v_add_f32_e32 v36, v37, v36
	v_add_f32_e32 v36, v36, v39
	v_add_f32_e32 v36, v36, v38
	ds_bpermute_b32 v37, v42, v36
	v_cvt_pk_bf16_f32 v39, v34, s0
	v_add_u32_e32 v38, s8, v149
	v_cvt_pk_bf16_f32 v41, v30, s0
	v_lshlrev_b32_e32 v30, s68, v38
	s_waitcnt lgkmcnt(0)
	v_add_f32_e32 v36, v36, v37
	ds_bpermute_b32 v37, v44, v36
	v_cvt_pk_bf16_f32 v40, v31, s0
	v_ashrrev_i32_e32 v31, 31, v30
	v_cvt_pk_bf16_f32 v35, v35, s0
	v_lshl_add_u64 v[30:31], v[30:31], 1, v[28:29]
	s_waitcnt lgkmcnt(0)
	v_add_f32_e32 v36, v36, v37
	ds_bpermute_b32 v37, v45, v36
	global_store_short v[30:31], v35, off
	global_store_short v[30:31], v39, off offset:64
	global_store_short v[30:31], v40, off offset:128
	global_store_short v[30:31], v41, off offset:192
	s_and_b64 vcc, exec, s[0:1]
	s_waitcnt lgkmcnt(0)
	v_add_f32_e32 v36, v36, v37
	ds_bpermute_b32 v37, v46, v36
	s_waitcnt lgkmcnt(0)
	v_add_f32_e32 v34, v36, v37
	ds_bpermute_b32 v36, v43, v34
	s_waitcnt lgkmcnt(0)
	v_add_f32_e32 v34, v34, v36
	v_fmamk_f32 v34, v34, 0x3c000000, v166
	v_rsq_f32_e32 v34, v34
	s_nop 0
	v_pk_mul_f32 v[30:31], v[12:13], v[34:35] op_sel_hi:[1,0]
	v_pk_mul_f32 v[34:35], v[14:15], v[34:35] op_sel_hi:[1,0]
	v_pk_mul_f32 v[30:31], v[24:25], v[30:31]
	v_pk_mul_f32 v[24:25], v[32:33], v[34:35]
	s_cbranch_vccnz .LBB0_1232
	v_add_lshl_u32 v32, s66, v150, 8
	v_ashrrev_i32_e32 v33, 31, v32
	v_lshl_add_u64 v[32:33], v[32:33], 2, v[26:27]
	global_store_dword v[32:33], v31, off sc1
	global_store_dword v[32:33], v30, off offset:128 sc1
	global_store_dword v[32:33], v25, off offset:256 sc1
	global_store_dword v[32:33], v24, off offset:384 sc1

.LBB0_1234:
	v_pk_mul_f32 v[32:33], v[20:21], v[20:21]
	v_pk_mul_f32 v[34:35], v[22:23], v[22:23]
	v_add_f32_e32 v32, v33, v32
	v_add_f32_e32 v32, v32, v35
	v_add_f32_e32 v32, v32, v34
	ds_bpermute_b32 v33, v42, v32
	v_cvt_pk_bf16_f32 v35, v30, s0
	v_add_u32_e32 v34, s8, v150
	v_cvt_pk_bf16_f32 v37, v24, s0
	v_lshlrev_b32_e32 v24, s68, v34
	s_waitcnt lgkmcnt(0)
	v_add_f32_e32 v32, v32, v33
	ds_bpermute_b32 v33, v44, v32
	v_cvt_pk_bf16_f32 v36, v25, s0
	v_ashrrev_i32_e32 v25, 31, v24
	v_cvt_pk_bf16_f32 v31, v31, s0
	v_lshl_add_u64 v[24:25], v[24:25], 1, v[28:29]
	s_waitcnt lgkmcnt(0)
	v_add_f32_e32 v32, v32, v33
	ds_bpermute_b32 v33, v45, v32
	global_store_short v[24:25], v31, off
	global_store_short v[24:25], v35, off offset:64
	global_store_short v[24:25], v36, off offset:128
	global_store_short v[24:25], v37, off offset:192
	s_and_b64 vcc, exec, s[0:1]
	s_waitcnt lgkmcnt(0)
	v_add_f32_e32 v32, v32, v33
	ds_bpermute_b32 v33, v46, v32
	s_waitcnt lgkmcnt(0)
	v_add_f32_e32 v30, v32, v33
	ds_bpermute_b32 v32, v43, v30
	s_waitcnt lgkmcnt(0)
	v_add_f32_e32 v30, v30, v32
	v_fmamk_f32 v30, v30, 0x3c000000, v166
	v_rsq_f32_e32 v30, v30
	s_nop 0
	v_pk_mul_f32 v[24:25], v[12:13], v[30:31] op_sel_hi:[1,0]
	v_pk_mul_f32 v[30:31], v[14:15], v[30:31] op_sel_hi:[1,0]
	v_pk_mul_f32 v[24:25], v[20:21], v[24:25]
	v_pk_mul_f32 v[20:21], v[22:23], v[30:31]
	s_cbranch_vccnz .LBB0_1236
	v_add_lshl_u32 v22, s66, v151, 8
	v_ashrrev_i32_e32 v23, 31, v22
	v_lshl_add_u64 v[22:23], v[22:23], 2, v[26:27]
	global_store_dword v[22:23], v25, off sc1
	global_store_dword v[22:23], v24, off offset:128 sc1
	global_store_dword v[22:23], v21, off offset:256 sc1
	global_store_dword v[22:23], v20, off offset:384 sc1

.LBB0_1238:
	v_pk_mul_f32 v[22:23], v[16:17], v[16:17]
	v_pk_mul_f32 v[30:31], v[18:19], v[18:19]
	v_add_f32_e32 v22, v23, v22
	v_add_f32_e32 v22, v22, v31
	v_add_f32_e32 v22, v22, v30
	ds_bpermute_b32 v23, v42, v22
	v_add_u32_e32 v30, s8, v151
	v_cvt_pk_bf16_f32 v32, v20, s0
	v_lshlrev_b32_e32 v20, s68, v30
	v_cvt_pk_bf16_f32 v31, v21, s0
	s_waitcnt lgkmcnt(0)
	v_add_f32_e32 v22, v22, v23
	ds_bpermute_b32 v23, v44, v22
	v_ashrrev_i32_e32 v21, 31, v20
	v_cvt_pk_bf16_f32 v25, v25, s0
	v_cvt_pk_bf16_f32 v24, v24, s0
	v_lshl_add_u64 v[20:21], v[20:21], 1, v[28:29]
	s_waitcnt lgkmcnt(0)
	v_add_f32_e32 v22, v22, v23
	ds_bpermute_b32 v23, v45, v22
	global_store_short v[20:21], v25, off
	global_store_short v[20:21], v24, off offset:64
	global_store_short v[20:21], v31, off offset:128
	global_store_short v[20:21], v32, off offset:192
	s_and_b64 vcc, exec, s[0:1]
	s_waitcnt lgkmcnt(0)
	v_add_f32_e32 v22, v22, v23
	ds_bpermute_b32 v23, v46, v22
	s_waitcnt lgkmcnt(0)
	v_add_f32_e32 v22, v22, v23
	ds_bpermute_b32 v23, v43, v22
	s_waitcnt lgkmcnt(0)
	v_add_f32_e32 v22, v22, v23
	v_fmamk_f32 v22, v22, 0x3c000000, v166
	v_rsq_f32_e32 v22, v22
	s_nop 0
	v_pk_mul_f32 v[20:21], v[12:13], v[22:23] op_sel_hi:[1,0]
	v_pk_mul_f32 v[22:23], v[14:15], v[22:23] op_sel_hi:[1,0]
	v_pk_mul_f32 v[20:21], v[16:17], v[20:21]
	v_pk_mul_f32 v[16:17], v[18:19], v[22:23]
	s_cbranch_vccnz .LBB0_1240
	v_add_lshl_u32 v18, s66, v152, 8
	v_ashrrev_i32_e32 v19, 31, v18
	v_lshl_add_u64 v[18:19], v[18:19], 2, v[26:27]
	global_store_dword v[18:19], v21, off sc1
	global_store_dword v[18:19], v20, off offset:128 sc1
	global_store_dword v[18:19], v17, off offset:256 sc1
	global_store_dword v[18:19], v16, off offset:384 sc1

.LBB0_1242:
	v_pk_mul_f32 v[18:19], v[8:9], v[8:9]
	v_pk_mul_f32 v[22:23], v[10:11], v[10:11]
	v_add_f32_e32 v18, v19, v18
	v_add_f32_e32 v18, v18, v23
	v_add_f32_e32 v18, v18, v22
	ds_bpermute_b32 v19, v42, v18
	v_add_u32_e32 v22, s8, v152
	v_cvt_pk_bf16_f32 v24, v16, s0
	v_lshlrev_b32_e32 v16, s68, v22
	v_cvt_pk_bf16_f32 v23, v17, s0
	s_waitcnt lgkmcnt(0)
	v_add_f32_e32 v18, v18, v19
	ds_bpermute_b32 v19, v44, v18
	v_ashrrev_i32_e32 v17, 31, v16
	v_cvt_pk_bf16_f32 v21, v21, s0
	v_cvt_pk_bf16_f32 v20, v20, s0
	v_lshl_add_u64 v[16:17], v[16:17], 1, v[28:29]
	s_waitcnt lgkmcnt(0)
	v_add_f32_e32 v18, v18, v19
	ds_bpermute_b32 v19, v45, v18
	global_store_short v[16:17], v21, off
	global_store_short v[16:17], v20, off offset:64
	global_store_short v[16:17], v23, off offset:128
	global_store_short v[16:17], v24, off offset:192
	s_and_b64 vcc, exec, s[0:1]
	s_waitcnt lgkmcnt(0)
	v_add_f32_e32 v18, v18, v19
	ds_bpermute_b32 v19, v46, v18
	s_waitcnt lgkmcnt(0)
	v_add_f32_e32 v18, v18, v19
	ds_bpermute_b32 v19, v43, v18
	s_waitcnt lgkmcnt(0)
	v_add_f32_e32 v18, v18, v19
	v_fmamk_f32 v18, v18, 0x3c000000, v166
	v_rsq_f32_e32 v18, v18
	s_nop 0
	v_pk_mul_f32 v[16:17], v[12:13], v[18:19] op_sel_hi:[1,0]
	v_pk_mul_f32 v[18:19], v[14:15], v[18:19] op_sel_hi:[1,0]
	v_pk_mul_f32 v[16:17], v[8:9], v[16:17]
	v_pk_mul_f32 v[8:9], v[10:11], v[18:19]
	s_cbranch_vccnz .LBB0_1244
	v_add_lshl_u32 v10, s66, v153, 8
	v_ashrrev_i32_e32 v11, 31, v10
	v_lshl_add_u64 v[10:11], v[10:11], 2, v[26:27]
	global_store_dword v[10:11], v17, off sc1
	global_store_dword v[10:11], v16, off offset:128 sc1
	global_store_dword v[10:11], v9, off offset:256 sc1
	global_store_dword v[10:11], v8, off offset:384 sc1

.LBB0_1246:
	v_pk_mul_f32 v[10:11], v[4:5], v[4:5]
	v_pk_mul_f32 v[18:19], v[6:7], v[6:7]
	v_add_f32_e32 v10, v11, v10
	v_add_f32_e32 v10, v10, v19
	v_add_f32_e32 v10, v10, v18
	ds_bpermute_b32 v11, v42, v10
	v_add_u32_e32 v18, s8, v153
	v_cvt_pk_bf16_f32 v20, v8, s0
	v_lshlrev_b32_e32 v8, s68, v18
	v_cvt_pk_bf16_f32 v19, v9, s0
	s_waitcnt lgkmcnt(0)
	v_add_f32_e32 v10, v10, v11
	ds_bpermute_b32 v11, v44, v10
	v_ashrrev_i32_e32 v9, 31, v8
	v_cvt_pk_bf16_f32 v17, v17, s0
	v_cvt_pk_bf16_f32 v16, v16, s0
	v_lshl_add_u64 v[8:9], v[8:9], 1, v[28:29]
	s_waitcnt lgkmcnt(0)
	v_add_f32_e32 v10, v10, v11
	ds_bpermute_b32 v11, v45, v10
	global_store_short v[8:9], v17, off
	global_store_short v[8:9], v16, off offset:64
	global_store_short v[8:9], v19, off offset:128
	global_store_short v[8:9], v20, off offset:192
	s_and_b64 vcc, exec, s[0:1]
	s_waitcnt lgkmcnt(0)
	v_add_f32_e32 v10, v10, v11
	ds_bpermute_b32 v11, v46, v10
	s_waitcnt lgkmcnt(0)
	v_add_f32_e32 v10, v10, v11
	ds_bpermute_b32 v11, v43, v10
	s_waitcnt lgkmcnt(0)
	v_add_f32_e32 v10, v10, v11
	v_fmamk_f32 v10, v10, 0x3c000000, v166
	v_rsq_f32_e32 v10, v10
	s_nop 0
	v_pk_mul_f32 v[8:9], v[12:13], v[10:11] op_sel_hi:[1,0]
	v_pk_mul_f32 v[10:11], v[14:15], v[10:11] op_sel_hi:[1,0]
	v_pk_mul_f32 v[8:9], v[4:5], v[8:9]
	v_pk_mul_f32 v[4:5], v[6:7], v[10:11]
	s_cbranch_vccnz .LBB0_1248
	v_add_lshl_u32 v6, s66, v154, 8
	v_ashrrev_i32_e32 v7, 31, v6
	v_lshl_add_u64 v[6:7], v[6:7], 2, v[26:27]
	global_store_dword v[6:7], v9, off sc1
	global_store_dword v[6:7], v8, off offset:128 sc1
	global_store_dword v[6:7], v5, off offset:256 sc1
	global_store_dword v[6:7], v4, off offset:384 sc1

.LBB0_1250:
	v_pk_mul_f32 v[6:7], v[0:1], v[0:1]
	v_pk_mul_f32 v[10:11], v[2:3], v[2:3]
	v_add_f32_e32 v6, v7, v6
	v_add_f32_e32 v6, v11, v6
	v_add_f32_e32 v6, v10, v6
	ds_bpermute_b32 v7, v42, v6
	v_add_u32_e32 v10, s8, v154
	v_cvt_pk_bf16_f32 v16, v4, s0
	v_lshlrev_b32_e32 v4, s68, v10
	v_cvt_pk_bf16_f32 v11, v5, s0
	s_waitcnt lgkmcnt(0)
	v_add_f32_e32 v6, v6, v7
	ds_bpermute_b32 v7, v44, v6
	v_ashrrev_i32_e32 v5, 31, v4
	v_cvt_pk_bf16_f32 v9, v9, s0
	v_cvt_pk_bf16_f32 v8, v8, s0
	v_lshl_add_u64 v[4:5], v[4:5], 1, v[28:29]
	s_waitcnt lgkmcnt(0)
	v_add_f32_e32 v6, v6, v7
	ds_bpermute_b32 v7, v45, v6
	global_store_short v[4:5], v9, off
	global_store_short v[4:5], v8, off offset:64
	global_store_short v[4:5], v11, off offset:128
	global_store_short v[4:5], v16, off offset:192
	s_and_b64 vcc, exec, s[0:1]
	s_waitcnt lgkmcnt(0)
	v_add_f32_e32 v6, v6, v7
	ds_bpermute_b32 v7, v46, v6
	s_waitcnt lgkmcnt(0)
	v_add_f32_e32 v6, v6, v7
	ds_bpermute_b32 v7, v43, v6
	s_waitcnt lgkmcnt(0)
	v_add_f32_e32 v6, v6, v7
	v_fmamk_f32 v6, v6, 0x3c000000, v166
	v_rsq_f32_e32 v6, v6
	s_nop 0
	v_pk_mul_f32 v[4:5], v[12:13], v[6:7] op_sel_hi:[1,0]
	v_pk_mul_f32 v[6:7], v[14:15], v[6:7] op_sel_hi:[1,0]
	v_pk_mul_f32 v[4:5], v[0:1], v[4:5]
	v_pk_mul_f32 v[0:1], v[2:3], v[6:7]
	s_cbranch_vccnz .LBB0_1252
	v_add_lshl_u32 v2, s66, v155, 8
	v_ashrrev_i32_e32 v3, 31, v2
	v_lshl_add_u64 v[2:3], v[2:3], 2, v[26:27]
	global_store_dword v[2:3], v5, off sc1
	global_store_dword v[2:3], v4, off offset:128 sc1
	global_store_dword v[2:3], v1, off offset:256 sc1
	global_store_dword v[2:3], v0, off offset:384 sc1
